# GEMM loops: last two LDS-DMA groups of each 6-piece load segment moved into the following MFMA burst (vmcnt 8->6)
# baseline (speedup 1.0000x reference)
; #define PG8_STAGE(bufoff, gbase, voff) do { _Pragma("unroll") for (int _i = 0; _i < 2; ++_i) \
;         __builtin_amdgcn_global_load_lds((const unsigned*)((const char*)(gbase) + (voff)[_i]), (PG8_LAS unsigned*)(lds + (bufoff) + ldsw + _i * 8192), 16, 0, 0); } while (0)
; #define PG8_LDA(dst, b, h) do { _Pragma("unroll") for (int m = 0; m < 4; ++m) _Pragma("unroll") for (int k = 0; k < 2; ++k) dst[m][k] = *(const PG8_LAS bf16x8*)(lds + PG8_SA(b, h) + aoff + m * 2048 + k * 1024); } while (0)
; #define PG8_LDB(dst, b, h) do { _Pragma("unroll") for (int n = 0; n < 2; ++n) _Pragma("unroll") for (int k = 0; k < 2; ++k) dst[n][k] = *(const PG8_LAS bf16x8*)(lds + PG8_SB(b, h) + boff + n * 2048 + k * 1024); } while (0)
; #define PG8_MMA(ai, bj, At, Bt) do { __builtin_amdgcn_s_setprio(1); _Pragma("unroll") for (int m = 0; m < 4; ++m) _Pragma("unroll") for (int n = 0; n < 2; ++n) _Pragma("unroll") for (int k = 0; k < 2; ++k) \
;         acc[ai][bj][m][n] = __builtin_amdgcn_mfma_f32_16x16x32_bf16(Bt[n][k], At[m][k], acc[ai][bj][m][n], 0, 0, 0); __builtin_amdgcn_s_setprio(0); } while (0)
; #define PG8_WAIT_V(n) asm volatile("s_waitcnt vmcnt(" #n ")" ::: "memory")
; #define PG8_WAIT_L(n) asm volatile("s_waitcnt lgkmcnt(" #n ")" ::: "memory")
; #define PG8_BAR __builtin_amdgcn_s_barrier()
; #define PG8_SCHED __builtin_amdgcn_sched_barrier(0)
; template <class Epi, class Sched, bool ALIGN_EPI = false, bool SP2 = false>
; __device__ __forceinline__ void gemm_phase(PG8_LAS unsigned char* lds, const Gemm g, const Sched& S, const Epi& E) {
;     ...
;             const char* a1 = cA + (size_t)(t + 1) * kstep;
;             const char* a2 = last ? nA : cA + (size_t)(t + 2) * kstep; const char* b2 = last ? nB : cB + (size_t)(t + 2) * kstep;
;             const char* a3 = a2 + kstep; const char* b3 = b2 + kstep;
;             if (last && has_next) S.a_ready(nxt);
;             if constexpr (SP2) {
;             PG8_LDB(B0, 0, 0); PG8_LDB(B1, 0, 1); PG8_SCHED; PG8_LDA(At, 0, 0); PG8_STAGE(PG8_SA(1, 1), a1 + hstepA, voffA);
;             PG8_WAIT_V(8); PG8_WAIT_L(0); PG8_BAR; PG8_MMA(0, 0, At, B0); PG8_MMA(0, 1, At, B1); PG8_BAR; PG8_SCHED;
;             PG8_LDA(At, 0, 1); PG8_STAGE(PG8_SB(0, 0), b2, voffB); PG8_STAGE(PG8_SB(0, 1), b2 + hstepB, voffB); PG8_STAGE(PG8_SA(0, 0), a2, voffA);
.LBB0_224:
	s_add_u32 s33, s68, s43
	s_addc_u32 s34, s69, 0
	s_add_u32 s35, s33, 0x100
	s_addc_u32 s45, s34, 0
	s_and_b64 s[12:13], s[72:73], exec
	s_cselect_b32 s77, s1, s45
	s_cselect_b32 s76, s0, s35
	s_add_u32 s12, s66, s43
	s_addc_u32 s13, s67, 0
	s_add_u32 s35, s12, 0x100
	s_addc_u32 s43, s13, 0
	s_and_b64 s[12:13], s[72:73], exec
	s_cselect_b32 s79, s47, s43
	s_cselect_b32 s78, s46, s35
	s_add_u32 s82, s33, 0x40080
	ds_read_b128 v[150:153], v146
	ds_read_b128 v[154:157], v146 offset:1024
	ds_read_b128 v[158:161], v146 offset:2048
	ds_read_b128 v[162:165], v146 offset:3072
	ds_read_b128 v[166:169], v147
	ds_read_b128 v[170:173], v147 offset:1024
	ds_read_b128 v[174:177], v147 offset:2048
	ds_read_b128 v[178:181], v147 offset:3072
	s_addc_u32 s83, s34, 0
	s_add_i32 s34, s97, s86
	s_add_i32 m0, s65, 0xc000
	s_add_i32 s61, s65, 0xe000
	s_add_i32 s60, s34, 0x2000
	s_add_u32 s80, s78, 0x10000
	s_addc_u32 s81, s79, 0
	s_add_i32 s35, s90, s86
	s_add_i32 s33, s35, 0x2000
	s_add_i32 s13, 0, 0x18000
	s_add_i32 vcc_lo, 0, 0x1c000
	s_add_u32 s74, s76, 0x40000
	s_addc_u32 s75, s77, 0
	s_add_i32 vcc_hi, s13, s86
	s_add_i32 s45, vcc_hi, 0x2000
	s_add_u32 s72, s78, 0x10080
	s_addc_u32 s73, s79, 0
	s_add_i32 s43, vcc_lo, s86
	s_add_i32 s12, s43, 0x2000
	v_lshl_add_u64 v[142:143], s[82:83], 0, v[136:137]
	ds_read_b128 v[182:185], v148
	ds_read_b128 v[186:189], v148 offset:1024
	ds_read_b128 v[190:193], v148 offset:2048
	ds_read_b128 v[194:197], v148 offset:3072
	ds_read_b128 v[200:203], v148 offset:4096
	ds_read_b128 v[204:207], v148 offset:5120
	ds_read_b128 v[208:211], v148 offset:6144
	ds_read_b128 v[212:215], v148 offset:7168
	global_load_lds_dwordx4 v[142:143], off
	v_lshl_add_u64 v[142:143], s[82:83], 0, v[132:133]
	s_mov_b32 m0, s61
	s_nop 0
	global_load_lds_dwordx4 v[142:143], off
	s_waitcnt vmcnt(8)
	s_waitcnt lgkmcnt(0)
	s_barrier
	s_setprio 1
	s_waitcnt lgkmcnt(0)
	v_mfma_f32_16x16x32_bf16 v[126:129], v[150:153], v[182:185], v[126:129]
	v_mfma_f32_16x16x32_bf16 v[122:125], v[158:161], v[182:185], v[122:125]
	v_mfma_f32_16x16x32_bf16 v[118:121], v[150:153], v[190:193], v[118:121]
	v_mfma_f32_16x16x32_bf16 v[110:113], v[158:161], v[190:193], v[110:113]
	v_mfma_f32_16x16x32_bf16 v[102:105], v[150:153], v[200:203], v[102:105]
	v_mfma_f32_16x16x32_bf16 v[94:97], v[158:161], v[200:203], v[94:97]
	v_mfma_f32_16x16x32_bf16 v[86:89], v[150:153], v[208:211], v[86:89]
	v_mfma_f32_16x16x32_bf16 v[78:81], v[158:161], v[208:211], v[78:81]
	v_mfma_f32_16x16x32_bf16 v[126:129], v[154:157], v[186:189], v[126:129]
	v_mfma_f32_16x16x32_bf16 v[122:125], v[162:165], v[186:189], v[122:125]
	v_mfma_f32_16x16x32_bf16 v[118:121], v[154:157], v[194:197], v[118:121]
	v_mfma_f32_16x16x32_bf16 v[110:113], v[162:165], v[194:197], v[110:113]
	v_mfma_f32_16x16x32_bf16 v[102:105], v[154:157], v[204:207], v[102:105]
	v_mfma_f32_16x16x32_bf16 v[94:97], v[162:165], v[204:207], v[94:97]
	v_mfma_f32_16x16x32_bf16 v[86:89], v[154:157], v[212:215], v[86:89]
	v_mfma_f32_16x16x32_bf16 v[78:81], v[162:165], v[212:215], v[78:81]
	s_setprio 0
	s_setprio 1
	v_mfma_f32_16x16x32_bf16 v[114:117], v[166:169], v[182:185], v[114:117]
	v_mfma_f32_16x16x32_bf16 v[106:109], v[174:177], v[182:185], v[106:109]
	v_mfma_f32_16x16x32_bf16 v[98:101], v[166:169], v[190:193], v[98:101]
	v_mfma_f32_16x16x32_bf16 v[90:93], v[174:177], v[190:193], v[90:93]
	v_mfma_f32_16x16x32_bf16 v[82:85], v[166:169], v[200:203], v[82:85]
	v_mfma_f32_16x16x32_bf16 v[74:77], v[174:177], v[200:203], v[74:77]
	v_mfma_f32_16x16x32_bf16 v[70:73], v[166:169], v[208:211], v[70:73]
	v_mfma_f32_16x16x32_bf16 v[66:69], v[174:177], v[208:211], v[66:69]
	v_mfma_f32_16x16x32_bf16 v[114:117], v[170:173], v[186:189], v[114:117]
	v_mfma_f32_16x16x32_bf16 v[106:109], v[178:181], v[186:189], v[106:109]
	v_mfma_f32_16x16x32_bf16 v[98:101], v[170:173], v[194:197], v[98:101]
	v_mfma_f32_16x16x32_bf16 v[90:93], v[178:181], v[194:197], v[90:93]
	v_mfma_f32_16x16x32_bf16 v[82:85], v[170:173], v[204:207], v[82:85]
	v_mfma_f32_16x16x32_bf16 v[74:77], v[178:181], v[204:207], v[74:77]
	v_mfma_f32_16x16x32_bf16 v[70:73], v[170:173], v[212:215], v[70:73]
	v_mfma_f32_16x16x32_bf16 v[66:69], v[178:181], v[212:215], v[66:69]
	s_setprio 0
	s_barrier
	s_mov_b32 m0, s34
	v_lshl_add_u64 v[142:143], s[78:79], 0, v[134:135]
	ds_read_b128 v[182:185], v148 offset:16384
	ds_read_b128 v[186:189], v148 offset:17408
	ds_read_b128 v[190:193], v148 offset:18432
	ds_read_b128 v[194:197], v148 offset:19456
	ds_read_b128 v[200:203], v148 offset:20480
	ds_read_b128 v[204:207], v148 offset:21504
	ds_read_b128 v[208:211], v148 offset:22528
	ds_read_b128 v[212:215], v148 offset:23552
	global_load_lds_dwordx4 v[142:143], off
	v_lshl_add_u64 v[216:217], s[78:79], 0, v[130:131]
	s_mov_b32 m0, s60
	v_lshl_add_u64 v[218:219], s[80:81], 0, v[134:135]
	global_load_lds_dwordx4 v[216:217], off
	s_mov_b32 m0, s35
	v_lshl_add_u64 v[220:221], s[76:77], 0, v[132:133]
	global_load_lds_dwordx4 v[218:219], off
	v_lshl_add_u64 v[218:219], s[80:81], 0, v[130:131]
	s_mov_b32 m0, s33
	s_nop 0
	global_load_lds_dwordx4 v[218:219], off
	s_waitcnt vmcnt(6)
	s_waitcnt lgkmcnt(0)
	s_barrier
; #define PG8_STAGE(bufoff, gbase, voff) do { _Pragma("unroll") for (int _i = 0; _i < 2; ++_i) \
;         __builtin_amdgcn_global_load_lds((const unsigned*)((const char*)(gbase) + (voff)[_i]), (PG8_LAS unsigned*)(lds + (bufoff) + ldsw + _i * 8192), 16, 0, 0); } while (0)
; #define PG8_LDA(dst, b, h) do { _Pragma("unroll") for (int m = 0; m < 4; ++m) _Pragma("unroll") for (int k = 0; k < 2; ++k) dst[m][k] = *(const PG8_LAS bf16x8*)(lds + PG8_SA(b, h) + aoff + m * 2048 + k * 1024); } while (0)
; #define PG8_LDB(dst, b, h) do { _Pragma("unroll") for (int n = 0; n < 2; ++n) _Pragma("unroll") for (int k = 0; k < 2; ++k) dst[n][k] = *(const PG8_LAS bf16x8*)(lds + PG8_SB(b, h) + boff + n * 2048 + k * 1024); } while (0)
; #define PG8_MMA(ai, bj, At, Bt) do { __builtin_amdgcn_s_setprio(1); _Pragma("unroll") for (int m = 0; m < 4; ++m) _Pragma("unroll") for (int n = 0; n < 2; ++n) _Pragma("unroll") for (int k = 0; k < 2; ++k) \
;         acc[ai][bj][m][n] = __builtin_amdgcn_mfma_f32_16x16x32_bf16(Bt[n][k], At[m][k], acc[ai][bj][m][n], 0, 0, 0); __builtin_amdgcn_s_setprio(0); } while (0)
; #define PG8_WAIT_V(n) asm volatile("s_waitcnt vmcnt(" #n ")" ::: "memory")
; #define PG8_WAIT_L(n) asm volatile("s_waitcnt lgkmcnt(" #n ")" ::: "memory")
; #define PG8_BAR __builtin_amdgcn_s_barrier()
; #define PG8_SCHED __builtin_amdgcn_sched_barrier(0)
; template <class Epi, class Sched, bool ALIGN_EPI = false, bool SP2 = false>
; __device__ __forceinline__ void gemm_phase(PG8_LAS unsigned char* lds, const Gemm g, const Sched& S, const Epi& E) {
;     ...
;             PG8_WAIT_V(8); PG8_WAIT_L(0); PG8_BAR; PG8_MMA(1, 0, At, B0); PG8_MMA(1, 1, At, B1); PG8_BAR; PG8_SCHED;
;             PG8_LDB(B0, 1, 0); PG8_LDB(B1, 1, 1); PG8_SCHED; PG8_LDA(At, 1, 0); PG8_STAGE(PG8_SA(0, 1), a2 + hstepA, voffA);
;             PG8_WAIT_V(8); PG8_WAIT_L(0); PG8_BAR; PG8_MMA(0, 0, At, B0); PG8_MMA(0, 1, At, B1); PG8_BAR; PG8_SCHED;
;             PG8_LDA(At, 1, 1); PG8_STAGE(PG8_SB(1, 0), b3, voffB); PG8_STAGE(PG8_SB(1, 1), b3 + hstepB, voffB); PG8_STAGE(PG8_SA(1, 0), a3, voffA);
	s_setprio 1
	s_waitcnt lgkmcnt(0)
	v_mfma_f32_16x16x32_bf16 v[62:65], v[150:153], v[182:185], v[62:65]
	v_mfma_f32_16x16x32_bf16 v[58:61], v[158:161], v[182:185], v[58:61]
	v_mfma_f32_16x16x32_bf16 v[54:57], v[150:153], v[190:193], v[54:57]
	v_mfma_f32_16x16x32_bf16 v[46:49], v[158:161], v[190:193], v[46:49]
	v_mfma_f32_16x16x32_bf16 v[38:41], v[150:153], v[200:203], v[38:41]
	v_mfma_f32_16x16x32_bf16 v[30:33], v[158:161], v[200:203], v[30:33]
	v_mfma_f32_16x16x32_bf16 v[22:25], v[150:153], v[208:211], v[22:25]
	v_mfma_f32_16x16x32_bf16 v[14:17], v[158:161], v[208:211], v[14:17]
	v_mfma_f32_16x16x32_bf16 v[62:65], v[154:157], v[186:189], v[62:65]
	v_mfma_f32_16x16x32_bf16 v[58:61], v[162:165], v[186:189], v[58:61]
	v_lshl_add_u64 v[218:219], s[76:77], 0, v[136:137]
	s_mov_b32 m0, s65
	s_nop 0
	global_load_lds_dwordx4 v[218:219], off
	v_mfma_f32_16x16x32_bf16 v[54:57], v[154:157], v[194:197], v[54:57]
	v_mfma_f32_16x16x32_bf16 v[46:49], v[162:165], v[194:197], v[46:49]
	v_mfma_f32_16x16x32_bf16 v[38:41], v[154:157], v[204:207], v[38:41]
	v_mfma_f32_16x16x32_bf16 v[30:33], v[162:165], v[204:207], v[30:33]
	v_mfma_f32_16x16x32_bf16 v[22:25], v[154:157], v[212:215], v[22:25]
	v_mfma_f32_16x16x32_bf16 v[14:17], v[162:165], v[212:215], v[14:17]
	s_setprio 0
	s_setprio 1
	v_mfma_f32_16x16x32_bf16 v[50:53], v[166:169], v[182:185], v[50:53]
	v_mfma_f32_16x16x32_bf16 v[42:45], v[174:177], v[182:185], v[42:45]
	v_mfma_f32_16x16x32_bf16 v[34:37], v[166:169], v[190:193], v[34:37]
	v_mfma_f32_16x16x32_bf16 v[26:29], v[174:177], v[190:193], v[26:29]
	v_mfma_f32_16x16x32_bf16 v[18:21], v[166:169], v[200:203], v[18:21]
	v_mfma_f32_16x16x32_bf16 v[10:13], v[174:177], v[200:203], v[10:13]
	s_mov_b32 m0, s88
	s_nop 0
	global_load_lds_dwordx4 v[220:221], off
	v_mfma_f32_16x16x32_bf16 v[6:9], v[166:169], v[208:211], v[6:9]
	v_mfma_f32_16x16x32_bf16 v[2:5], v[174:177], v[208:211], v[2:5]
	v_mfma_f32_16x16x32_bf16 v[50:53], v[170:173], v[186:189], v[50:53]
	v_mfma_f32_16x16x32_bf16 v[42:45], v[178:181], v[186:189], v[42:45]
	v_mfma_f32_16x16x32_bf16 v[34:37], v[170:173], v[194:197], v[34:37]
	v_mfma_f32_16x16x32_bf16 v[26:29], v[178:181], v[194:197], v[26:29]
	v_mfma_f32_16x16x32_bf16 v[18:21], v[170:173], v[204:207], v[18:21]
	v_mfma_f32_16x16x32_bf16 v[10:13], v[178:181], v[204:207], v[10:13]
	v_mfma_f32_16x16x32_bf16 v[6:9], v[170:173], v[212:215], v[6:9]
	v_mfma_f32_16x16x32_bf16 v[2:5], v[178:181], v[212:215], v[2:5]
	s_setprio 0
	s_barrier
	v_add_u32_e32 v149, s13, v144
	ds_read_b128 v[150:153], v149
	ds_read_b128 v[154:157], v149 offset:1024
	ds_read_b128 v[158:161], v149 offset:2048
	ds_read_b128 v[162:165], v149 offset:3072
	v_add_u32_e32 v149, vcc_lo, v144
	ds_read_b128 v[166:169], v149
	ds_read_b128 v[170:173], v149 offset:1024
	ds_read_b128 v[174:177], v149 offset:2048
	ds_read_b128 v[178:181], v149 offset:3072
	s_mov_b32 m0, s89
	v_lshl_add_u64 v[222:223], s[74:75], 0, v[136:137]
	ds_read_b128 v[182:185], v148 offset:32768
	ds_read_b128 v[186:189], v148 offset:33792
	ds_read_b128 v[190:193], v148 offset:34816
	ds_read_b128 v[194:197], v148 offset:35840
	ds_read_b128 v[200:203], v148 offset:36864
	ds_read_b128 v[204:207], v148 offset:37888
	ds_read_b128 v[208:211], v148 offset:38912
	ds_read_b128 v[212:215], v148 offset:39936
	global_load_lds_dwordx4 v[222:223], off
	v_lshl_add_u64 v[222:223], s[74:75], 0, v[132:133]
	s_mov_b32 m0, s91
	s_nop 0
	global_load_lds_dwordx4 v[222:223], off
	s_waitcnt vmcnt(8)
	s_waitcnt lgkmcnt(0)
	s_barrier
	s_setprio 1
	s_waitcnt lgkmcnt(0)
	v_mfma_f32_16x16x32_bf16 v[126:129], v[150:153], v[182:185], v[126:129]
	v_mfma_f32_16x16x32_bf16 v[122:125], v[158:161], v[182:185], v[122:125]
	v_mfma_f32_16x16x32_bf16 v[118:121], v[150:153], v[190:193], v[118:121]
	v_mfma_f32_16x16x32_bf16 v[110:113], v[158:161], v[190:193], v[110:113]
	v_mfma_f32_16x16x32_bf16 v[102:105], v[150:153], v[200:203], v[102:105]
	v_mfma_f32_16x16x32_bf16 v[94:97], v[158:161], v[200:203], v[94:97]
	v_mfma_f32_16x16x32_bf16 v[86:89], v[150:153], v[208:211], v[86:89]
	v_mfma_f32_16x16x32_bf16 v[78:81], v[158:161], v[208:211], v[78:81]
	v_mfma_f32_16x16x32_bf16 v[126:129], v[154:157], v[186:189], v[126:129]
	v_mfma_f32_16x16x32_bf16 v[122:125], v[162:165], v[186:189], v[122:125]
	v_mfma_f32_16x16x32_bf16 v[118:121], v[154:157], v[194:197], v[118:121]
	v_mfma_f32_16x16x32_bf16 v[110:113], v[162:165], v[194:197], v[110:113]
	v_mfma_f32_16x16x32_bf16 v[102:105], v[154:157], v[204:207], v[102:105]
	v_mfma_f32_16x16x32_bf16 v[94:97], v[162:165], v[204:207], v[94:97]
	v_mfma_f32_16x16x32_bf16 v[86:89], v[154:157], v[212:215], v[86:89]
	v_mfma_f32_16x16x32_bf16 v[78:81], v[162:165], v[212:215], v[78:81]
	s_setprio 0
	s_setprio 1
	v_mfma_f32_16x16x32_bf16 v[114:117], v[166:169], v[182:185], v[114:117]
	v_mfma_f32_16x16x32_bf16 v[106:109], v[174:177], v[182:185], v[106:109]
	v_mfma_f32_16x16x32_bf16 v[98:101], v[166:169], v[190:193], v[98:101]
	v_mfma_f32_16x16x32_bf16 v[90:93], v[174:177], v[190:193], v[90:93]
	v_mfma_f32_16x16x32_bf16 v[82:85], v[166:169], v[200:203], v[82:85]
	v_mfma_f32_16x16x32_bf16 v[74:77], v[174:177], v[200:203], v[74:77]
	v_mfma_f32_16x16x32_bf16 v[70:73], v[166:169], v[208:211], v[70:73]
	v_mfma_f32_16x16x32_bf16 v[66:69], v[174:177], v[208:211], v[66:69]
	v_mfma_f32_16x16x32_bf16 v[114:117], v[170:173], v[186:189], v[114:117]
	v_mfma_f32_16x16x32_bf16 v[106:109], v[178:181], v[186:189], v[106:109]
	v_mfma_f32_16x16x32_bf16 v[98:101], v[170:173], v[194:197], v[98:101]
	v_mfma_f32_16x16x32_bf16 v[90:93], v[178:181], v[194:197], v[90:93]
	v_mfma_f32_16x16x32_bf16 v[82:85], v[170:173], v[204:207], v[82:85]
	v_mfma_f32_16x16x32_bf16 v[74:77], v[178:181], v[204:207], v[74:77]
	v_mfma_f32_16x16x32_bf16 v[70:73], v[170:173], v[212:215], v[70:73]
	v_mfma_f32_16x16x32_bf16 v[66:69], v[178:181], v[212:215], v[66:69]
	s_setprio 0
	s_barrier
; #define PG8_STAGE(bufoff, gbase, voff) do { _Pragma("unroll") for (int _i = 0; _i < 2; ++_i) \
;         __builtin_amdgcn_global_load_lds((const unsigned*)((const char*)(gbase) + (voff)[_i]), (PG8_LAS unsigned*)(lds + (bufoff) + ldsw + _i * 8192), 16, 0, 0); } while (0)
; #define PG8_LDA(dst, b, h) do { _Pragma("unroll") for (int m = 0; m < 4; ++m) _Pragma("unroll") for (int k = 0; k < 2; ++k) dst[m][k] = *(const PG8_LAS bf16x8*)(lds + PG8_SA(b, h) + aoff + m * 2048 + k * 1024); } while (0)
; #define PG8_MMA(ai, bj, At, Bt) do { __builtin_amdgcn_s_setprio(1); _Pragma("unroll") for (int m = 0; m < 4; ++m) _Pragma("unroll") for (int n = 0; n < 2; ++n) _Pragma("unroll") for (int k = 0; k < 2; ++k) \
;         acc[ai][bj][m][n] = __builtin_amdgcn_mfma_f32_16x16x32_bf16(Bt[n][k], At[m][k], acc[ai][bj][m][n], 0, 0, 0); __builtin_amdgcn_s_setprio(0); } while (0)
; #define PG8_WAIT_V(n) asm volatile("s_waitcnt vmcnt(" #n ")" ::: "memory")
; #define PG8_WAIT_L(n) asm volatile("s_waitcnt lgkmcnt(" #n ")" ::: "memory")
; #define PG8_BAR __builtin_amdgcn_s_barrier()
; #define PG8_SCHED __builtin_amdgcn_sched_barrier(0)
; template <class Epi, class Sched, bool ALIGN_EPI = false, bool SP2 = false>
; __device__ __forceinline__ void gemm_phase(PG8_LAS unsigned char* lds, const Gemm g, const Sched& S, const Epi& E) {
;     ...
;         for (int t = 0; t < nt; t += 2) {
;             const bool last = (t == nt - 2);
;             const char* a1 = cA + (size_t)(t + 1) * kstep;
;             const char* a2 = last ? nA : cA + (size_t)(t + 2) * kstep; const char* b2 = last ? nB : cB + (size_t)(t + 2) * kstep;
;     ...
;             PG8_LDA(At, 1, 1); PG8_STAGE(PG8_SB(1, 0), b3, voffB); PG8_STAGE(PG8_SB(1, 1), b3 + hstepB, voffB); PG8_STAGE(PG8_SA(1, 0), a3, voffA);
;             PG8_WAIT_V(8); PG8_WAIT_L(0); PG8_BAR; PG8_MMA(1, 0, At, B0); PG8_MMA(1, 1, At, B1); PG8_BAR; PG8_SCHED;
	s_mov_b32 m0, vcc_hi
	v_lshl_add_u64 v[142:143], v[142:143], 0, s[8:9]
	ds_read_b128 v[182:185], v148 offset:49152
	ds_read_b128 v[186:189], v148 offset:50176
	ds_read_b128 v[190:193], v148 offset:51200
	ds_read_b128 v[194:197], v148 offset:52224
	ds_read_b128 v[200:203], v148 offset:53248
	ds_read_b128 v[204:207], v148 offset:54272
	ds_read_b128 v[208:211], v148 offset:55296
	ds_read_b128 v[212:215], v148 offset:56320
	global_load_lds_dwordx4 v[142:143], off
	v_lshl_add_u64 v[142:143], v[216:217], 0, s[8:9]
	s_mov_b32 m0, s45
	s_nop 0
	global_load_lds_dwordx4 v[142:143], off
	v_lshl_add_u64 v[142:143], s[72:73], 0, v[134:135]
	s_mov_b32 m0, s43
	s_nop 0
	global_load_lds_dwordx4 v[142:143], off
	v_lshl_add_u64 v[142:143], s[72:73], 0, v[130:131]
	s_mov_b32 m0, s12
	s_nop 0
	global_load_lds_dwordx4 v[142:143], off
	s_waitcnt vmcnt(6)
	s_waitcnt lgkmcnt(0)
	s_barrier
	s_setprio 1
	s_waitcnt lgkmcnt(0)
	v_mfma_f32_16x16x32_bf16 v[62:65], v[150:153], v[182:185], v[62:65]
	v_mfma_f32_16x16x32_bf16 v[58:61], v[158:161], v[182:185], v[58:61]
	v_mfma_f32_16x16x32_bf16 v[54:57], v[150:153], v[190:193], v[54:57]
	v_mfma_f32_16x16x32_bf16 v[46:49], v[158:161], v[190:193], v[46:49]
	v_mfma_f32_16x16x32_bf16 v[38:41], v[150:153], v[200:203], v[38:41]
	v_mfma_f32_16x16x32_bf16 v[30:33], v[158:161], v[200:203], v[30:33]
	v_mfma_f32_16x16x32_bf16 v[22:25], v[150:153], v[208:211], v[22:25]
	v_mfma_f32_16x16x32_bf16 v[14:17], v[158:161], v[208:211], v[14:17]
	v_mfma_f32_16x16x32_bf16 v[62:65], v[154:157], v[186:189], v[62:65]
	v_mfma_f32_16x16x32_bf16 v[58:61], v[162:165], v[186:189], v[58:61]
	v_lshl_add_u64 v[142:143], v[218:219], 0, s[8:9]
	s_mov_b32 m0, s93
	s_nop 0
	global_load_lds_dwordx4 v[142:143], off
	v_mfma_f32_16x16x32_bf16 v[54:57], v[154:157], v[194:197], v[54:57]
	v_mfma_f32_16x16x32_bf16 v[46:49], v[162:165], v[194:197], v[46:49]
	v_mfma_f32_16x16x32_bf16 v[38:41], v[154:157], v[204:207], v[38:41]
	v_mfma_f32_16x16x32_bf16 v[30:33], v[162:165], v[204:207], v[30:33]
	v_mfma_f32_16x16x32_bf16 v[22:25], v[154:157], v[212:215], v[22:25]
	v_mfma_f32_16x16x32_bf16 v[14:17], v[162:165], v[212:215], v[14:17]
	s_setprio 0
	s_setprio 1
	v_mfma_f32_16x16x32_bf16 v[50:53], v[166:169], v[182:185], v[50:53]
	v_mfma_f32_16x16x32_bf16 v[42:45], v[174:177], v[182:185], v[42:45]
	v_mfma_f32_16x16x32_bf16 v[34:37], v[166:169], v[190:193], v[34:37]
	v_mfma_f32_16x16x32_bf16 v[26:29], v[174:177], v[190:193], v[26:29]
	v_mfma_f32_16x16x32_bf16 v[18:21], v[166:169], v[200:203], v[18:21]
	v_mfma_f32_16x16x32_bf16 v[10:13], v[174:177], v[200:203], v[10:13]
	v_lshl_add_u64 v[142:143], v[220:221], 0, s[8:9]
	s_mov_b32 m0, s94
	s_nop 0
	global_load_lds_dwordx4 v[142:143], off
	v_mfma_f32_16x16x32_bf16 v[6:9], v[166:169], v[208:211], v[6:9]
	v_mfma_f32_16x16x32_bf16 v[2:5], v[174:177], v[208:211], v[2:5]
	v_mfma_f32_16x16x32_bf16 v[50:53], v[170:173], v[186:189], v[50:53]
	v_mfma_f32_16x16x32_bf16 v[42:45], v[178:181], v[186:189], v[42:45]
	v_mfma_f32_16x16x32_bf16 v[34:37], v[170:173], v[194:197], v[34:37]
	v_mfma_f32_16x16x32_bf16 v[26:29], v[178:181], v[194:197], v[26:29]
	v_mfma_f32_16x16x32_bf16 v[18:21], v[170:173], v[204:207], v[18:21]
	v_mfma_f32_16x16x32_bf16 v[10:13], v[178:181], v[204:207], v[10:13]
	v_mfma_f32_16x16x32_bf16 v[6:9], v[170:173], v[212:215], v[6:9]
	v_mfma_f32_16x16x32_bf16 v[2:5], v[178:181], v[212:215], v[2:5]
	s_setprio 0
	s_barrier
	s_movk_i32 s43, 0x100
	s_andn2_b64 vcc, exec, s[70:71]
	s_mov_b64 s[72:73], -1
	s_mov_b64 s[70:71], 0
	s_cbranch_vccz .LBB0_224
	s_and_b64 vcc, exec, s[38:39]
	s_cbranch_vccz .LBB0_227
	s_barrier

; #define PG8_STAGE(bufoff, gbase, voff) do { _Pragma("unroll") for (int _i = 0; _i < 2; ++_i) \
;         __builtin_amdgcn_global_load_lds((const unsigned*)((const char*)(gbase) + (voff)[_i]), (PG8_LAS unsigned*)(lds + (bufoff) + ldsw + _i * 8192), 16, 0, 0); } while (0)
; #define PG8_LDA(dst, b, h) do { _Pragma("unroll") for (int m = 0; m < 4; ++m) _Pragma("unroll") for (int k = 0; k < 2; ++k) dst[m][k] = *(const PG8_LAS bf16x8*)(lds + PG8_SA(b, h) + aoff + m * 2048 + k * 1024); } while (0)
; #define PG8_LDB(dst, b, h) do { _Pragma("unroll") for (int n = 0; n < 2; ++n) _Pragma("unroll") for (int k = 0; k < 2; ++k) dst[n][k] = *(const PG8_LAS bf16x8*)(lds + PG8_SB(b, h) + boff + n * 2048 + k * 1024); } while (0)
; #define PG8_MMA(ai, bj, At, Bt) do { __builtin_amdgcn_s_setprio(1); _Pragma("unroll") for (int m = 0; m < 4; ++m) _Pragma("unroll") for (int n = 0; n < 2; ++n) _Pragma("unroll") for (int k = 0; k < 2; ++k) \
;         acc[ai][bj][m][n] = __builtin_amdgcn_mfma_f32_16x16x32_bf16(Bt[n][k], At[m][k], acc[ai][bj][m][n], 0, 0, 0); __builtin_amdgcn_s_setprio(0); } while (0)
; #define PG8_WAIT_V(n) asm volatile("s_waitcnt vmcnt(" #n ")" ::: "memory")
; #define PG8_WAIT_L(n) asm volatile("s_waitcnt lgkmcnt(" #n ")" ::: "memory")
; #define PG8_BAR __builtin_amdgcn_s_barrier()
; #define PG8_SCHED __builtin_amdgcn_sched_barrier(0)
; template <class Epi, class Sched, bool ALIGN_EPI = false, bool SP2 = false>
; __device__ __forceinline__ void gemm_phase(PG8_LAS unsigned char* lds, const Gemm g, const Sched& S, const Epi& E) {
;     ...
;             const char* a1 = cA + (size_t)(t + 1) * kstep;
;             const char* a2 = last ? nA : cA + (size_t)(t + 2) * kstep; const char* b2 = last ? nB : cB + (size_t)(t + 2) * kstep;
;             const char* a3 = a2 + kstep; const char* b3 = b2 + kstep;
;             if (last && has_next) S.a_ready(nxt);
;             if constexpr (SP2) {
;             PG8_LDB(B0, 0, 0); PG8_LDB(B1, 0, 1); PG8_SCHED; PG8_LDA(At, 0, 0); PG8_STAGE(PG8_SA(1, 1), a1 + hstepA, voffA);
;             PG8_WAIT_V(8); PG8_WAIT_L(0); PG8_BAR; PG8_MMA(0, 0, At, B0); PG8_MMA(0, 1, At, B1); PG8_BAR; PG8_SCHED;
;             PG8_LDA(At, 0, 1); PG8_STAGE(PG8_SB(0, 0), b2, voffB); PG8_STAGE(PG8_SB(0, 1), b2 + hstepB, voffB); PG8_STAGE(PG8_SA(0, 0), a2, voffA);
.LBB0_378:
	ds_read_b128 v[146:149], v154
	ds_read_b128 v[158:161], v154 offset:1024
	ds_read_b128 v[162:165], v154 offset:2048
	ds_read_b128 v[166:169], v154 offset:3072
	ds_read_b128 v[170:173], v155
	ds_read_b128 v[174:177], v155 offset:1024
	ds_read_b128 v[178:181], v155 offset:2048
	ds_read_b128 v[182:185], v155 offset:3072
	s_add_u32 s12, s0, 0xfffc0080
	s_addc_u32 s13, s1, -1
	s_cmp_eq_u32 s97, 12
	s_cselect_b32 s73, s47, s13
	s_cselect_b32 s72, s90, s12
	s_cselect_b32 s71, s65, s96
	s_cselect_b32 s70, s64, s95
	v_lshl_add_u64 v[150:151], s[0:1], 0, v[138:139]
	s_add_i32 m0, s69, 0xc000
	ds_read_b128 v[186:189], v156
	ds_read_b128 v[190:193], v156 offset:1024
	ds_read_b128 v[194:197], v156 offset:2048
	ds_read_b128 v[200:203], v156 offset:3072
	ds_read_b128 v[204:207], v156 offset:4096
	ds_read_b128 v[208:211], v156 offset:5120
	ds_read_b128 v[212:215], v156 offset:6144
	ds_read_b128 v[216:219], v156 offset:7168
	global_load_lds_dwordx4 v[150:151], off
	v_lshl_add_u64 v[150:151], s[0:1], 0, v[140:141]
	s_add_i32 m0, s69, 0xe000
	s_nop 0
	global_load_lds_dwordx4 v[150:151], off
	s_waitcnt vmcnt(8)
	s_waitcnt lgkmcnt(0)
	s_barrier
	s_setprio 1
	s_waitcnt lgkmcnt(0)
	v_mfma_f32_16x16x32_bf16 v[126:129], v[146:149], v[186:189], v[126:129]
	v_mfma_f32_16x16x32_bf16 v[122:125], v[162:165], v[186:189], v[122:125]
	v_mfma_f32_16x16x32_bf16 v[110:113], v[146:149], v[194:197], v[110:113]
	v_mfma_f32_16x16x32_bf16 v[106:109], v[162:165], v[194:197], v[106:109]
	v_mfma_f32_16x16x32_bf16 v[94:97], v[146:149], v[204:207], v[94:97]
	v_mfma_f32_16x16x32_bf16 v[90:93], v[162:165], v[204:207], v[90:93]
	v_mfma_f32_16x16x32_bf16 v[78:81], v[146:149], v[212:215], v[78:81]
	v_mfma_f32_16x16x32_bf16 v[74:77], v[162:165], v[212:215], v[74:77]
	v_mfma_f32_16x16x32_bf16 v[126:129], v[158:161], v[190:193], v[126:129]
	v_mfma_f32_16x16x32_bf16 v[122:125], v[166:169], v[190:193], v[122:125]
	v_mfma_f32_16x16x32_bf16 v[110:113], v[158:161], v[200:203], v[110:113]
	v_mfma_f32_16x16x32_bf16 v[106:109], v[166:169], v[200:203], v[106:109]
	v_mfma_f32_16x16x32_bf16 v[94:97], v[158:161], v[208:211], v[94:97]
	v_mfma_f32_16x16x32_bf16 v[90:93], v[166:169], v[208:211], v[90:93]
	v_mfma_f32_16x16x32_bf16 v[78:81], v[158:161], v[216:219], v[78:81]
	v_mfma_f32_16x16x32_bf16 v[74:77], v[166:169], v[216:219], v[74:77]
	s_setprio 0
	s_setprio 1
	v_mfma_f32_16x16x32_bf16 v[118:121], v[170:173], v[186:189], v[118:121]
	v_mfma_f32_16x16x32_bf16 v[114:117], v[178:181], v[186:189], v[114:117]
	v_mfma_f32_16x16x32_bf16 v[102:105], v[170:173], v[194:197], v[102:105]
	v_mfma_f32_16x16x32_bf16 v[98:101], v[178:181], v[194:197], v[98:101]
	v_mfma_f32_16x16x32_bf16 v[86:89], v[170:173], v[204:207], v[86:89]
	v_mfma_f32_16x16x32_bf16 v[82:85], v[178:181], v[204:207], v[82:85]
	v_mfma_f32_16x16x32_bf16 v[70:73], v[170:173], v[212:215], v[70:73]
	v_mfma_f32_16x16x32_bf16 v[66:69], v[178:181], v[212:215], v[66:69]
	v_mfma_f32_16x16x32_bf16 v[118:121], v[174:177], v[190:193], v[118:121]
	v_mfma_f32_16x16x32_bf16 v[114:117], v[182:185], v[190:193], v[114:117]
	v_mfma_f32_16x16x32_bf16 v[102:105], v[174:177], v[200:203], v[102:105]
	v_mfma_f32_16x16x32_bf16 v[98:101], v[182:185], v[200:203], v[98:101]
	v_mfma_f32_16x16x32_bf16 v[86:89], v[174:177], v[208:211], v[86:89]
	v_mfma_f32_16x16x32_bf16 v[82:85], v[182:185], v[208:211], v[82:85]
	v_mfma_f32_16x16x32_bf16 v[70:73], v[174:177], v[216:219], v[70:73]
	v_mfma_f32_16x16x32_bf16 v[66:69], v[182:185], v[216:219], v[66:69]
	s_setprio 0
	s_barrier
	s_add_i32 s12, s87, s76
	v_lshl_add_u64 v[150:151], s[70:71], 0, v[134:135]
	s_mov_b32 m0, s12
	ds_read_b128 v[186:189], v156 offset:16384
	ds_read_b128 v[190:193], v156 offset:17408
	ds_read_b128 v[194:197], v156 offset:18432
	ds_read_b128 v[200:203], v156 offset:19456
	ds_read_b128 v[204:207], v156 offset:20480
	ds_read_b128 v[208:211], v156 offset:21504
	ds_read_b128 v[212:215], v156 offset:22528
	ds_read_b128 v[216:219], v156 offset:23552
	global_load_lds_dwordx4 v[150:151], off
	s_add_i32 m0, s12, 0x2000
	s_add_u32 s12, s70, 0x40000
	v_lshl_add_u64 v[220:221], s[70:71], 0, v[130:131]
	s_addc_u32 s13, s71, 0
	s_add_i32 s33, s88, s76
	global_load_lds_dwordx4 v[220:221], off
	v_lshl_add_u64 v[222:223], s[12:13], 0, v[134:135]
	s_mov_b32 m0, s33
	v_lshl_add_u64 v[224:225], s[72:73], 0, v[132:133]
	global_load_lds_dwordx4 v[222:223], off
	v_lshl_add_u64 v[222:223], s[12:13], 0, v[130:131]
	s_add_i32 m0, s33, 0x2000
	s_nop 0
	global_load_lds_dwordx4 v[222:223], off
	s_waitcnt vmcnt(6)
	s_waitcnt lgkmcnt(0)
	s_barrier
; #define PG8_STAGE(bufoff, gbase, voff) do { _Pragma("unroll") for (int _i = 0; _i < 2; ++_i) \
;         __builtin_amdgcn_global_load_lds((const unsigned*)((const char*)(gbase) + (voff)[_i]), (PG8_LAS unsigned*)(lds + (bufoff) + ldsw + _i * 8192), 16, 0, 0); } while (0)
; #define PG8_LDA(dst, b, h) do { _Pragma("unroll") for (int m = 0; m < 4; ++m) _Pragma("unroll") for (int k = 0; k < 2; ++k) dst[m][k] = *(const PG8_LAS bf16x8*)(lds + PG8_SA(b, h) + aoff + m * 2048 + k * 1024); } while (0)
; #define PG8_LDB(dst, b, h) do { _Pragma("unroll") for (int n = 0; n < 2; ++n) _Pragma("unroll") for (int k = 0; k < 2; ++k) dst[n][k] = *(const PG8_LAS bf16x8*)(lds + PG8_SB(b, h) + boff + n * 2048 + k * 1024); } while (0)
; #define PG8_MMA(ai, bj, At, Bt) do { __builtin_amdgcn_s_setprio(1); _Pragma("unroll") for (int m = 0; m < 4; ++m) _Pragma("unroll") for (int n = 0; n < 2; ++n) _Pragma("unroll") for (int k = 0; k < 2; ++k) \
;         acc[ai][bj][m][n] = __builtin_amdgcn_mfma_f32_16x16x32_bf16(Bt[n][k], At[m][k], acc[ai][bj][m][n], 0, 0, 0); __builtin_amdgcn_s_setprio(0); } while (0)
; #define PG8_WAIT_V(n) asm volatile("s_waitcnt vmcnt(" #n ")" ::: "memory")
; #define PG8_WAIT_L(n) asm volatile("s_waitcnt lgkmcnt(" #n ")" ::: "memory")
; #define PG8_BAR __builtin_amdgcn_s_barrier()
; #define PG8_SCHED __builtin_amdgcn_sched_barrier(0)
; template <class Epi, class Sched, bool ALIGN_EPI = false, bool SP2 = false>
; __device__ __forceinline__ void gemm_phase(PG8_LAS unsigned char* lds, const Gemm g, const Sched& S, const Epi& E) {
;     ...
;             PG8_WAIT_V(8); PG8_WAIT_L(0); PG8_BAR; PG8_MMA(1, 0, At, B0); PG8_MMA(1, 1, At, B1); PG8_BAR; PG8_SCHED;
;             PG8_LDB(B0, 1, 0); PG8_LDB(B1, 1, 1); PG8_SCHED; PG8_LDA(At, 1, 0); PG8_STAGE(PG8_SA(0, 1), a2 + hstepA, voffA);
;             PG8_WAIT_V(8); PG8_WAIT_L(0); PG8_BAR; PG8_MMA(0, 0, At, B0); PG8_MMA(0, 1, At, B1); PG8_BAR; PG8_SCHED;
;             PG8_LDA(At, 1, 1); PG8_STAGE(PG8_SB(1, 0), b3, voffB); PG8_STAGE(PG8_SB(1, 1), b3 + hstepB, voffB); PG8_STAGE(PG8_SA(1, 0), a3, voffA);
	s_setprio 1
	s_waitcnt lgkmcnt(0)
	v_mfma_f32_16x16x32_bf16 v[62:65], v[146:149], v[186:189], v[62:65]
	v_mfma_f32_16x16x32_bf16 v[58:61], v[162:165], v[186:189], v[58:61]
	v_mfma_f32_16x16x32_bf16 v[46:49], v[146:149], v[194:197], v[46:49]
	v_mfma_f32_16x16x32_bf16 v[42:45], v[162:165], v[194:197], v[42:45]
	v_mfma_f32_16x16x32_bf16 v[30:33], v[146:149], v[204:207], v[30:33]
	v_mfma_f32_16x16x32_bf16 v[26:29], v[162:165], v[204:207], v[26:29]
	v_mfma_f32_16x16x32_bf16 v[14:17], v[146:149], v[212:215], v[14:17]
	v_mfma_f32_16x16x32_bf16 v[10:13], v[162:165], v[212:215], v[10:13]
	v_mfma_f32_16x16x32_bf16 v[62:65], v[158:161], v[190:193], v[62:65]
	v_mfma_f32_16x16x32_bf16 v[58:61], v[166:169], v[190:193], v[58:61]
	v_lshl_add_u64 v[222:223], s[72:73], 0, v[136:137]
	s_mov_b32 m0, s69
	s_nop 0
	global_load_lds_dwordx4 v[222:223], off
	v_mfma_f32_16x16x32_bf16 v[46:49], v[158:161], v[200:203], v[46:49]
	v_mfma_f32_16x16x32_bf16 v[42:45], v[166:169], v[200:203], v[42:45]
	v_mfma_f32_16x16x32_bf16 v[30:33], v[158:161], v[208:211], v[30:33]
	v_mfma_f32_16x16x32_bf16 v[26:29], v[166:169], v[208:211], v[26:29]
	v_mfma_f32_16x16x32_bf16 v[14:17], v[158:161], v[216:219], v[14:17]
	v_mfma_f32_16x16x32_bf16 v[10:13], v[166:169], v[216:219], v[10:13]
	s_setprio 0
	s_setprio 1
	v_mfma_f32_16x16x32_bf16 v[54:57], v[170:173], v[186:189], v[54:57]
	v_mfma_f32_16x16x32_bf16 v[50:53], v[178:181], v[186:189], v[50:53]
	v_mfma_f32_16x16x32_bf16 v[38:41], v[170:173], v[194:197], v[38:41]
	v_mfma_f32_16x16x32_bf16 v[34:37], v[178:181], v[194:197], v[34:37]
	v_mfma_f32_16x16x32_bf16 v[22:25], v[170:173], v[204:207], v[22:25]
	v_mfma_f32_16x16x32_bf16 v[18:21], v[178:181], v[204:207], v[18:21]
	s_mov_b32 m0, s79
	s_nop 0
	global_load_lds_dwordx4 v[224:225], off
	v_mfma_f32_16x16x32_bf16 v[6:9], v[170:173], v[212:215], v[6:9]
	v_mfma_f32_16x16x32_bf16 v[2:5], v[178:181], v[212:215], v[2:5]
	v_mfma_f32_16x16x32_bf16 v[54:57], v[174:177], v[190:193], v[54:57]
	v_mfma_f32_16x16x32_bf16 v[50:53], v[182:185], v[190:193], v[50:53]
	v_mfma_f32_16x16x32_bf16 v[38:41], v[174:177], v[200:203], v[38:41]
	v_mfma_f32_16x16x32_bf16 v[34:37], v[182:185], v[200:203], v[34:37]
	v_mfma_f32_16x16x32_bf16 v[22:25], v[174:177], v[208:211], v[22:25]
	v_mfma_f32_16x16x32_bf16 v[18:21], v[182:185], v[208:211], v[18:21]
	v_mfma_f32_16x16x32_bf16 v[6:9], v[174:177], v[216:219], v[6:9]
	v_mfma_f32_16x16x32_bf16 v[2:5], v[182:185], v[216:219], v[2:5]
	s_setprio 0
	s_barrier
	s_add_i32 s33, 0, 0x18000
	v_add_u32_e32 v157, s33, v152
	s_add_i32 s34, 0, 0x1c000
	ds_read_b128 v[146:149], v157
	ds_read_b128 v[158:161], v157 offset:1024
	ds_read_b128 v[162:165], v157 offset:2048
	ds_read_b128 v[166:169], v157 offset:3072
	v_add_u32_e32 v157, s34, v152
	ds_read_b128 v[170:173], v157
	ds_read_b128 v[174:177], v157 offset:1024
	ds_read_b128 v[178:181], v157 offset:2048
	ds_read_b128 v[182:185], v157 offset:3072
	s_add_u32 s12, s72, 0x40000
	s_addc_u32 s13, s73, 0
	s_mov_b32 m0, s80
	v_lshl_add_u64 v[226:227], s[12:13], 0, v[136:137]
	ds_read_b128 v[186:189], v156 offset:32768
	ds_read_b128 v[190:193], v156 offset:33792
	ds_read_b128 v[194:197], v156 offset:34816
	ds_read_b128 v[200:203], v156 offset:35840
	ds_read_b128 v[204:207], v156 offset:36864
	ds_read_b128 v[208:211], v156 offset:37888
	ds_read_b128 v[212:215], v156 offset:38912
	ds_read_b128 v[216:219], v156 offset:39936
	global_load_lds_dwordx4 v[226:227], off
	v_lshl_add_u64 v[226:227], s[12:13], 0, v[132:133]
	s_mov_b32 m0, s81
	s_nop 0
	global_load_lds_dwordx4 v[226:227], off
	s_waitcnt vmcnt(8)
	s_waitcnt lgkmcnt(0)
	s_barrier
	s_setprio 1
	s_waitcnt lgkmcnt(0)
	v_mfma_f32_16x16x32_bf16 v[126:129], v[146:149], v[186:189], v[126:129]
	v_mfma_f32_16x16x32_bf16 v[122:125], v[162:165], v[186:189], v[122:125]
	v_mfma_f32_16x16x32_bf16 v[110:113], v[146:149], v[194:197], v[110:113]
	v_mfma_f32_16x16x32_bf16 v[106:109], v[162:165], v[194:197], v[106:109]
	v_mfma_f32_16x16x32_bf16 v[94:97], v[146:149], v[204:207], v[94:97]
	v_mfma_f32_16x16x32_bf16 v[90:93], v[162:165], v[204:207], v[90:93]
	v_mfma_f32_16x16x32_bf16 v[78:81], v[146:149], v[212:215], v[78:81]
	v_mfma_f32_16x16x32_bf16 v[74:77], v[162:165], v[212:215], v[74:77]
	v_mfma_f32_16x16x32_bf16 v[126:129], v[158:161], v[190:193], v[126:129]
	v_mfma_f32_16x16x32_bf16 v[122:125], v[166:169], v[190:193], v[122:125]
	v_mfma_f32_16x16x32_bf16 v[110:113], v[158:161], v[200:203], v[110:113]
	v_mfma_f32_16x16x32_bf16 v[106:109], v[166:169], v[200:203], v[106:109]
	v_mfma_f32_16x16x32_bf16 v[94:97], v[158:161], v[208:211], v[94:97]
	v_mfma_f32_16x16x32_bf16 v[90:93], v[166:169], v[208:211], v[90:93]
	v_mfma_f32_16x16x32_bf16 v[78:81], v[158:161], v[216:219], v[78:81]
	v_mfma_f32_16x16x32_bf16 v[74:77], v[166:169], v[216:219], v[74:77]
	s_setprio 0
	s_setprio 1
	v_mfma_f32_16x16x32_bf16 v[118:121], v[170:173], v[186:189], v[118:121]
	v_mfma_f32_16x16x32_bf16 v[114:117], v[178:181], v[186:189], v[114:117]
	v_mfma_f32_16x16x32_bf16 v[102:105], v[170:173], v[194:197], v[102:105]
	v_mfma_f32_16x16x32_bf16 v[98:101], v[178:181], v[194:197], v[98:101]
	v_mfma_f32_16x16x32_bf16 v[86:89], v[170:173], v[204:207], v[86:89]
	v_mfma_f32_16x16x32_bf16 v[82:85], v[178:181], v[204:207], v[82:85]
	v_mfma_f32_16x16x32_bf16 v[70:73], v[170:173], v[212:215], v[70:73]
	v_mfma_f32_16x16x32_bf16 v[66:69], v[178:181], v[212:215], v[66:69]
	v_mfma_f32_16x16x32_bf16 v[118:121], v[174:177], v[190:193], v[118:121]
	v_mfma_f32_16x16x32_bf16 v[114:117], v[182:185], v[190:193], v[114:117]
	v_mfma_f32_16x16x32_bf16 v[102:105], v[174:177], v[200:203], v[102:105]
	v_mfma_f32_16x16x32_bf16 v[98:101], v[182:185], v[200:203], v[98:101]
	v_mfma_f32_16x16x32_bf16 v[86:89], v[174:177], v[208:211], v[86:89]
	v_mfma_f32_16x16x32_bf16 v[82:85], v[182:185], v[208:211], v[82:85]
	v_mfma_f32_16x16x32_bf16 v[70:73], v[174:177], v[216:219], v[70:73]
	v_mfma_f32_16x16x32_bf16 v[66:69], v[182:185], v[216:219], v[66:69]
	s_setprio 0
	s_barrier
; #define PG8_STAGE(bufoff, gbase, voff) do { _Pragma("unroll") for (int _i = 0; _i < 2; ++_i) \
;         __builtin_amdgcn_global_load_lds((const unsigned*)((const char*)(gbase) + (voff)[_i]), (PG8_LAS unsigned*)(lds + (bufoff) + ldsw + _i * 8192), 16, 0, 0); } while (0)
; #define PG8_LDA(dst, b, h) do { _Pragma("unroll") for (int m = 0; m < 4; ++m) _Pragma("unroll") for (int k = 0; k < 2; ++k) dst[m][k] = *(const PG8_LAS bf16x8*)(lds + PG8_SA(b, h) + aoff + m * 2048 + k * 1024); } while (0)
; #define PG8_MMA(ai, bj, At, Bt) do { __builtin_amdgcn_s_setprio(1); _Pragma("unroll") for (int m = 0; m < 4; ++m) _Pragma("unroll") for (int n = 0; n < 2; ++n) _Pragma("unroll") for (int k = 0; k < 2; ++k) \
;         acc[ai][bj][m][n] = __builtin_amdgcn_mfma_f32_16x16x32_bf16(Bt[n][k], At[m][k], acc[ai][bj][m][n], 0, 0, 0); __builtin_amdgcn_s_setprio(0); } while (0)
; #define PG8_WAIT_V(n) asm volatile("s_waitcnt vmcnt(" #n ")" ::: "memory")
; #define PG8_WAIT_L(n) asm volatile("s_waitcnt lgkmcnt(" #n ")" ::: "memory")
; #define PG8_BAR __builtin_amdgcn_s_barrier()
; #define PG8_SCHED __builtin_amdgcn_sched_barrier(0)
; template <class Epi, class Sched, bool ALIGN_EPI = false, bool SP2 = false>
; __device__ __forceinline__ void gemm_phase(PG8_LAS unsigned char* lds, const Gemm g, const Sched& S, const Epi& E) {
;     ...
;         for (int t = 0; t < nt; t += 2) {
;             const bool last = (t == nt - 2);
;             const char* a1 = cA + (size_t)(t + 1) * kstep;
;             const char* a2 = last ? nA : cA + (size_t)(t + 2) * kstep; const char* b2 = last ? nB : cB + (size_t)(t + 2) * kstep;
;     ...
;             PG8_LDA(At, 1, 1); PG8_STAGE(PG8_SB(1, 0), b3, voffB); PG8_STAGE(PG8_SB(1, 1), b3 + hstepB, voffB); PG8_STAGE(PG8_SA(1, 0), a3, voffA);
;             PG8_WAIT_V(8); PG8_WAIT_L(0); PG8_BAR; PG8_MMA(1, 0, At, B0); PG8_MMA(1, 1, At, B1); PG8_BAR; PG8_SCHED;
	s_add_i32 s12, s33, s76
	v_lshl_add_u64 v[150:151], v[150:151], 0, s[8:9]
	s_mov_b32 m0, s12
	ds_read_b128 v[186:189], v156 offset:49152
	ds_read_b128 v[190:193], v156 offset:50176
	ds_read_b128 v[194:197], v156 offset:51200
	ds_read_b128 v[200:203], v156 offset:52224
	ds_read_b128 v[204:207], v156 offset:53248
	ds_read_b128 v[208:211], v156 offset:54272
	ds_read_b128 v[212:215], v156 offset:55296
	ds_read_b128 v[216:219], v156 offset:56320
	global_load_lds_dwordx4 v[150:151], off
	s_add_i32 m0, s12, 0x2000
	s_add_u32 s12, s70, 0x40080
	v_lshl_add_u64 v[150:151], v[220:221], 0, s[8:9]
	s_addc_u32 s13, s71, 0
	s_add_i32 s33, s34, s76
	global_load_lds_dwordx4 v[150:151], off
	v_lshl_add_u64 v[150:151], s[12:13], 0, v[134:135]
	s_mov_b32 m0, s33
	s_nop 0
	global_load_lds_dwordx4 v[150:151], off
	v_lshl_add_u64 v[150:151], s[12:13], 0, v[130:131]
	s_add_i32 m0, s33, 0x2000
	s_nop 0
	global_load_lds_dwordx4 v[150:151], off
	s_waitcnt vmcnt(6)
	s_waitcnt lgkmcnt(0)
	s_barrier
	s_setprio 1
	s_waitcnt lgkmcnt(0)
	v_mfma_f32_16x16x32_bf16 v[62:65], v[146:149], v[186:189], v[62:65]
	v_mfma_f32_16x16x32_bf16 v[58:61], v[162:165], v[186:189], v[58:61]
	v_mfma_f32_16x16x32_bf16 v[46:49], v[146:149], v[194:197], v[46:49]
	v_mfma_f32_16x16x32_bf16 v[42:45], v[162:165], v[194:197], v[42:45]
	v_mfma_f32_16x16x32_bf16 v[30:33], v[146:149], v[204:207], v[30:33]
	v_mfma_f32_16x16x32_bf16 v[26:29], v[162:165], v[204:207], v[26:29]
	v_mfma_f32_16x16x32_bf16 v[14:17], v[146:149], v[212:215], v[14:17]
	v_mfma_f32_16x16x32_bf16 v[10:13], v[162:165], v[212:215], v[10:13]
	v_mfma_f32_16x16x32_bf16 v[62:65], v[158:161], v[190:193], v[62:65]
	v_mfma_f32_16x16x32_bf16 v[58:61], v[166:169], v[190:193], v[58:61]
	v_lshl_add_u64 v[150:151], v[222:223], 0, s[8:9]
	s_mov_b32 m0, s83
	s_nop 0
	global_load_lds_dwordx4 v[150:151], off
	v_mfma_f32_16x16x32_bf16 v[46:49], v[158:161], v[200:203], v[46:49]
	v_mfma_f32_16x16x32_bf16 v[42:45], v[166:169], v[200:203], v[42:45]
	v_mfma_f32_16x16x32_bf16 v[30:33], v[158:161], v[208:211], v[30:33]
	v_mfma_f32_16x16x32_bf16 v[26:29], v[166:169], v[208:211], v[26:29]
	v_mfma_f32_16x16x32_bf16 v[14:17], v[158:161], v[216:219], v[14:17]
	v_mfma_f32_16x16x32_bf16 v[10:13], v[166:169], v[216:219], v[10:13]
	s_setprio 0
	s_setprio 1
	v_mfma_f32_16x16x32_bf16 v[54:57], v[170:173], v[186:189], v[54:57]
	v_mfma_f32_16x16x32_bf16 v[50:53], v[178:181], v[186:189], v[50:53]
	v_mfma_f32_16x16x32_bf16 v[38:41], v[170:173], v[194:197], v[38:41]
	v_mfma_f32_16x16x32_bf16 v[34:37], v[178:181], v[194:197], v[34:37]
	v_mfma_f32_16x16x32_bf16 v[22:25], v[170:173], v[204:207], v[22:25]
	v_mfma_f32_16x16x32_bf16 v[18:21], v[178:181], v[204:207], v[18:21]
	v_lshl_add_u64 v[150:151], v[224:225], 0, s[8:9]
	s_mov_b32 m0, s84
	s_nop 0
	global_load_lds_dwordx4 v[150:151], off
	v_mfma_f32_16x16x32_bf16 v[6:9], v[170:173], v[212:215], v[6:9]
	v_mfma_f32_16x16x32_bf16 v[2:5], v[178:181], v[212:215], v[2:5]
	v_mfma_f32_16x16x32_bf16 v[54:57], v[174:177], v[190:193], v[54:57]
	v_mfma_f32_16x16x32_bf16 v[50:53], v[182:185], v[190:193], v[50:53]
	v_mfma_f32_16x16x32_bf16 v[38:41], v[174:177], v[200:203], v[38:41]
	v_mfma_f32_16x16x32_bf16 v[34:37], v[182:185], v[200:203], v[34:37]
	v_mfma_f32_16x16x32_bf16 v[22:25], v[174:177], v[208:211], v[22:25]
	v_mfma_f32_16x16x32_bf16 v[18:21], v[182:185], v[208:211], v[18:21]
	v_mfma_f32_16x16x32_bf16 v[6:9], v[174:177], v[216:219], v[6:9]
	v_mfma_f32_16x16x32_bf16 v[2:5], v[182:185], v[216:219], v[2:5]
	s_setprio 0
	s_barrier
	s_add_i32 s97, s97, 2
	s_add_u32 s0, s0, 0x100
	s_addc_u32 s1, s1, 0
	s_add_u32 s95, s95, 0x100
	s_addc_u32 s96, s96, 0
	s_cmp_gt_u32 s97, 13
	s_cbranch_scc0 .LBB0_378
	s_and_b64 vcc, exec, s[36:37]
	s_cbranch_vccz .LBB0_381
	s_barrier

; #define PG8_STAGE(bufoff, gbase, voff) do { _Pragma("unroll") for (int _i = 0; _i < 2; ++_i) \
;         __builtin_amdgcn_global_load_lds((const unsigned*)((const char*)(gbase) + (voff)[_i]), (PG8_LAS unsigned*)(lds + (bufoff) + ldsw + _i * 8192), 16, 0, 0); } while (0)
; #define PG8_LDA(dst, b, h) do { _Pragma("unroll") for (int m = 0; m < 4; ++m) _Pragma("unroll") for (int k = 0; k < 2; ++k) dst[m][k] = *(const PG8_LAS bf16x8*)(lds + PG8_SA(b, h) + aoff + m * 2048 + k * 1024); } while (0)
; #define PG8_LDB(dst, b, h) do { _Pragma("unroll") for (int n = 0; n < 2; ++n) _Pragma("unroll") for (int k = 0; k < 2; ++k) dst[n][k] = *(const PG8_LAS bf16x8*)(lds + PG8_SB(b, h) + boff + n * 2048 + k * 1024); } while (0)
; #define PG8_MMA(ai, bj, At, Bt) do { __builtin_amdgcn_s_setprio(1); _Pragma("unroll") for (int m = 0; m < 4; ++m) _Pragma("unroll") for (int n = 0; n < 2; ++n) _Pragma("unroll") for (int k = 0; k < 2; ++k) \
;         acc[ai][bj][m][n] = __builtin_amdgcn_mfma_f32_16x16x32_bf16(Bt[n][k], At[m][k], acc[ai][bj][m][n], 0, 0, 0); __builtin_amdgcn_s_setprio(0); } while (0)
; #define PG8_WAIT_V(n) asm volatile("s_waitcnt vmcnt(" #n ")" ::: "memory")
; #define PG8_WAIT_L(n) asm volatile("s_waitcnt lgkmcnt(" #n ")" ::: "memory")
; #define PG8_BAR __builtin_amdgcn_s_barrier()
; #define PG8_SCHED __builtin_amdgcn_sched_barrier(0)
; template <class Epi, class Sched, bool ALIGN_EPI = false, bool SP2 = false>
; __device__ __forceinline__ void gemm_phase(PG8_LAS unsigned char* lds, const Gemm g, const Sched& S, const Epi& E) {
;     ...
;             const char* a1 = cA + (size_t)(t + 1) * kstep;
;             const char* a2 = last ? nA : cA + (size_t)(t + 2) * kstep; const char* b2 = last ? nB : cB + (size_t)(t + 2) * kstep;
;             const char* a3 = a2 + kstep; const char* b3 = b2 + kstep;
;             if (last && has_next) S.a_ready(nxt);
;             if constexpr (SP2) {
;             PG8_LDB(B0, 0, 0); PG8_LDB(B1, 0, 1); PG8_SCHED; PG8_LDA(At, 0, 0); PG8_STAGE(PG8_SA(1, 1), a1 + hstepA, voffA);
;             PG8_WAIT_V(8); PG8_WAIT_L(0); PG8_BAR; PG8_MMA(0, 0, At, B0); PG8_MMA(0, 1, At, B1); PG8_BAR; PG8_SCHED;
;             PG8_LDA(At, 0, 1); PG8_STAGE(PG8_SB(0, 0), b2, voffB); PG8_STAGE(PG8_SB(0, 1), b2 + hstepB, voffB); PG8_STAGE(PG8_SA(0, 0), a2, voffA);
.LBB0_480:
	ds_read_b128 v[162:165], v158
	ds_read_b128 v[166:169], v158 offset:1024
	ds_read_b128 v[170:173], v158 offset:2048
	ds_read_b128 v[174:177], v158 offset:3072
	ds_read_b128 v[178:181], v159
	ds_read_b128 v[182:185], v159 offset:1024
	ds_read_b128 v[186:189], v159 offset:2048
	ds_read_b128 v[190:193], v159 offset:3072
	s_add_u32 s12, s0, 0xfff00080
	s_addc_u32 s13, s1, -1
	s_cmp_eq_u32 s88, 60
	s_cselect_b32 s65, s43, s13
	s_cselect_b32 s64, s85, s12
	s_cselect_b32 s55, s45, s87
	s_cselect_b32 s54, s44, s86
	v_lshl_add_u64 v[146:147], s[0:1], 0, v[138:139]
	s_add_i32 m0, s53, 0xc000
	ds_read_b128 v[194:197], v160
	ds_read_b128 v[200:203], v160 offset:1024
	ds_read_b128 v[204:207], v160 offset:2048
	ds_read_b128 v[208:211], v160 offset:3072
	ds_read_b128 v[212:215], v160 offset:4096
	ds_read_b128 v[216:219], v160 offset:5120
	ds_read_b128 v[220:223], v160 offset:6144
	ds_read_b128 v[224:227], v160 offset:7168
	global_load_lds_dwordx4 v[146:147], off
	v_lshl_add_u64 v[146:147], s[0:1], 0, v[140:141]
	s_add_i32 m0, s53, 0xe000
	s_nop 0
	global_load_lds_dwordx4 v[146:147], off
	s_waitcnt vmcnt(8)
	s_waitcnt lgkmcnt(0)
	s_barrier
	s_setprio 1
	s_waitcnt lgkmcnt(0)
	v_mfma_f32_16x16x32_bf16 v[126:129], v[162:165], v[194:197], v[126:129]
	v_mfma_f32_16x16x32_bf16 v[122:125], v[170:173], v[194:197], v[122:125]
	v_mfma_f32_16x16x32_bf16 v[118:121], v[162:165], v[204:207], v[118:121]
	v_mfma_f32_16x16x32_bf16 v[110:113], v[170:173], v[204:207], v[110:113]
	v_mfma_f32_16x16x32_bf16 v[102:105], v[162:165], v[212:215], v[102:105]
	v_mfma_f32_16x16x32_bf16 v[94:97], v[170:173], v[212:215], v[94:97]
	v_mfma_f32_16x16x32_bf16 v[86:89], v[162:165], v[220:223], v[86:89]
	v_mfma_f32_16x16x32_bf16 v[78:81], v[170:173], v[220:223], v[78:81]
	v_mfma_f32_16x16x32_bf16 v[126:129], v[166:169], v[200:203], v[126:129]
	v_mfma_f32_16x16x32_bf16 v[122:125], v[174:177], v[200:203], v[122:125]
	v_mfma_f32_16x16x32_bf16 v[118:121], v[166:169], v[208:211], v[118:121]
	v_mfma_f32_16x16x32_bf16 v[110:113], v[174:177], v[208:211], v[110:113]
	v_mfma_f32_16x16x32_bf16 v[102:105], v[166:169], v[216:219], v[102:105]
	v_mfma_f32_16x16x32_bf16 v[94:97], v[174:177], v[216:219], v[94:97]
	v_mfma_f32_16x16x32_bf16 v[86:89], v[166:169], v[224:227], v[86:89]
	v_mfma_f32_16x16x32_bf16 v[78:81], v[174:177], v[224:227], v[78:81]
	s_setprio 0
	s_setprio 1
	v_mfma_f32_16x16x32_bf16 v[114:117], v[178:181], v[194:197], v[114:117]
	v_mfma_f32_16x16x32_bf16 v[106:109], v[186:189], v[194:197], v[106:109]
	v_mfma_f32_16x16x32_bf16 v[98:101], v[178:181], v[204:207], v[98:101]
	v_mfma_f32_16x16x32_bf16 v[90:93], v[186:189], v[204:207], v[90:93]
	v_mfma_f32_16x16x32_bf16 v[82:85], v[178:181], v[212:215], v[82:85]
	v_mfma_f32_16x16x32_bf16 v[74:77], v[186:189], v[212:215], v[74:77]
	v_mfma_f32_16x16x32_bf16 v[70:73], v[178:181], v[220:223], v[70:73]
	v_mfma_f32_16x16x32_bf16 v[66:69], v[186:189], v[220:223], v[66:69]
	v_mfma_f32_16x16x32_bf16 v[114:117], v[182:185], v[200:203], v[114:117]
	v_mfma_f32_16x16x32_bf16 v[106:109], v[190:193], v[200:203], v[106:109]
	v_mfma_f32_16x16x32_bf16 v[98:101], v[182:185], v[208:211], v[98:101]
	v_mfma_f32_16x16x32_bf16 v[90:93], v[190:193], v[208:211], v[90:93]
	v_mfma_f32_16x16x32_bf16 v[82:85], v[182:185], v[216:219], v[82:85]
	v_mfma_f32_16x16x32_bf16 v[74:77], v[190:193], v[216:219], v[74:77]
	v_mfma_f32_16x16x32_bf16 v[70:73], v[182:185], v[224:227], v[70:73]
	v_mfma_f32_16x16x32_bf16 v[66:69], v[190:193], v[224:227], v[66:69]
	s_setprio 0
	s_barrier
	s_add_i32 s12, s78, s69
	v_lshl_add_u64 v[146:147], s[54:55], 0, v[132:133]
	s_mov_b32 m0, s12
	ds_read_b128 v[194:197], v160 offset:16384
	ds_read_b128 v[200:203], v160 offset:17408
	ds_read_b128 v[204:207], v160 offset:18432
	ds_read_b128 v[208:211], v160 offset:19456
	ds_read_b128 v[212:215], v160 offset:20480
	ds_read_b128 v[216:219], v160 offset:21504
	ds_read_b128 v[220:223], v160 offset:22528
	ds_read_b128 v[224:227], v160 offset:23552
	global_load_lds_dwordx4 v[146:147], off
	s_add_i32 m0, s12, 0x2000
	s_add_u32 s12, s54, 0x100000
	v_lshl_add_u64 v[228:229], s[54:55], 0, v[136:137]
	s_addc_u32 s13, s55, 0
	s_add_i32 s33, s79, s69
	global_load_lds_dwordx4 v[228:229], off
	v_lshl_add_u64 v[230:231], s[12:13], 0, v[132:133]
	s_mov_b32 m0, s33
	v_lshl_add_u64 v[232:233], s[64:65], 0, v[134:135]
	global_load_lds_dwordx4 v[230:231], off
	v_lshl_add_u64 v[230:231], s[12:13], 0, v[136:137]
	s_add_i32 m0, s33, 0x2000
	s_nop 0
	global_load_lds_dwordx4 v[230:231], off
	s_waitcnt vmcnt(6)
	s_waitcnt lgkmcnt(0)
	s_barrier
; #define PG8_STAGE(bufoff, gbase, voff) do { _Pragma("unroll") for (int _i = 0; _i < 2; ++_i) \
;         __builtin_amdgcn_global_load_lds((const unsigned*)((const char*)(gbase) + (voff)[_i]), (PG8_LAS unsigned*)(lds + (bufoff) + ldsw + _i * 8192), 16, 0, 0); } while (0)
; #define PG8_LDA(dst, b, h) do { _Pragma("unroll") for (int m = 0; m < 4; ++m) _Pragma("unroll") for (int k = 0; k < 2; ++k) dst[m][k] = *(const PG8_LAS bf16x8*)(lds + PG8_SA(b, h) + aoff + m * 2048 + k * 1024); } while (0)
; #define PG8_LDB(dst, b, h) do { _Pragma("unroll") for (int n = 0; n < 2; ++n) _Pragma("unroll") for (int k = 0; k < 2; ++k) dst[n][k] = *(const PG8_LAS bf16x8*)(lds + PG8_SB(b, h) + boff + n * 2048 + k * 1024); } while (0)
; #define PG8_MMA(ai, bj, At, Bt) do { __builtin_amdgcn_s_setprio(1); _Pragma("unroll") for (int m = 0; m < 4; ++m) _Pragma("unroll") for (int n = 0; n < 2; ++n) _Pragma("unroll") for (int k = 0; k < 2; ++k) \
;         acc[ai][bj][m][n] = __builtin_amdgcn_mfma_f32_16x16x32_bf16(Bt[n][k], At[m][k], acc[ai][bj][m][n], 0, 0, 0); __builtin_amdgcn_s_setprio(0); } while (0)
; #define PG8_WAIT_V(n) asm volatile("s_waitcnt vmcnt(" #n ")" ::: "memory")
; #define PG8_WAIT_L(n) asm volatile("s_waitcnt lgkmcnt(" #n ")" ::: "memory")
; #define PG8_BAR __builtin_amdgcn_s_barrier()
; #define PG8_SCHED __builtin_amdgcn_sched_barrier(0)
; template <class Epi, class Sched, bool ALIGN_EPI = false, bool SP2 = false>
; __device__ __forceinline__ void gemm_phase(PG8_LAS unsigned char* lds, const Gemm g, const Sched& S, const Epi& E) {
;     ...
;             PG8_WAIT_V(8); PG8_WAIT_L(0); PG8_BAR; PG8_MMA(1, 0, At, B0); PG8_MMA(1, 1, At, B1); PG8_BAR; PG8_SCHED;
;             PG8_LDB(B0, 1, 0); PG8_LDB(B1, 1, 1); PG8_SCHED; PG8_LDA(At, 1, 0); PG8_STAGE(PG8_SA(0, 1), a2 + hstepA, voffA);
;             PG8_WAIT_V(8); PG8_WAIT_L(0); PG8_BAR; PG8_MMA(0, 0, At, B0); PG8_MMA(0, 1, At, B1); PG8_BAR; PG8_SCHED;
;             PG8_LDA(At, 1, 1); PG8_STAGE(PG8_SB(1, 0), b3, voffB); PG8_STAGE(PG8_SB(1, 1), b3 + hstepB, voffB); PG8_STAGE(PG8_SA(1, 0), a3, voffA);
	s_setprio 1
	s_waitcnt lgkmcnt(0)
	v_mfma_f32_16x16x32_bf16 v[62:65], v[162:165], v[194:197], v[62:65]
	v_mfma_f32_16x16x32_bf16 v[58:61], v[170:173], v[194:197], v[58:61]
	v_mfma_f32_16x16x32_bf16 v[54:57], v[162:165], v[204:207], v[54:57]
	v_mfma_f32_16x16x32_bf16 v[46:49], v[170:173], v[204:207], v[46:49]
	v_mfma_f32_16x16x32_bf16 v[38:41], v[162:165], v[212:215], v[38:41]
	v_mfma_f32_16x16x32_bf16 v[30:33], v[170:173], v[212:215], v[30:33]
	v_mfma_f32_16x16x32_bf16 v[22:25], v[162:165], v[220:223], v[22:25]
	v_mfma_f32_16x16x32_bf16 v[14:17], v[170:173], v[220:223], v[14:17]
	v_mfma_f32_16x16x32_bf16 v[62:65], v[166:169], v[200:203], v[62:65]
	v_mfma_f32_16x16x32_bf16 v[58:61], v[174:177], v[200:203], v[58:61]
	v_lshl_add_u64 v[230:231], s[64:65], 0, v[130:131]
	s_mov_b32 m0, s53
	s_nop 0
	global_load_lds_dwordx4 v[230:231], off
	v_mfma_f32_16x16x32_bf16 v[54:57], v[166:169], v[208:211], v[54:57]
	v_mfma_f32_16x16x32_bf16 v[46:49], v[174:177], v[208:211], v[46:49]
	v_mfma_f32_16x16x32_bf16 v[38:41], v[166:169], v[216:219], v[38:41]
	v_mfma_f32_16x16x32_bf16 v[30:33], v[174:177], v[216:219], v[30:33]
	v_mfma_f32_16x16x32_bf16 v[22:25], v[166:169], v[224:227], v[22:25]
	v_mfma_f32_16x16x32_bf16 v[14:17], v[174:177], v[224:227], v[14:17]
	s_setprio 0
	s_setprio 1
	v_mfma_f32_16x16x32_bf16 v[50:53], v[178:181], v[194:197], v[50:53]
	v_mfma_f32_16x16x32_bf16 v[42:45], v[186:189], v[194:197], v[42:45]
	v_mfma_f32_16x16x32_bf16 v[34:37], v[178:181], v[204:207], v[34:37]
	v_mfma_f32_16x16x32_bf16 v[26:29], v[186:189], v[204:207], v[26:29]
	v_mfma_f32_16x16x32_bf16 v[18:21], v[178:181], v[212:215], v[18:21]
	v_mfma_f32_16x16x32_bf16 v[10:13], v[186:189], v[212:215], v[10:13]
	s_mov_b32 m0, s70
	s_nop 0
	global_load_lds_dwordx4 v[232:233], off
	v_mfma_f32_16x16x32_bf16 v[6:9], v[178:181], v[220:223], v[6:9]
	v_mfma_f32_16x16x32_bf16 v[2:5], v[186:189], v[220:223], v[2:5]
	v_mfma_f32_16x16x32_bf16 v[50:53], v[182:185], v[200:203], v[50:53]
	v_mfma_f32_16x16x32_bf16 v[42:45], v[190:193], v[200:203], v[42:45]
	v_mfma_f32_16x16x32_bf16 v[34:37], v[182:185], v[208:211], v[34:37]
	v_mfma_f32_16x16x32_bf16 v[26:29], v[190:193], v[208:211], v[26:29]
	v_mfma_f32_16x16x32_bf16 v[18:21], v[182:185], v[216:219], v[18:21]
	v_mfma_f32_16x16x32_bf16 v[10:13], v[190:193], v[216:219], v[10:13]
	v_mfma_f32_16x16x32_bf16 v[6:9], v[182:185], v[224:227], v[6:9]
	v_mfma_f32_16x16x32_bf16 v[2:5], v[190:193], v[224:227], v[2:5]
	s_setprio 0
	s_barrier
	s_add_i32 s33, 0, 0x18000
	v_add_u32_e32 v161, s33, v156
	s_add_i32 s34, 0, 0x1c000
	ds_read_b128 v[162:165], v161
	ds_read_b128 v[166:169], v161 offset:1024
	ds_read_b128 v[170:173], v161 offset:2048
	ds_read_b128 v[174:177], v161 offset:3072
	v_add_u32_e32 v161, s34, v156
	ds_read_b128 v[178:181], v161
	ds_read_b128 v[182:185], v161 offset:1024
	ds_read_b128 v[186:189], v161 offset:2048
	ds_read_b128 v[190:193], v161 offset:3072
	s_add_u32 s12, s64, 0x100000
	s_addc_u32 s13, s65, 0
	s_mov_b32 m0, s71
	v_lshl_add_u64 v[234:235], s[12:13], 0, v[130:131]
	ds_read_b128 v[194:197], v160 offset:32768
	ds_read_b128 v[200:203], v160 offset:33792
	ds_read_b128 v[204:207], v160 offset:34816
	ds_read_b128 v[208:211], v160 offset:35840
	ds_read_b128 v[212:215], v160 offset:36864
	ds_read_b128 v[216:219], v160 offset:37888
	ds_read_b128 v[220:223], v160 offset:38912
	ds_read_b128 v[224:227], v160 offset:39936
	global_load_lds_dwordx4 v[234:235], off
	v_lshl_add_u64 v[234:235], s[12:13], 0, v[134:135]
	s_mov_b32 m0, s72
	s_nop 0
	global_load_lds_dwordx4 v[234:235], off
	s_waitcnt vmcnt(8)
	s_waitcnt lgkmcnt(0)
	s_barrier
	s_setprio 1
	s_waitcnt lgkmcnt(0)
	v_mfma_f32_16x16x32_bf16 v[126:129], v[162:165], v[194:197], v[126:129]
	v_mfma_f32_16x16x32_bf16 v[122:125], v[170:173], v[194:197], v[122:125]
	v_mfma_f32_16x16x32_bf16 v[118:121], v[162:165], v[204:207], v[118:121]
	v_mfma_f32_16x16x32_bf16 v[110:113], v[170:173], v[204:207], v[110:113]
	v_mfma_f32_16x16x32_bf16 v[102:105], v[162:165], v[212:215], v[102:105]
	v_mfma_f32_16x16x32_bf16 v[94:97], v[170:173], v[212:215], v[94:97]
	v_mfma_f32_16x16x32_bf16 v[86:89], v[162:165], v[220:223], v[86:89]
	v_mfma_f32_16x16x32_bf16 v[78:81], v[170:173], v[220:223], v[78:81]
	v_mfma_f32_16x16x32_bf16 v[126:129], v[166:169], v[200:203], v[126:129]
	v_mfma_f32_16x16x32_bf16 v[122:125], v[174:177], v[200:203], v[122:125]
	v_mfma_f32_16x16x32_bf16 v[118:121], v[166:169], v[208:211], v[118:121]
	v_mfma_f32_16x16x32_bf16 v[110:113], v[174:177], v[208:211], v[110:113]
	v_mfma_f32_16x16x32_bf16 v[102:105], v[166:169], v[216:219], v[102:105]
	v_mfma_f32_16x16x32_bf16 v[94:97], v[174:177], v[216:219], v[94:97]
	v_mfma_f32_16x16x32_bf16 v[86:89], v[166:169], v[224:227], v[86:89]
	v_mfma_f32_16x16x32_bf16 v[78:81], v[174:177], v[224:227], v[78:81]
	s_setprio 0
	s_setprio 1
	v_mfma_f32_16x16x32_bf16 v[114:117], v[178:181], v[194:197], v[114:117]
	v_mfma_f32_16x16x32_bf16 v[106:109], v[186:189], v[194:197], v[106:109]
	v_mfma_f32_16x16x32_bf16 v[98:101], v[178:181], v[204:207], v[98:101]
	v_mfma_f32_16x16x32_bf16 v[90:93], v[186:189], v[204:207], v[90:93]
	v_mfma_f32_16x16x32_bf16 v[82:85], v[178:181], v[212:215], v[82:85]
	v_mfma_f32_16x16x32_bf16 v[74:77], v[186:189], v[212:215], v[74:77]
	v_mfma_f32_16x16x32_bf16 v[70:73], v[178:181], v[220:223], v[70:73]
	v_mfma_f32_16x16x32_bf16 v[66:69], v[186:189], v[220:223], v[66:69]
	v_mfma_f32_16x16x32_bf16 v[114:117], v[182:185], v[200:203], v[114:117]
	v_mfma_f32_16x16x32_bf16 v[106:109], v[190:193], v[200:203], v[106:109]
	v_mfma_f32_16x16x32_bf16 v[98:101], v[182:185], v[208:211], v[98:101]
	v_mfma_f32_16x16x32_bf16 v[90:93], v[190:193], v[208:211], v[90:93]
	v_mfma_f32_16x16x32_bf16 v[82:85], v[182:185], v[216:219], v[82:85]
	v_mfma_f32_16x16x32_bf16 v[74:77], v[190:193], v[216:219], v[74:77]
	v_mfma_f32_16x16x32_bf16 v[70:73], v[182:185], v[224:227], v[70:73]
	v_mfma_f32_16x16x32_bf16 v[66:69], v[190:193], v[224:227], v[66:69]
	s_setprio 0
	s_barrier
; #define PG8_STAGE(bufoff, gbase, voff) do { _Pragma("unroll") for (int _i = 0; _i < 2; ++_i) \
;         __builtin_amdgcn_global_load_lds((const unsigned*)((const char*)(gbase) + (voff)[_i]), (PG8_LAS unsigned*)(lds + (bufoff) + ldsw + _i * 8192), 16, 0, 0); } while (0)
; #define PG8_LDA(dst, b, h) do { _Pragma("unroll") for (int m = 0; m < 4; ++m) _Pragma("unroll") for (int k = 0; k < 2; ++k) dst[m][k] = *(const PG8_LAS bf16x8*)(lds + PG8_SA(b, h) + aoff + m * 2048 + k * 1024); } while (0)
; #define PG8_MMA(ai, bj, At, Bt) do { __builtin_amdgcn_s_setprio(1); _Pragma("unroll") for (int m = 0; m < 4; ++m) _Pragma("unroll") for (int n = 0; n < 2; ++n) _Pragma("unroll") for (int k = 0; k < 2; ++k) \
;         acc[ai][bj][m][n] = __builtin_amdgcn_mfma_f32_16x16x32_bf16(Bt[n][k], At[m][k], acc[ai][bj][m][n], 0, 0, 0); __builtin_amdgcn_s_setprio(0); } while (0)
; #define PG8_WAIT_V(n) asm volatile("s_waitcnt vmcnt(" #n ")" ::: "memory")
; #define PG8_WAIT_L(n) asm volatile("s_waitcnt lgkmcnt(" #n ")" ::: "memory")
; #define PG8_BAR __builtin_amdgcn_s_barrier()
; #define PG8_SCHED __builtin_amdgcn_sched_barrier(0)
; template <class Epi, class Sched, bool ALIGN_EPI = false, bool SP2 = false>
; __device__ __forceinline__ void gemm_phase(PG8_LAS unsigned char* lds, const Gemm g, const Sched& S, const Epi& E) {
;     ...
;         for (int t = 0; t < nt; t += 2) {
;             const bool last = (t == nt - 2);
;             const char* a1 = cA + (size_t)(t + 1) * kstep;
;             const char* a2 = last ? nA : cA + (size_t)(t + 2) * kstep; const char* b2 = last ? nB : cB + (size_t)(t + 2) * kstep;
;     ...
;             PG8_LDA(At, 1, 1); PG8_STAGE(PG8_SB(1, 0), b3, voffB); PG8_STAGE(PG8_SB(1, 1), b3 + hstepB, voffB); PG8_STAGE(PG8_SA(1, 0), a3, voffA);
;             PG8_WAIT_V(8); PG8_WAIT_L(0); PG8_BAR; PG8_MMA(1, 0, At, B0); PG8_MMA(1, 1, At, B1); PG8_BAR; PG8_SCHED;
	s_add_i32 s12, s33, s69
	v_lshl_add_u64 v[146:147], v[146:147], 0, s[8:9]
	s_mov_b32 m0, s12
	ds_read_b128 v[194:197], v160 offset:49152
	ds_read_b128 v[200:203], v160 offset:50176
	ds_read_b128 v[204:207], v160 offset:51200
	ds_read_b128 v[208:211], v160 offset:52224
	ds_read_b128 v[212:215], v160 offset:53248
	ds_read_b128 v[216:219], v160 offset:54272
	ds_read_b128 v[220:223], v160 offset:55296
	ds_read_b128 v[224:227], v160 offset:56320
	global_load_lds_dwordx4 v[146:147], off
	s_add_i32 m0, s12, 0x2000
	s_add_u32 s12, s54, 0x100080
	v_lshl_add_u64 v[146:147], v[228:229], 0, s[8:9]
	s_addc_u32 s13, s55, 0
	s_add_i32 s33, s34, s69
	global_load_lds_dwordx4 v[146:147], off
	v_lshl_add_u64 v[146:147], s[12:13], 0, v[132:133]
	s_mov_b32 m0, s33
	s_nop 0
	global_load_lds_dwordx4 v[146:147], off
	v_lshl_add_u64 v[146:147], s[12:13], 0, v[136:137]
	s_add_i32 m0, s33, 0x2000
	s_nop 0
	global_load_lds_dwordx4 v[146:147], off
	s_waitcnt vmcnt(6)
	s_waitcnt lgkmcnt(0)
	s_barrier
	s_setprio 1
	s_waitcnt lgkmcnt(0)
	v_mfma_f32_16x16x32_bf16 v[62:65], v[162:165], v[194:197], v[62:65]
	v_mfma_f32_16x16x32_bf16 v[58:61], v[170:173], v[194:197], v[58:61]
	v_mfma_f32_16x16x32_bf16 v[54:57], v[162:165], v[204:207], v[54:57]
	v_mfma_f32_16x16x32_bf16 v[46:49], v[170:173], v[204:207], v[46:49]
	v_mfma_f32_16x16x32_bf16 v[38:41], v[162:165], v[212:215], v[38:41]
	v_mfma_f32_16x16x32_bf16 v[30:33], v[170:173], v[212:215], v[30:33]
	v_mfma_f32_16x16x32_bf16 v[22:25], v[162:165], v[220:223], v[22:25]
	v_mfma_f32_16x16x32_bf16 v[14:17], v[170:173], v[220:223], v[14:17]
	v_mfma_f32_16x16x32_bf16 v[62:65], v[166:169], v[200:203], v[62:65]
	v_mfma_f32_16x16x32_bf16 v[58:61], v[174:177], v[200:203], v[58:61]
	v_lshl_add_u64 v[146:147], v[230:231], 0, s[8:9]
	s_mov_b32 m0, s74
	s_nop 0
	global_load_lds_dwordx4 v[146:147], off
	v_mfma_f32_16x16x32_bf16 v[54:57], v[166:169], v[208:211], v[54:57]
	v_mfma_f32_16x16x32_bf16 v[46:49], v[174:177], v[208:211], v[46:49]
	v_mfma_f32_16x16x32_bf16 v[38:41], v[166:169], v[216:219], v[38:41]
	v_mfma_f32_16x16x32_bf16 v[30:33], v[174:177], v[216:219], v[30:33]
	v_mfma_f32_16x16x32_bf16 v[22:25], v[166:169], v[224:227], v[22:25]
	v_mfma_f32_16x16x32_bf16 v[14:17], v[174:177], v[224:227], v[14:17]
	s_setprio 0
	s_setprio 1
	v_mfma_f32_16x16x32_bf16 v[50:53], v[178:181], v[194:197], v[50:53]
	v_mfma_f32_16x16x32_bf16 v[42:45], v[186:189], v[194:197], v[42:45]
	v_mfma_f32_16x16x32_bf16 v[34:37], v[178:181], v[204:207], v[34:37]
	v_mfma_f32_16x16x32_bf16 v[26:29], v[186:189], v[204:207], v[26:29]
	v_mfma_f32_16x16x32_bf16 v[18:21], v[178:181], v[212:215], v[18:21]
	v_mfma_f32_16x16x32_bf16 v[10:13], v[186:189], v[212:215], v[10:13]
	v_lshl_add_u64 v[146:147], v[232:233], 0, s[8:9]
	s_mov_b32 m0, s75
	s_nop 0
	global_load_lds_dwordx4 v[146:147], off
	v_mfma_f32_16x16x32_bf16 v[6:9], v[178:181], v[220:223], v[6:9]
	v_mfma_f32_16x16x32_bf16 v[2:5], v[186:189], v[220:223], v[2:5]
	v_mfma_f32_16x16x32_bf16 v[50:53], v[182:185], v[200:203], v[50:53]
	v_mfma_f32_16x16x32_bf16 v[42:45], v[190:193], v[200:203], v[42:45]
	v_mfma_f32_16x16x32_bf16 v[34:37], v[182:185], v[208:211], v[34:37]
	v_mfma_f32_16x16x32_bf16 v[26:29], v[190:193], v[208:211], v[26:29]
	v_mfma_f32_16x16x32_bf16 v[18:21], v[182:185], v[216:219], v[18:21]
	v_mfma_f32_16x16x32_bf16 v[10:13], v[190:193], v[216:219], v[10:13]
	v_mfma_f32_16x16x32_bf16 v[6:9], v[182:185], v[224:227], v[6:9]
	v_mfma_f32_16x16x32_bf16 v[2:5], v[190:193], v[224:227], v[2:5]
	s_setprio 0
	s_barrier
	s_add_i32 s88, s88, 2
	s_add_u32 s0, s0, 0x100
	s_addc_u32 s1, s1, 0
	s_add_u32 s86, s86, 0x100
	s_addc_u32 s87, s87, 0
	s_cmp_gt_u32 s88, 61
	s_cbranch_scc0 .LBB0_480
	s_and_b64 vcc, exec, s[24:25]
	s_cbranch_vccz .LBB0_483
	s_barrier

; #define PG8_STAGE(bufoff, gbase, voff) do { _Pragma("unroll") for (int _i = 0; _i < 2; ++_i) \
;         __builtin_amdgcn_global_load_lds((const unsigned*)((const char*)(gbase) + (voff)[_i]), (PG8_LAS unsigned*)(lds + (bufoff) + ldsw + _i * 8192), 16, 0, 0); } while (0)
; #define PG8_LDA(dst, b, h) do { _Pragma("unroll") for (int m = 0; m < 4; ++m) _Pragma("unroll") for (int k = 0; k < 2; ++k) dst[m][k] = *(const PG8_LAS bf16x8*)(lds + PG8_SA(b, h) + aoff + m * 2048 + k * 1024); } while (0)
; #define PG8_LDB(dst, b, h) do { _Pragma("unroll") for (int n = 0; n < 2; ++n) _Pragma("unroll") for (int k = 0; k < 2; ++k) dst[n][k] = *(const PG8_LAS bf16x8*)(lds + PG8_SB(b, h) + boff + n * 2048 + k * 1024); } while (0)
; #define PG8_MMA(ai, bj, At, Bt) do { __builtin_amdgcn_s_setprio(1); _Pragma("unroll") for (int m = 0; m < 4; ++m) _Pragma("unroll") for (int n = 0; n < 2; ++n) _Pragma("unroll") for (int k = 0; k < 2; ++k) \
;         acc[ai][bj][m][n] = __builtin_amdgcn_mfma_f32_16x16x32_bf16(Bt[n][k], At[m][k], acc[ai][bj][m][n], 0, 0, 0); __builtin_amdgcn_s_setprio(0); } while (0)
; #define PG8_WAIT_V(n) asm volatile("s_waitcnt vmcnt(" #n ")" ::: "memory")
; #define PG8_WAIT_L(n) asm volatile("s_waitcnt lgkmcnt(" #n ")" ::: "memory")
; #define PG8_BAR __builtin_amdgcn_s_barrier()
; #define PG8_SCHED __builtin_amdgcn_sched_barrier(0)
; template <class Epi, class Sched, bool ALIGN_EPI = false, bool SP2 = false>
; __device__ __forceinline__ void gemm_phase(PG8_LAS unsigned char* lds, const Gemm g, const Sched& S, const Epi& E) {
;     ...
;             const char* a1 = cA + (size_t)(t + 1) * kstep;
;             const char* a2 = last ? nA : cA + (size_t)(t + 2) * kstep; const char* b2 = last ? nB : cB + (size_t)(t + 2) * kstep;
;             const char* a3 = a2 + kstep; const char* b3 = b2 + kstep;
;             if (last && has_next) S.a_ready(nxt);
;             if constexpr (SP2) {
;             PG8_LDB(B0, 0, 0); PG8_LDB(B1, 0, 1); PG8_SCHED; PG8_LDA(At, 0, 0); PG8_STAGE(PG8_SA(1, 1), a1 + hstepA, voffA);
;             PG8_WAIT_V(8); PG8_WAIT_L(0); PG8_BAR; PG8_MMA(0, 0, At, B0); PG8_MMA(0, 1, At, B1); PG8_BAR; PG8_SCHED;
;             PG8_LDA(At, 0, 1); PG8_STAGE(PG8_SB(0, 0), b2, voffB); PG8_STAGE(PG8_SB(0, 1), b2 + hstepB, voffB); PG8_STAGE(PG8_SA(0, 0), a2, voffA);
.LBB0_508:
	ds_read_b128 v[150:153], v1
	ds_read_b128 v[154:157], v1 offset:1024
	ds_read_b128 v[158:161], v1 offset:2048
	ds_read_b128 v[162:165], v1 offset:3072
	ds_read_b128 v[166:169], v147
	ds_read_b128 v[170:173], v147 offset:1024
	ds_read_b128 v[174:177], v147 offset:2048
	ds_read_b128 v[178:181], v147 offset:3072
	s_add_u32 s12, s52, 0xfff00080
	s_addc_u32 s13, s53, -1
	s_cmp_eq_u32 s87, 4
	s_cselect_b32 s65, s45, s13
	s_cselect_b32 s64, s44, s12
	s_cselect_b32 s55, s47, s43
	s_cselect_b32 s54, s46, s15
	v_lshl_add_u64 v[216:217], s[52:53], 0, v[140:141]
	s_add_i32 m0, s9, 0xc000
	ds_read_b128 v[182:185], v148
	ds_read_b128 v[186:189], v148 offset:1024
	ds_read_b128 v[190:193], v148 offset:2048
	ds_read_b128 v[194:197], v148 offset:3072
	ds_read_b128 v[200:203], v148 offset:4096
	ds_read_b128 v[204:207], v148 offset:5120
	ds_read_b128 v[208:211], v148 offset:6144
	ds_read_b128 v[212:215], v148 offset:7168
	global_load_lds_dwordx4 v[216:217], off
	v_lshl_add_u64 v[216:217], s[52:53], 0, v[142:143]
	s_add_i32 m0, s9, 0xe000
	s_nop 0
	global_load_lds_dwordx4 v[216:217], off
	s_waitcnt vmcnt(8)
	s_waitcnt lgkmcnt(0)
	s_barrier
	s_setprio 1
	s_waitcnt lgkmcnt(0)
	v_mfma_f32_16x16x32_bf16 v[126:129], v[150:153], v[182:185], v[126:129]
	v_mfma_f32_16x16x32_bf16 v[122:125], v[158:161], v[182:185], v[122:125]
	v_mfma_f32_16x16x32_bf16 v[118:121], v[150:153], v[190:193], v[118:121]
	v_mfma_f32_16x16x32_bf16 v[114:117], v[158:161], v[190:193], v[114:117]
	v_mfma_f32_16x16x32_bf16 v[106:109], v[150:153], v[200:203], v[106:109]
	v_mfma_f32_16x16x32_bf16 v[98:101], v[158:161], v[200:203], v[98:101]
	v_mfma_f32_16x16x32_bf16 v[90:93], v[150:153], v[208:211], v[90:93]
	v_mfma_f32_16x16x32_bf16 v[82:85], v[158:161], v[208:211], v[82:85]
	v_mfma_f32_16x16x32_bf16 v[126:129], v[154:157], v[186:189], v[126:129]
	v_mfma_f32_16x16x32_bf16 v[122:125], v[162:165], v[186:189], v[122:125]
	v_mfma_f32_16x16x32_bf16 v[118:121], v[154:157], v[194:197], v[118:121]
	v_mfma_f32_16x16x32_bf16 v[114:117], v[162:165], v[194:197], v[114:117]
	v_mfma_f32_16x16x32_bf16 v[106:109], v[154:157], v[204:207], v[106:109]
	v_mfma_f32_16x16x32_bf16 v[98:101], v[162:165], v[204:207], v[98:101]
	v_mfma_f32_16x16x32_bf16 v[90:93], v[154:157], v[212:215], v[90:93]
	v_mfma_f32_16x16x32_bf16 v[82:85], v[162:165], v[212:215], v[82:85]
	s_setprio 0
	s_setprio 1
	v_mfma_f32_16x16x32_bf16 v[110:113], v[166:169], v[182:185], v[110:113]
	v_mfma_f32_16x16x32_bf16 v[102:105], v[174:177], v[182:185], v[102:105]
	v_mfma_f32_16x16x32_bf16 v[94:97], v[166:169], v[190:193], v[94:97]
	v_mfma_f32_16x16x32_bf16 v[86:89], v[174:177], v[190:193], v[86:89]
	v_mfma_f32_16x16x32_bf16 v[78:81], v[166:169], v[200:203], v[78:81]
	v_mfma_f32_16x16x32_bf16 v[74:77], v[174:177], v[200:203], v[74:77]
	v_mfma_f32_16x16x32_bf16 v[70:73], v[166:169], v[208:211], v[70:73]
	v_mfma_f32_16x16x32_bf16 v[66:69], v[174:177], v[208:211], v[66:69]
	v_mfma_f32_16x16x32_bf16 v[110:113], v[170:173], v[186:189], v[110:113]
	v_mfma_f32_16x16x32_bf16 v[102:105], v[178:181], v[186:189], v[102:105]
	v_mfma_f32_16x16x32_bf16 v[94:97], v[170:173], v[194:197], v[94:97]
	v_mfma_f32_16x16x32_bf16 v[86:89], v[178:181], v[194:197], v[86:89]
	v_mfma_f32_16x16x32_bf16 v[78:81], v[170:173], v[204:207], v[78:81]
	v_mfma_f32_16x16x32_bf16 v[74:77], v[178:181], v[204:207], v[74:77]
	v_mfma_f32_16x16x32_bf16 v[70:73], v[170:173], v[212:215], v[70:73]
	v_mfma_f32_16x16x32_bf16 v[66:69], v[178:181], v[212:215], v[66:69]
	s_setprio 0
	s_barrier
	s_add_i32 s12, s80, s71
	v_lshl_add_u64 v[216:217], s[54:55], 0, v[132:133]
	s_mov_b32 m0, s12
	ds_read_b128 v[182:185], v148 offset:16384
	ds_read_b128 v[186:189], v148 offset:17408
	ds_read_b128 v[190:193], v148 offset:18432
	ds_read_b128 v[194:197], v148 offset:19456
	ds_read_b128 v[200:203], v148 offset:20480
	ds_read_b128 v[204:207], v148 offset:21504
	ds_read_b128 v[208:211], v148 offset:22528
	ds_read_b128 v[212:215], v148 offset:23552
	global_load_lds_dwordx4 v[216:217], off
	s_add_i32 m0, s12, 0x2000
	s_add_u32 s12, s54, 0x100000
	v_lshl_add_u64 v[218:219], s[54:55], 0, v[136:137]
	s_addc_u32 s13, s55, 0
	s_add_i32 s33, s81, s71
	global_load_lds_dwordx4 v[218:219], off
	v_lshl_add_u64 v[220:221], s[12:13], 0, v[132:133]
	s_mov_b32 m0, s33
	v_lshl_add_u64 v[222:223], s[64:65], 0, v[134:135]
	global_load_lds_dwordx4 v[220:221], off
	v_lshl_add_u64 v[220:221], s[12:13], 0, v[136:137]
	s_add_i32 m0, s33, 0x2000
	s_nop 0
	global_load_lds_dwordx4 v[220:221], off
	s_waitcnt vmcnt(6)
	s_waitcnt lgkmcnt(0)
	s_barrier
; #define PG8_STAGE(bufoff, gbase, voff) do { _Pragma("unroll") for (int _i = 0; _i < 2; ++_i) \
;         __builtin_amdgcn_global_load_lds((const unsigned*)((const char*)(gbase) + (voff)[_i]), (PG8_LAS unsigned*)(lds + (bufoff) + ldsw + _i * 8192), 16, 0, 0); } while (0)
; #define PG8_LDA(dst, b, h) do { _Pragma("unroll") for (int m = 0; m < 4; ++m) _Pragma("unroll") for (int k = 0; k < 2; ++k) dst[m][k] = *(const PG8_LAS bf16x8*)(lds + PG8_SA(b, h) + aoff + m * 2048 + k * 1024); } while (0)
; #define PG8_LDB(dst, b, h) do { _Pragma("unroll") for (int n = 0; n < 2; ++n) _Pragma("unroll") for (int k = 0; k < 2; ++k) dst[n][k] = *(const PG8_LAS bf16x8*)(lds + PG8_SB(b, h) + boff + n * 2048 + k * 1024); } while (0)
; #define PG8_MMA(ai, bj, At, Bt) do { __builtin_amdgcn_s_setprio(1); _Pragma("unroll") for (int m = 0; m < 4; ++m) _Pragma("unroll") for (int n = 0; n < 2; ++n) _Pragma("unroll") for (int k = 0; k < 2; ++k) \
;         acc[ai][bj][m][n] = __builtin_amdgcn_mfma_f32_16x16x32_bf16(Bt[n][k], At[m][k], acc[ai][bj][m][n], 0, 0, 0); __builtin_amdgcn_s_setprio(0); } while (0)
; #define PG8_WAIT_V(n) asm volatile("s_waitcnt vmcnt(" #n ")" ::: "memory")
; #define PG8_WAIT_L(n) asm volatile("s_waitcnt lgkmcnt(" #n ")" ::: "memory")
; #define PG8_BAR __builtin_amdgcn_s_barrier()
; #define PG8_SCHED __builtin_amdgcn_sched_barrier(0)
; template <class Epi, class Sched, bool ALIGN_EPI = false, bool SP2 = false>
; __device__ __forceinline__ void gemm_phase(PG8_LAS unsigned char* lds, const Gemm g, const Sched& S, const Epi& E) {
;     ...
;             PG8_WAIT_V(8); PG8_WAIT_L(0); PG8_BAR; PG8_MMA(1, 0, At, B0); PG8_MMA(1, 1, At, B1); PG8_BAR; PG8_SCHED;
;             PG8_LDB(B0, 1, 0); PG8_LDB(B1, 1, 1); PG8_SCHED; PG8_LDA(At, 1, 0); PG8_STAGE(PG8_SA(0, 1), a2 + hstepA, voffA);
;             PG8_WAIT_V(8); PG8_WAIT_L(0); PG8_BAR; PG8_MMA(0, 0, At, B0); PG8_MMA(0, 1, At, B1); PG8_BAR; PG8_SCHED;
;             PG8_LDA(At, 1, 1); PG8_STAGE(PG8_SB(1, 0), b3, voffB); PG8_STAGE(PG8_SB(1, 1), b3 + hstepB, voffB); PG8_STAGE(PG8_SA(1, 0), a3, voffA);
	s_setprio 1
	s_waitcnt lgkmcnt(0)
	v_mfma_f32_16x16x32_bf16 v[62:65], v[150:153], v[182:185], v[62:65]
	v_mfma_f32_16x16x32_bf16 v[58:61], v[158:161], v[182:185], v[58:61]
	v_mfma_f32_16x16x32_bf16 v[54:57], v[150:153], v[190:193], v[54:57]
	v_mfma_f32_16x16x32_bf16 v[50:53], v[158:161], v[190:193], v[50:53]
	v_mfma_f32_16x16x32_bf16 v[42:45], v[150:153], v[200:203], v[42:45]
	v_mfma_f32_16x16x32_bf16 v[34:37], v[158:161], v[200:203], v[34:37]
	v_mfma_f32_16x16x32_bf16 v[26:29], v[150:153], v[208:211], v[26:29]
	v_mfma_f32_16x16x32_bf16 v[18:21], v[158:161], v[208:211], v[18:21]
	v_mfma_f32_16x16x32_bf16 v[62:65], v[154:157], v[186:189], v[62:65]
	v_mfma_f32_16x16x32_bf16 v[58:61], v[162:165], v[186:189], v[58:61]
	v_lshl_add_u64 v[220:221], s[64:65], 0, v[130:131]
	s_mov_b32 m0, s9
	s_nop 0
	global_load_lds_dwordx4 v[220:221], off
	v_mfma_f32_16x16x32_bf16 v[54:57], v[154:157], v[194:197], v[54:57]
	v_mfma_f32_16x16x32_bf16 v[50:53], v[162:165], v[194:197], v[50:53]
	v_mfma_f32_16x16x32_bf16 v[42:45], v[154:157], v[204:207], v[42:45]
	v_mfma_f32_16x16x32_bf16 v[34:37], v[162:165], v[204:207], v[34:37]
	v_mfma_f32_16x16x32_bf16 v[26:29], v[154:157], v[212:215], v[26:29]
	v_mfma_f32_16x16x32_bf16 v[18:21], v[162:165], v[212:215], v[18:21]
	s_setprio 0
	s_setprio 1
	v_mfma_f32_16x16x32_bf16 v[46:49], v[166:169], v[182:185], v[46:49]
	v_mfma_f32_16x16x32_bf16 v[38:41], v[174:177], v[182:185], v[38:41]
	v_mfma_f32_16x16x32_bf16 v[30:33], v[166:169], v[190:193], v[30:33]
	v_mfma_f32_16x16x32_bf16 v[22:25], v[174:177], v[190:193], v[22:25]
	v_mfma_f32_16x16x32_bf16 v[14:17], v[166:169], v[200:203], v[14:17]
	v_mfma_f32_16x16x32_bf16 v[10:13], v[174:177], v[200:203], v[10:13]
	s_mov_b32 m0, s72
	s_nop 0
	global_load_lds_dwordx4 v[222:223], off
	v_mfma_f32_16x16x32_bf16 v[6:9], v[166:169], v[208:211], v[6:9]
	v_mfma_f32_16x16x32_bf16 v[2:5], v[174:177], v[208:211], v[2:5]
	v_mfma_f32_16x16x32_bf16 v[46:49], v[170:173], v[186:189], v[46:49]
	v_mfma_f32_16x16x32_bf16 v[38:41], v[178:181], v[186:189], v[38:41]
	v_mfma_f32_16x16x32_bf16 v[30:33], v[170:173], v[194:197], v[30:33]
	v_mfma_f32_16x16x32_bf16 v[22:25], v[178:181], v[194:197], v[22:25]
	v_mfma_f32_16x16x32_bf16 v[14:17], v[170:173], v[204:207], v[14:17]
	v_mfma_f32_16x16x32_bf16 v[10:13], v[178:181], v[204:207], v[10:13]
	v_mfma_f32_16x16x32_bf16 v[6:9], v[170:173], v[212:215], v[6:9]
	v_mfma_f32_16x16x32_bf16 v[2:5], v[178:181], v[212:215], v[2:5]
	s_setprio 0
	s_barrier
	s_add_i32 s33, 0, 0x18000
	v_add_u32_e32 v138, s33, v145
	s_add_i32 s34, 0, 0x1c000
	ds_read_b128 v[150:153], v138
	ds_read_b128 v[154:157], v138 offset:1024
	ds_read_b128 v[158:161], v138 offset:2048
	ds_read_b128 v[162:165], v138 offset:3072
	v_add_u32_e32 v138, s34, v145
	ds_read_b128 v[166:169], v138
	ds_read_b128 v[170:173], v138 offset:1024
	ds_read_b128 v[174:177], v138 offset:2048
	ds_read_b128 v[178:181], v138 offset:3072
	s_add_u32 s12, s64, 0x100000
	s_addc_u32 s13, s65, 0
	s_mov_b32 m0, s73
	v_lshl_add_u64 v[224:225], s[12:13], 0, v[130:131]
	ds_read_b128 v[182:185], v148 offset:32768
	ds_read_b128 v[186:189], v148 offset:33792
	ds_read_b128 v[190:193], v148 offset:34816
	ds_read_b128 v[194:197], v148 offset:35840
	ds_read_b128 v[200:203], v148 offset:36864
	ds_read_b128 v[204:207], v148 offset:37888
	ds_read_b128 v[208:211], v148 offset:38912
	ds_read_b128 v[212:215], v148 offset:39936
	global_load_lds_dwordx4 v[224:225], off
	v_lshl_add_u64 v[224:225], s[12:13], 0, v[134:135]
	s_mov_b32 m0, s74
	s_nop 0
	global_load_lds_dwordx4 v[224:225], off
	s_waitcnt vmcnt(8)
	s_waitcnt lgkmcnt(0)
	s_barrier
	s_setprio 1
	s_waitcnt lgkmcnt(0)
	v_mfma_f32_16x16x32_bf16 v[126:129], v[150:153], v[182:185], v[126:129]
	v_mfma_f32_16x16x32_bf16 v[122:125], v[158:161], v[182:185], v[122:125]
	v_mfma_f32_16x16x32_bf16 v[118:121], v[150:153], v[190:193], v[118:121]
	v_mfma_f32_16x16x32_bf16 v[114:117], v[158:161], v[190:193], v[114:117]
	v_mfma_f32_16x16x32_bf16 v[106:109], v[150:153], v[200:203], v[106:109]
	v_mfma_f32_16x16x32_bf16 v[98:101], v[158:161], v[200:203], v[98:101]
	v_mfma_f32_16x16x32_bf16 v[90:93], v[150:153], v[208:211], v[90:93]
	v_mfma_f32_16x16x32_bf16 v[82:85], v[158:161], v[208:211], v[82:85]
	v_mfma_f32_16x16x32_bf16 v[126:129], v[154:157], v[186:189], v[126:129]
	v_mfma_f32_16x16x32_bf16 v[122:125], v[162:165], v[186:189], v[122:125]
	v_mfma_f32_16x16x32_bf16 v[118:121], v[154:157], v[194:197], v[118:121]
	v_mfma_f32_16x16x32_bf16 v[114:117], v[162:165], v[194:197], v[114:117]
	v_mfma_f32_16x16x32_bf16 v[106:109], v[154:157], v[204:207], v[106:109]
	v_mfma_f32_16x16x32_bf16 v[98:101], v[162:165], v[204:207], v[98:101]
	v_mfma_f32_16x16x32_bf16 v[90:93], v[154:157], v[212:215], v[90:93]
	v_mfma_f32_16x16x32_bf16 v[82:85], v[162:165], v[212:215], v[82:85]
	s_setprio 0
	s_setprio 1
	v_mfma_f32_16x16x32_bf16 v[110:113], v[166:169], v[182:185], v[110:113]
	v_mfma_f32_16x16x32_bf16 v[102:105], v[174:177], v[182:185], v[102:105]
	v_mfma_f32_16x16x32_bf16 v[94:97], v[166:169], v[190:193], v[94:97]
	v_mfma_f32_16x16x32_bf16 v[86:89], v[174:177], v[190:193], v[86:89]
	v_mfma_f32_16x16x32_bf16 v[78:81], v[166:169], v[200:203], v[78:81]
	v_mfma_f32_16x16x32_bf16 v[74:77], v[174:177], v[200:203], v[74:77]
	v_mfma_f32_16x16x32_bf16 v[70:73], v[166:169], v[208:211], v[70:73]
	v_mfma_f32_16x16x32_bf16 v[66:69], v[174:177], v[208:211], v[66:69]
	v_mfma_f32_16x16x32_bf16 v[110:113], v[170:173], v[186:189], v[110:113]
	v_mfma_f32_16x16x32_bf16 v[102:105], v[178:181], v[186:189], v[102:105]
	v_mfma_f32_16x16x32_bf16 v[94:97], v[170:173], v[194:197], v[94:97]
	v_mfma_f32_16x16x32_bf16 v[86:89], v[178:181], v[194:197], v[86:89]
	v_mfma_f32_16x16x32_bf16 v[78:81], v[170:173], v[204:207], v[78:81]
	v_mfma_f32_16x16x32_bf16 v[74:77], v[178:181], v[204:207], v[74:77]
	v_mfma_f32_16x16x32_bf16 v[70:73], v[170:173], v[212:215], v[70:73]
	v_mfma_f32_16x16x32_bf16 v[66:69], v[178:181], v[212:215], v[66:69]
	s_setprio 0
	s_barrier
; #define PG8_STAGE(bufoff, gbase, voff) do { _Pragma("unroll") for (int _i = 0; _i < 2; ++_i) \
;         __builtin_amdgcn_global_load_lds((const unsigned*)((const char*)(gbase) + (voff)[_i]), (PG8_LAS unsigned*)(lds + (bufoff) + ldsw + _i * 8192), 16, 0, 0); } while (0)
; #define PG8_LDA(dst, b, h) do { _Pragma("unroll") for (int m = 0; m < 4; ++m) _Pragma("unroll") for (int k = 0; k < 2; ++k) dst[m][k] = *(const PG8_LAS bf16x8*)(lds + PG8_SA(b, h) + aoff + m * 2048 + k * 1024); } while (0)
; #define PG8_MMA(ai, bj, At, Bt) do { __builtin_amdgcn_s_setprio(1); _Pragma("unroll") for (int m = 0; m < 4; ++m) _Pragma("unroll") for (int n = 0; n < 2; ++n) _Pragma("unroll") for (int k = 0; k < 2; ++k) \
;         acc[ai][bj][m][n] = __builtin_amdgcn_mfma_f32_16x16x32_bf16(Bt[n][k], At[m][k], acc[ai][bj][m][n], 0, 0, 0); __builtin_amdgcn_s_setprio(0); } while (0)
; #define PG8_WAIT_V(n) asm volatile("s_waitcnt vmcnt(" #n ")" ::: "memory")
; #define PG8_WAIT_L(n) asm volatile("s_waitcnt lgkmcnt(" #n ")" ::: "memory")
; #define PG8_BAR __builtin_amdgcn_s_barrier()
; #define PG8_SCHED __builtin_amdgcn_sched_barrier(0)
; template <class Epi, class Sched, bool ALIGN_EPI = false, bool SP2 = false>
; __device__ __forceinline__ void gemm_phase(PG8_LAS unsigned char* lds, const Gemm g, const Sched& S, const Epi& E) {
;     ...
;         for (int t = 0; t < nt; t += 2) {
;             const bool last = (t == nt - 2);
;             const char* a1 = cA + (size_t)(t + 1) * kstep;
;             const char* a2 = last ? nA : cA + (size_t)(t + 2) * kstep; const char* b2 = last ? nB : cB + (size_t)(t + 2) * kstep;
;     ...
;             PG8_LDA(At, 1, 1); PG8_STAGE(PG8_SB(1, 0), b3, voffB); PG8_STAGE(PG8_SB(1, 1), b3 + hstepB, voffB); PG8_STAGE(PG8_SA(1, 0), a3, voffA);
;             PG8_WAIT_V(8); PG8_WAIT_L(0); PG8_BAR; PG8_MMA(1, 0, At, B0); PG8_MMA(1, 1, At, B1); PG8_BAR; PG8_SCHED;
	s_add_i32 s12, s33, s71
	v_lshl_add_u64 v[216:217], v[216:217], 0, s[6:7]
	s_mov_b32 m0, s12
	ds_read_b128 v[182:185], v148 offset:49152
	ds_read_b128 v[186:189], v148 offset:50176
	ds_read_b128 v[190:193], v148 offset:51200
	ds_read_b128 v[194:197], v148 offset:52224
	ds_read_b128 v[200:203], v148 offset:53248
	ds_read_b128 v[204:207], v148 offset:54272
	ds_read_b128 v[208:211], v148 offset:55296
	ds_read_b128 v[212:215], v148 offset:56320
	global_load_lds_dwordx4 v[216:217], off
	s_add_i32 m0, s12, 0x2000
	s_add_u32 s12, s54, 0x100080
	v_lshl_add_u64 v[216:217], v[218:219], 0, s[6:7]
	s_addc_u32 s13, s55, 0
	s_add_i32 s33, s34, s71
	global_load_lds_dwordx4 v[216:217], off
	v_lshl_add_u64 v[216:217], s[12:13], 0, v[132:133]
	s_mov_b32 m0, s33
	s_nop 0
	global_load_lds_dwordx4 v[216:217], off
	v_lshl_add_u64 v[216:217], s[12:13], 0, v[136:137]
	s_add_i32 m0, s33, 0x2000
	s_nop 0
	global_load_lds_dwordx4 v[216:217], off
	s_waitcnt vmcnt(6)
	s_waitcnt lgkmcnt(0)
	s_barrier
	s_setprio 1
	s_waitcnt lgkmcnt(0)
	v_mfma_f32_16x16x32_bf16 v[62:65], v[150:153], v[182:185], v[62:65]
	v_mfma_f32_16x16x32_bf16 v[58:61], v[158:161], v[182:185], v[58:61]
	v_mfma_f32_16x16x32_bf16 v[54:57], v[150:153], v[190:193], v[54:57]
	v_mfma_f32_16x16x32_bf16 v[50:53], v[158:161], v[190:193], v[50:53]
	v_mfma_f32_16x16x32_bf16 v[42:45], v[150:153], v[200:203], v[42:45]
	v_mfma_f32_16x16x32_bf16 v[34:37], v[158:161], v[200:203], v[34:37]
	v_mfma_f32_16x16x32_bf16 v[26:29], v[150:153], v[208:211], v[26:29]
	v_mfma_f32_16x16x32_bf16 v[18:21], v[158:161], v[208:211], v[18:21]
	v_mfma_f32_16x16x32_bf16 v[62:65], v[154:157], v[186:189], v[62:65]
	v_mfma_f32_16x16x32_bf16 v[58:61], v[162:165], v[186:189], v[58:61]
	v_lshl_add_u64 v[216:217], v[220:221], 0, s[6:7]
	s_mov_b32 m0, s76
	s_nop 0
	global_load_lds_dwordx4 v[216:217], off
	v_mfma_f32_16x16x32_bf16 v[54:57], v[154:157], v[194:197], v[54:57]
	v_mfma_f32_16x16x32_bf16 v[50:53], v[162:165], v[194:197], v[50:53]
	v_mfma_f32_16x16x32_bf16 v[42:45], v[154:157], v[204:207], v[42:45]
	v_mfma_f32_16x16x32_bf16 v[34:37], v[162:165], v[204:207], v[34:37]
	v_mfma_f32_16x16x32_bf16 v[26:29], v[154:157], v[212:215], v[26:29]
	v_mfma_f32_16x16x32_bf16 v[18:21], v[162:165], v[212:215], v[18:21]
	s_setprio 0
	s_setprio 1
	v_mfma_f32_16x16x32_bf16 v[46:49], v[166:169], v[182:185], v[46:49]
	v_mfma_f32_16x16x32_bf16 v[38:41], v[174:177], v[182:185], v[38:41]
	v_mfma_f32_16x16x32_bf16 v[30:33], v[166:169], v[190:193], v[30:33]
	v_mfma_f32_16x16x32_bf16 v[22:25], v[174:177], v[190:193], v[22:25]
	v_mfma_f32_16x16x32_bf16 v[14:17], v[166:169], v[200:203], v[14:17]
	v_mfma_f32_16x16x32_bf16 v[10:13], v[174:177], v[200:203], v[10:13]
	v_lshl_add_u64 v[216:217], v[222:223], 0, s[6:7]
	s_mov_b32 m0, s77
	s_nop 0
	global_load_lds_dwordx4 v[216:217], off
	v_mfma_f32_16x16x32_bf16 v[6:9], v[166:169], v[208:211], v[6:9]
	v_mfma_f32_16x16x32_bf16 v[2:5], v[174:177], v[208:211], v[2:5]
	v_mfma_f32_16x16x32_bf16 v[46:49], v[170:173], v[186:189], v[46:49]
	v_mfma_f32_16x16x32_bf16 v[38:41], v[178:181], v[186:189], v[38:41]
	v_mfma_f32_16x16x32_bf16 v[30:33], v[170:173], v[194:197], v[30:33]
	v_mfma_f32_16x16x32_bf16 v[22:25], v[178:181], v[194:197], v[22:25]
	v_mfma_f32_16x16x32_bf16 v[14:17], v[170:173], v[204:207], v[14:17]
	v_mfma_f32_16x16x32_bf16 v[10:13], v[178:181], v[204:207], v[10:13]
	v_mfma_f32_16x16x32_bf16 v[6:9], v[170:173], v[212:215], v[6:9]
	v_mfma_f32_16x16x32_bf16 v[2:5], v[178:181], v[212:215], v[2:5]
	s_setprio 0
	s_barrier
	s_add_i32 s87, s87, 2
	s_add_u32 s52, s52, 0x100
	s_addc_u32 s53, s53, 0
	s_add_u32 s15, s15, 0x100
	s_addc_u32 s43, s43, 0
	s_cmp_gt_u32 s87, 5
	s_cbranch_scc0 .LBB0_508
	s_and_b64 vcc, exec, s[24:25]
	s_cbranch_vccz .LBB0_511
	s_barrier

; #define PG8_STAGE(bufoff, gbase, voff) do { _Pragma("unroll") for (int _i = 0; _i < 2; ++_i) \
;         __builtin_amdgcn_global_load_lds((const unsigned*)((const char*)(gbase) + (voff)[_i]), (PG8_LAS unsigned*)(lds + (bufoff) + ldsw + _i * 8192), 16, 0, 0); } while (0)
; #define PG8_LDA(dst, b, h) do { _Pragma("unroll") for (int m = 0; m < 4; ++m) _Pragma("unroll") for (int k = 0; k < 2; ++k) dst[m][k] = *(const PG8_LAS bf16x8*)(lds + PG8_SA(b, h) + aoff + m * 2048 + k * 1024); } while (0)
; #define PG8_LDB(dst, b, h) do { _Pragma("unroll") for (int n = 0; n < 2; ++n) _Pragma("unroll") for (int k = 0; k < 2; ++k) dst[n][k] = *(const PG8_LAS bf16x8*)(lds + PG8_SB(b, h) + boff + n * 2048 + k * 1024); } while (0)
; #define PG8_MMA(ai, bj, At, Bt) do { __builtin_amdgcn_s_setprio(1); _Pragma("unroll") for (int m = 0; m < 4; ++m) _Pragma("unroll") for (int n = 0; n < 2; ++n) _Pragma("unroll") for (int k = 0; k < 2; ++k) \
;         acc[ai][bj][m][n] = __builtin_amdgcn_mfma_f32_16x16x32_bf16(Bt[n][k], At[m][k], acc[ai][bj][m][n], 0, 0, 0); __builtin_amdgcn_s_setprio(0); } while (0)
; #define PG8_WAIT_V(n) asm volatile("s_waitcnt vmcnt(" #n ")" ::: "memory")
; #define PG8_WAIT_L(n) asm volatile("s_waitcnt lgkmcnt(" #n ")" ::: "memory")
; #define PG8_BAR __builtin_amdgcn_s_barrier()
; #define PG8_SCHED __builtin_amdgcn_sched_barrier(0)
; template <class Epi, class Sched, bool ALIGN_EPI = false, bool SP2 = false>
; __device__ __forceinline__ void gemm_phase(PG8_LAS unsigned char* lds, const Gemm g, const Sched& S, const Epi& E) {
;     ...
;             const char* a1 = cA + (size_t)(t + 1) * kstep;
;             const char* a2 = last ? nA : cA + (size_t)(t + 2) * kstep; const char* b2 = last ? nB : cB + (size_t)(t + 2) * kstep;
;             const char* a3 = a2 + kstep; const char* b3 = b2 + kstep;
;             if (last && has_next) S.a_ready(nxt);
;             if constexpr (SP2) {
;             PG8_LDB(B0, 0, 0); PG8_LDB(B1, 0, 1); PG8_SCHED; PG8_LDA(At, 0, 0); PG8_STAGE(PG8_SA(1, 1), a1 + hstepA, voffA);
;             PG8_WAIT_V(8); PG8_WAIT_L(0); PG8_BAR; PG8_MMA(0, 0, At, B0); PG8_MMA(0, 1, At, B1); PG8_BAR; PG8_SCHED;
;             PG8_LDA(At, 0, 1); PG8_STAGE(PG8_SB(0, 0), b2, voffB); PG8_STAGE(PG8_SB(0, 1), b2 + hstepB, voffB); PG8_STAGE(PG8_SA(0, 0), a2, voffA);
.LBB0_688:
	ds_read_b128 v[114:117], v210
	ds_read_b128 v[118:121], v210 offset:1024
	ds_read_b128 v[122:125], v210 offset:2048
	ds_read_b128 v[126:129], v210 offset:3072
	ds_read_b128 v[146:149], v211
	ds_read_b128 v[150:153], v211 offset:1024
	ds_read_b128 v[154:157], v211 offset:2048
	ds_read_b128 v[180:183], v211 offset:3072
	s_add_u32 s10, s0, 0xfffc0080
	s_addc_u32 s11, s1, -1
	s_cmp_eq_u32 s49, 12
	s_cselect_b32 s47, s9, s11
	s_cselect_b32 s46, s15, s10
	s_cselect_b32 s11, s43, s48
	s_cselect_b32 s10, s42, s41
	v_lshl_add_u64 v[158:159], s[0:1], 0, v[174:175]
	s_add_i32 m0, s55, 0xc000
	ds_read_b128 v[184:187], v212
	ds_read_b128 v[218:221], v212 offset:1024
	ds_read_b128 v[222:225], v212 offset:2048
	ds_read_b128 v[226:229], v212 offset:3072
	ds_read_b128 v[230:233], v212 offset:4096
	ds_read_b128 v[234:237], v212 offset:5120
	ds_read_b128 v[238:241], v212 offset:6144
	ds_read_b128 v[242:245], v212 offset:7168
	global_load_lds_dwordx4 v[158:159], off
	v_lshl_add_u64 v[158:159], s[0:1], 0, v[176:177]
	s_add_i32 m0, s55, 0xe000
	s_nop 0
	global_load_lds_dwordx4 v[158:159], off
	s_waitcnt vmcnt(8)
	s_waitcnt lgkmcnt(0)
	s_barrier
	s_setprio 1
	s_waitcnt lgkmcnt(0)
	v_mfma_f32_16x16x32_bf16 v[142:145], v[114:117], v[184:187], v[142:145]
	v_mfma_f32_16x16x32_bf16 v[138:141], v[122:125], v[184:187], v[138:141]
	v_mfma_f32_16x16x32_bf16 v[110:113], v[114:117], v[222:225], v[110:113]
	v_mfma_f32_16x16x32_bf16 v[106:109], v[122:125], v[222:225], v[106:109]
	v_mfma_f32_16x16x32_bf16 v[94:97], v[114:117], v[230:233], v[94:97]
	v_mfma_f32_16x16x32_bf16 v[90:93], v[122:125], v[230:233], v[90:93]
	v_mfma_f32_16x16x32_bf16 v[78:81], v[114:117], v[238:241], v[78:81]
	v_mfma_f32_16x16x32_bf16 v[74:77], v[122:125], v[238:241], v[74:77]
	v_mfma_f32_16x16x32_bf16 v[142:145], v[118:121], v[218:221], v[142:145]
	v_mfma_f32_16x16x32_bf16 v[138:141], v[126:129], v[218:221], v[138:141]
	v_mfma_f32_16x16x32_bf16 v[110:113], v[118:121], v[226:229], v[110:113]
	v_mfma_f32_16x16x32_bf16 v[106:109], v[126:129], v[226:229], v[106:109]
	v_mfma_f32_16x16x32_bf16 v[94:97], v[118:121], v[234:237], v[94:97]
	v_mfma_f32_16x16x32_bf16 v[90:93], v[126:129], v[234:237], v[90:93]
	v_mfma_f32_16x16x32_bf16 v[78:81], v[118:121], v[242:245], v[78:81]
	v_mfma_f32_16x16x32_bf16 v[74:77], v[126:129], v[242:245], v[74:77]
	s_setprio 0
	s_setprio 1
	v_mfma_f32_16x16x32_bf16 v[134:137], v[146:149], v[184:187], v[134:137]
	v_mfma_f32_16x16x32_bf16 v[130:133], v[154:157], v[184:187], v[130:133]
	v_mfma_f32_16x16x32_bf16 v[102:105], v[146:149], v[222:225], v[102:105]
	v_mfma_f32_16x16x32_bf16 v[98:101], v[154:157], v[222:225], v[98:101]
	v_mfma_f32_16x16x32_bf16 v[86:89], v[146:149], v[230:233], v[86:89]
	v_mfma_f32_16x16x32_bf16 v[82:85], v[154:157], v[230:233], v[82:85]
	v_mfma_f32_16x16x32_bf16 v[70:73], v[146:149], v[238:241], v[70:73]
	v_mfma_f32_16x16x32_bf16 v[66:69], v[154:157], v[238:241], v[66:69]
	v_mfma_f32_16x16x32_bf16 v[134:137], v[150:153], v[218:221], v[134:137]
	v_mfma_f32_16x16x32_bf16 v[130:133], v[180:183], v[218:221], v[130:133]
	v_mfma_f32_16x16x32_bf16 v[102:105], v[150:153], v[226:229], v[102:105]
	v_mfma_f32_16x16x32_bf16 v[98:101], v[180:183], v[226:229], v[98:101]
	v_mfma_f32_16x16x32_bf16 v[86:89], v[150:153], v[234:237], v[86:89]
	v_mfma_f32_16x16x32_bf16 v[82:85], v[180:183], v[234:237], v[82:85]
	v_mfma_f32_16x16x32_bf16 v[70:73], v[150:153], v[242:245], v[70:73]
	v_mfma_f32_16x16x32_bf16 v[66:69], v[180:183], v[242:245], v[66:69]
	s_setprio 0
	s_barrier
	s_add_i32 s12, s74, s54
	v_lshl_add_u64 v[158:159], s[10:11], 0, v[162:163]
	s_mov_b32 m0, s12
	ds_read_b128 v[184:187], v212 offset:16384
	ds_read_b128 v[218:221], v212 offset:17408
	ds_read_b128 v[222:225], v212 offset:18432
	ds_read_b128 v[226:229], v212 offset:19456
	ds_read_b128 v[230:233], v212 offset:20480
	ds_read_b128 v[234:237], v212 offset:21504
	ds_read_b128 v[238:241], v212 offset:22528
	ds_read_b128 v[242:245], v212 offset:23552
	global_load_lds_dwordx4 v[158:159], off
	s_add_i32 m0, s12, 0x2000
	s_add_u32 s12, s10, 0x2000
	v_lshl_add_u64 v[246:247], s[10:11], 0, v[166:167]
	s_addc_u32 s13, s11, 0
	s_add_i32 s33, s75, s54
	global_load_lds_dwordx4 v[246:247], off
	v_lshl_add_u64 v[248:249], s[12:13], 0, v[162:163]
	s_mov_b32 m0, s33
	v_lshl_add_u64 v[250:251], s[46:47], 0, v[164:165]
	global_load_lds_dwordx4 v[248:249], off
	v_lshl_add_u64 v[248:249], s[12:13], 0, v[166:167]
	s_add_i32 m0, s33, 0x2000
	s_nop 0
	global_load_lds_dwordx4 v[248:249], off
	s_waitcnt vmcnt(6)
	s_waitcnt lgkmcnt(0)
	s_barrier
; #define PG8_STAGE(bufoff, gbase, voff) do { _Pragma("unroll") for (int _i = 0; _i < 2; ++_i) \
;         __builtin_amdgcn_global_load_lds((const unsigned*)((const char*)(gbase) + (voff)[_i]), (PG8_LAS unsigned*)(lds + (bufoff) + ldsw + _i * 8192), 16, 0, 0); } while (0)
; #define PG8_LDA(dst, b, h) do { _Pragma("unroll") for (int m = 0; m < 4; ++m) _Pragma("unroll") for (int k = 0; k < 2; ++k) dst[m][k] = *(const PG8_LAS bf16x8*)(lds + PG8_SA(b, h) + aoff + m * 2048 + k * 1024); } while (0)
; #define PG8_LDB(dst, b, h) do { _Pragma("unroll") for (int n = 0; n < 2; ++n) _Pragma("unroll") for (int k = 0; k < 2; ++k) dst[n][k] = *(const PG8_LAS bf16x8*)(lds + PG8_SB(b, h) + boff + n * 2048 + k * 1024); } while (0)
; #define PG8_MMA(ai, bj, At, Bt) do { __builtin_amdgcn_s_setprio(1); _Pragma("unroll") for (int m = 0; m < 4; ++m) _Pragma("unroll") for (int n = 0; n < 2; ++n) _Pragma("unroll") for (int k = 0; k < 2; ++k) \
;         acc[ai][bj][m][n] = __builtin_amdgcn_mfma_f32_16x16x32_bf16(Bt[n][k], At[m][k], acc[ai][bj][m][n], 0, 0, 0); __builtin_amdgcn_s_setprio(0); } while (0)
; #define PG8_WAIT_V(n) asm volatile("s_waitcnt vmcnt(" #n ")" ::: "memory")
; #define PG8_WAIT_L(n) asm volatile("s_waitcnt lgkmcnt(" #n ")" ::: "memory")
; #define PG8_BAR __builtin_amdgcn_s_barrier()
; #define PG8_SCHED __builtin_amdgcn_sched_barrier(0)
; template <class Epi, class Sched, bool ALIGN_EPI = false, bool SP2 = false>
; __device__ __forceinline__ void gemm_phase(PG8_LAS unsigned char* lds, const Gemm g, const Sched& S, const Epi& E) {
;     ...
;             PG8_WAIT_V(8); PG8_WAIT_L(0); PG8_BAR; PG8_MMA(1, 0, At, B0); PG8_MMA(1, 1, At, B1); PG8_BAR; PG8_SCHED;
;             PG8_LDB(B0, 1, 0); PG8_LDB(B1, 1, 1); PG8_SCHED; PG8_LDA(At, 1, 0); PG8_STAGE(PG8_SA(0, 1), a2 + hstepA, voffA);
;             PG8_WAIT_V(8); PG8_WAIT_L(0); PG8_BAR; PG8_MMA(0, 0, At, B0); PG8_MMA(0, 1, At, B1); PG8_BAR; PG8_SCHED;
;             PG8_LDA(At, 1, 1); PG8_STAGE(PG8_SB(1, 0), b3, voffB); PG8_STAGE(PG8_SB(1, 1), b3 + hstepB, voffB); PG8_STAGE(PG8_SA(1, 0), a3, voffA);
	s_setprio 1
	s_waitcnt lgkmcnt(0)
	v_mfma_f32_16x16x32_bf16 v[62:65], v[114:117], v[184:187], v[62:65]
	v_mfma_f32_16x16x32_bf16 v[58:61], v[122:125], v[184:187], v[58:61]
	v_mfma_f32_16x16x32_bf16 v[46:49], v[114:117], v[222:225], v[46:49]
	v_mfma_f32_16x16x32_bf16 v[42:45], v[122:125], v[222:225], v[42:45]
	v_mfma_f32_16x16x32_bf16 v[30:33], v[114:117], v[230:233], v[30:33]
	v_mfma_f32_16x16x32_bf16 v[26:29], v[122:125], v[230:233], v[26:29]
	v_mfma_f32_16x16x32_bf16 v[14:17], v[114:117], v[238:241], v[14:17]
	v_mfma_f32_16x16x32_bf16 v[10:13], v[122:125], v[238:241], v[10:13]
	v_mfma_f32_16x16x32_bf16 v[62:65], v[118:121], v[218:221], v[62:65]
	v_mfma_f32_16x16x32_bf16 v[58:61], v[126:129], v[218:221], v[58:61]
	v_lshl_add_u64 v[248:249], s[46:47], 0, v[160:161]
	s_mov_b32 m0, s55
	s_nop 0
	global_load_lds_dwordx4 v[248:249], off
	v_mfma_f32_16x16x32_bf16 v[46:49], v[118:121], v[226:229], v[46:49]
	v_mfma_f32_16x16x32_bf16 v[42:45], v[126:129], v[226:229], v[42:45]
	v_mfma_f32_16x16x32_bf16 v[30:33], v[118:121], v[234:237], v[30:33]
	v_mfma_f32_16x16x32_bf16 v[26:29], v[126:129], v[234:237], v[26:29]
	v_mfma_f32_16x16x32_bf16 v[14:17], v[118:121], v[242:245], v[14:17]
	v_mfma_f32_16x16x32_bf16 v[10:13], v[126:129], v[242:245], v[10:13]
	s_setprio 0
	s_setprio 1
	v_mfma_f32_16x16x32_bf16 v[54:57], v[146:149], v[184:187], v[54:57]
	v_mfma_f32_16x16x32_bf16 v[50:53], v[154:157], v[184:187], v[50:53]
	v_mfma_f32_16x16x32_bf16 v[38:41], v[146:149], v[222:225], v[38:41]
	v_mfma_f32_16x16x32_bf16 v[34:37], v[154:157], v[222:225], v[34:37]
	v_mfma_f32_16x16x32_bf16 v[22:25], v[146:149], v[230:233], v[22:25]
	v_mfma_f32_16x16x32_bf16 v[18:21], v[154:157], v[230:233], v[18:21]
	s_mov_b32 m0, s64
	s_nop 0
	global_load_lds_dwordx4 v[250:251], off
	v_mfma_f32_16x16x32_bf16 v[6:9], v[146:149], v[238:241], v[6:9]
	v_mfma_f32_16x16x32_bf16 v[2:5], v[154:157], v[238:241], v[2:5]
	v_mfma_f32_16x16x32_bf16 v[54:57], v[150:153], v[218:221], v[54:57]
	v_mfma_f32_16x16x32_bf16 v[50:53], v[180:183], v[218:221], v[50:53]
	v_mfma_f32_16x16x32_bf16 v[38:41], v[150:153], v[226:229], v[38:41]
	v_mfma_f32_16x16x32_bf16 v[34:37], v[180:183], v[226:229], v[34:37]
	v_mfma_f32_16x16x32_bf16 v[22:25], v[150:153], v[234:237], v[22:25]
	v_mfma_f32_16x16x32_bf16 v[18:21], v[180:183], v[234:237], v[18:21]
	v_mfma_f32_16x16x32_bf16 v[6:9], v[150:153], v[242:245], v[6:9]
	v_mfma_f32_16x16x32_bf16 v[2:5], v[180:183], v[242:245], v[2:5]
	s_setprio 0
	s_barrier
	s_add_i32 s33, 0, 0x18000
	s_add_i32 s34, 0, 0x1c000
	v_add_u32_e32 v126, s33, v189
	v_add_u32_e32 v180, s34, v189
	ds_read_b128 v[114:117], v126
	ds_read_b128 v[118:121], v126 offset:1024
	ds_read_b128 v[122:125], v126 offset:2048
	ds_read_b128 v[126:129], v126 offset:3072
	ds_read_b128 v[146:149], v180
	ds_read_b128 v[150:153], v180 offset:1024
	ds_read_b128 v[154:157], v180 offset:2048
	ds_read_b128 v[180:183], v180 offset:3072
	s_add_u32 s12, s46, 0x40000
	s_addc_u32 s13, s47, 0
	s_mov_b32 m0, s65
	v_lshl_add_u64 v[252:253], s[12:13], 0, v[160:161]
	ds_read_b128 v[184:187], v212 offset:32768
	ds_read_b128 v[218:221], v212 offset:33792
	ds_read_b128 v[222:225], v212 offset:34816
	ds_read_b128 v[226:229], v212 offset:35840
	ds_read_b128 v[230:233], v212 offset:36864
	ds_read_b128 v[234:237], v212 offset:37888
	ds_read_b128 v[238:241], v212 offset:38912
	ds_read_b128 v[242:245], v212 offset:39936
	global_load_lds_dwordx4 v[252:253], off
	v_lshl_add_u64 v[252:253], s[12:13], 0, v[164:165]
	s_mov_b32 m0, s66
	s_nop 0
	global_load_lds_dwordx4 v[252:253], off
	s_waitcnt vmcnt(8)
	s_waitcnt lgkmcnt(0)
	s_barrier
	s_setprio 1
	s_waitcnt lgkmcnt(0)
	v_mfma_f32_16x16x32_bf16 v[142:145], v[114:117], v[184:187], v[142:145]
	v_mfma_f32_16x16x32_bf16 v[138:141], v[122:125], v[184:187], v[138:141]
	v_mfma_f32_16x16x32_bf16 v[110:113], v[114:117], v[222:225], v[110:113]
	v_mfma_f32_16x16x32_bf16 v[106:109], v[122:125], v[222:225], v[106:109]
	v_mfma_f32_16x16x32_bf16 v[94:97], v[114:117], v[230:233], v[94:97]
	v_mfma_f32_16x16x32_bf16 v[90:93], v[122:125], v[230:233], v[90:93]
	v_mfma_f32_16x16x32_bf16 v[78:81], v[114:117], v[238:241], v[78:81]
	v_mfma_f32_16x16x32_bf16 v[74:77], v[122:125], v[238:241], v[74:77]
	v_mfma_f32_16x16x32_bf16 v[142:145], v[118:121], v[218:221], v[142:145]
	v_mfma_f32_16x16x32_bf16 v[138:141], v[126:129], v[218:221], v[138:141]
	v_mfma_f32_16x16x32_bf16 v[110:113], v[118:121], v[226:229], v[110:113]
	v_mfma_f32_16x16x32_bf16 v[106:109], v[126:129], v[226:229], v[106:109]
	v_mfma_f32_16x16x32_bf16 v[94:97], v[118:121], v[234:237], v[94:97]
	v_mfma_f32_16x16x32_bf16 v[90:93], v[126:129], v[234:237], v[90:93]
	v_mfma_f32_16x16x32_bf16 v[78:81], v[118:121], v[242:245], v[78:81]
	v_mfma_f32_16x16x32_bf16 v[74:77], v[126:129], v[242:245], v[74:77]
	s_setprio 0
	s_setprio 1
	v_mfma_f32_16x16x32_bf16 v[134:137], v[146:149], v[184:187], v[134:137]
	v_mfma_f32_16x16x32_bf16 v[130:133], v[154:157], v[184:187], v[130:133]
	v_mfma_f32_16x16x32_bf16 v[102:105], v[146:149], v[222:225], v[102:105]
	v_mfma_f32_16x16x32_bf16 v[98:101], v[154:157], v[222:225], v[98:101]
	v_mfma_f32_16x16x32_bf16 v[86:89], v[146:149], v[230:233], v[86:89]
	v_mfma_f32_16x16x32_bf16 v[82:85], v[154:157], v[230:233], v[82:85]
	v_mfma_f32_16x16x32_bf16 v[70:73], v[146:149], v[238:241], v[70:73]
	v_mfma_f32_16x16x32_bf16 v[66:69], v[154:157], v[238:241], v[66:69]
	v_mfma_f32_16x16x32_bf16 v[134:137], v[150:153], v[218:221], v[134:137]
	v_mfma_f32_16x16x32_bf16 v[130:133], v[180:183], v[218:221], v[130:133]
	v_mfma_f32_16x16x32_bf16 v[102:105], v[150:153], v[226:229], v[102:105]
	v_mfma_f32_16x16x32_bf16 v[98:101], v[180:183], v[226:229], v[98:101]
	v_mfma_f32_16x16x32_bf16 v[86:89], v[150:153], v[234:237], v[86:89]
	v_mfma_f32_16x16x32_bf16 v[82:85], v[180:183], v[234:237], v[82:85]
	v_mfma_f32_16x16x32_bf16 v[70:73], v[150:153], v[242:245], v[70:73]
	v_mfma_f32_16x16x32_bf16 v[66:69], v[180:183], v[242:245], v[66:69]
	s_setprio 0
	s_barrier
; #define PG8_STAGE(bufoff, gbase, voff) do { _Pragma("unroll") for (int _i = 0; _i < 2; ++_i) \
;         __builtin_amdgcn_global_load_lds((const unsigned*)((const char*)(gbase) + (voff)[_i]), (PG8_LAS unsigned*)(lds + (bufoff) + ldsw + _i * 8192), 16, 0, 0); } while (0)
; #define PG8_LDA(dst, b, h) do { _Pragma("unroll") for (int m = 0; m < 4; ++m) _Pragma("unroll") for (int k = 0; k < 2; ++k) dst[m][k] = *(const PG8_LAS bf16x8*)(lds + PG8_SA(b, h) + aoff + m * 2048 + k * 1024); } while (0)
; #define PG8_MMA(ai, bj, At, Bt) do { __builtin_amdgcn_s_setprio(1); _Pragma("unroll") for (int m = 0; m < 4; ++m) _Pragma("unroll") for (int n = 0; n < 2; ++n) _Pragma("unroll") for (int k = 0; k < 2; ++k) \
;         acc[ai][bj][m][n] = __builtin_amdgcn_mfma_f32_16x16x32_bf16(Bt[n][k], At[m][k], acc[ai][bj][m][n], 0, 0, 0); __builtin_amdgcn_s_setprio(0); } while (0)
; #define PG8_WAIT_V(n) asm volatile("s_waitcnt vmcnt(" #n ")" ::: "memory")
; #define PG8_WAIT_L(n) asm volatile("s_waitcnt lgkmcnt(" #n ")" ::: "memory")
; #define PG8_BAR __builtin_amdgcn_s_barrier()
; #define PG8_SCHED __builtin_amdgcn_sched_barrier(0)
; template <class Epi, class Sched, bool ALIGN_EPI = false, bool SP2 = false>
; __device__ __forceinline__ void gemm_phase(PG8_LAS unsigned char* lds, const Gemm g, const Sched& S, const Epi& E) {
;     ...
;         for (int t = 0; t < nt; t += 2) {
;             const bool last = (t == nt - 2);
;             const char* a1 = cA + (size_t)(t + 1) * kstep;
;             const char* a2 = last ? nA : cA + (size_t)(t + 2) * kstep; const char* b2 = last ? nB : cB + (size_t)(t + 2) * kstep;
;     ...
;             PG8_LDA(At, 1, 1); PG8_STAGE(PG8_SB(1, 0), b3, voffB); PG8_STAGE(PG8_SB(1, 1), b3 + hstepB, voffB); PG8_STAGE(PG8_SA(1, 0), a3, voffA);
;             PG8_WAIT_V(8); PG8_WAIT_L(0); PG8_BAR; PG8_MMA(1, 0, At, B0); PG8_MMA(1, 1, At, B1); PG8_BAR; PG8_SCHED;
	s_add_i32 s12, s33, s54
	v_lshl_add_u64 v[158:159], v[158:159], 0, s[36:37]
	s_mov_b32 m0, s12
	ds_read_b128 v[184:187], v212 offset:49152
	ds_read_b128 v[218:221], v212 offset:50176
	ds_read_b128 v[222:225], v212 offset:51200
	ds_read_b128 v[226:229], v212 offset:52224
	ds_read_b128 v[230:233], v212 offset:53248
	ds_read_b128 v[234:237], v212 offset:54272
	ds_read_b128 v[238:241], v212 offset:55296
	ds_read_b128 v[242:245], v212 offset:56320
	global_load_lds_dwordx4 v[158:159], off
	s_add_i32 m0, s12, 0x2000
	s_add_u32 s10, s10, 0x2080
	v_lshl_add_u64 v[158:159], v[246:247], 0, s[36:37]
	s_addc_u32 s11, s11, 0
	s_add_i32 s12, s34, s54
	global_load_lds_dwordx4 v[158:159], off
	v_lshl_add_u64 v[158:159], s[10:11], 0, v[162:163]
	s_mov_b32 m0, s12
	s_nop 0
	global_load_lds_dwordx4 v[158:159], off
	v_lshl_add_u64 v[158:159], s[10:11], 0, v[166:167]
	s_add_i32 m0, s12, 0x2000
	s_nop 0
	global_load_lds_dwordx4 v[158:159], off
	s_waitcnt vmcnt(6)
	s_waitcnt lgkmcnt(0)
	s_barrier
	s_setprio 1
	s_waitcnt lgkmcnt(0)
	v_mfma_f32_16x16x32_bf16 v[62:65], v[114:117], v[184:187], v[62:65]
	v_mfma_f32_16x16x32_bf16 v[58:61], v[122:125], v[184:187], v[58:61]
	v_mfma_f32_16x16x32_bf16 v[46:49], v[114:117], v[222:225], v[46:49]
	v_mfma_f32_16x16x32_bf16 v[42:45], v[122:125], v[222:225], v[42:45]
	v_mfma_f32_16x16x32_bf16 v[30:33], v[114:117], v[230:233], v[30:33]
	v_mfma_f32_16x16x32_bf16 v[26:29], v[122:125], v[230:233], v[26:29]
	v_mfma_f32_16x16x32_bf16 v[14:17], v[114:117], v[238:241], v[14:17]
	v_mfma_f32_16x16x32_bf16 v[10:13], v[122:125], v[238:241], v[10:13]
	v_mfma_f32_16x16x32_bf16 v[62:65], v[118:121], v[218:221], v[62:65]
	v_mfma_f32_16x16x32_bf16 v[58:61], v[126:129], v[218:221], v[58:61]
	v_lshl_add_u64 v[158:159], v[248:249], 0, s[36:37]
	s_mov_b32 m0, s69
	s_nop 0
	global_load_lds_dwordx4 v[158:159], off
	v_mfma_f32_16x16x32_bf16 v[46:49], v[118:121], v[226:229], v[46:49]
	v_mfma_f32_16x16x32_bf16 v[42:45], v[126:129], v[226:229], v[42:45]
	v_mfma_f32_16x16x32_bf16 v[30:33], v[118:121], v[234:237], v[30:33]
	v_mfma_f32_16x16x32_bf16 v[26:29], v[126:129], v[234:237], v[26:29]
	v_mfma_f32_16x16x32_bf16 v[14:17], v[118:121], v[242:245], v[14:17]
	v_mfma_f32_16x16x32_bf16 v[10:13], v[126:129], v[242:245], v[10:13]
	s_setprio 0
	s_setprio 1
	v_mfma_f32_16x16x32_bf16 v[54:57], v[146:149], v[184:187], v[54:57]
	v_mfma_f32_16x16x32_bf16 v[50:53], v[154:157], v[184:187], v[50:53]
	v_mfma_f32_16x16x32_bf16 v[38:41], v[146:149], v[222:225], v[38:41]
	v_mfma_f32_16x16x32_bf16 v[34:37], v[154:157], v[222:225], v[34:37]
	v_mfma_f32_16x16x32_bf16 v[22:25], v[146:149], v[230:233], v[22:25]
	v_mfma_f32_16x16x32_bf16 v[18:21], v[154:157], v[230:233], v[18:21]
	v_lshl_add_u64 v[158:159], v[250:251], 0, s[36:37]
	s_mov_b32 m0, s70
	s_nop 0
	global_load_lds_dwordx4 v[158:159], off
	v_mfma_f32_16x16x32_bf16 v[6:9], v[146:149], v[238:241], v[6:9]
	v_mfma_f32_16x16x32_bf16 v[2:5], v[154:157], v[238:241], v[2:5]
	v_mfma_f32_16x16x32_bf16 v[54:57], v[150:153], v[218:221], v[54:57]
	v_mfma_f32_16x16x32_bf16 v[50:53], v[180:183], v[218:221], v[50:53]
	v_mfma_f32_16x16x32_bf16 v[38:41], v[150:153], v[226:229], v[38:41]
	v_mfma_f32_16x16x32_bf16 v[34:37], v[180:183], v[226:229], v[34:37]
	v_mfma_f32_16x16x32_bf16 v[22:25], v[150:153], v[234:237], v[22:25]
	v_mfma_f32_16x16x32_bf16 v[18:21], v[180:183], v[234:237], v[18:21]
	v_mfma_f32_16x16x32_bf16 v[6:9], v[150:153], v[242:245], v[6:9]
	v_mfma_f32_16x16x32_bf16 v[2:5], v[180:183], v[242:245], v[2:5]
	s_setprio 0
	s_barrier
	s_add_i32 s49, s49, 2
	s_add_u32 s0, s0, 0x100
	s_addc_u32 s1, s1, 0
	s_add_u32 s41, s41, 0x100
	s_addc_u32 s48, s48, 0
	s_cmp_gt_u32 s49, 13
	s_cbranch_scc0 .LBB0_688
	s_and_b64 vcc, exec, s[38:39]
	s_cbranch_vccz .LBB0_691
	s_barrier

; #define PG8_STAGE(bufoff, gbase, voff) do { _Pragma("unroll") for (int _i = 0; _i < 2; ++_i) \
;         __builtin_amdgcn_global_load_lds((const unsigned*)((const char*)(gbase) + (voff)[_i]), (PG8_LAS unsigned*)(lds + (bufoff) + ldsw + _i * 8192), 16, 0, 0); } while (0)
; #define PG8_LDA(dst, b, h) do { _Pragma("unroll") for (int m = 0; m < 4; ++m) _Pragma("unroll") for (int k = 0; k < 2; ++k) dst[m][k] = *(const PG8_LAS bf16x8*)(lds + PG8_SA(b, h) + aoff + m * 2048 + k * 1024); } while (0)
; #define PG8_LDB(dst, b, h) do { _Pragma("unroll") for (int n = 0; n < 2; ++n) _Pragma("unroll") for (int k = 0; k < 2; ++k) dst[n][k] = *(const PG8_LAS bf16x8*)(lds + PG8_SB(b, h) + boff + n * 2048 + k * 1024); } while (0)
; #define PG8_MMA(ai, bj, At, Bt) do { __builtin_amdgcn_s_setprio(1); _Pragma("unroll") for (int m = 0; m < 4; ++m) _Pragma("unroll") for (int n = 0; n < 2; ++n) _Pragma("unroll") for (int k = 0; k < 2; ++k) \
;         acc[ai][bj][m][n] = __builtin_amdgcn_mfma_f32_16x16x32_bf16(Bt[n][k], At[m][k], acc[ai][bj][m][n], 0, 0, 0); __builtin_amdgcn_s_setprio(0); } while (0)
; #define PG8_WAIT_V(n) asm volatile("s_waitcnt vmcnt(" #n ")" ::: "memory")
; #define PG8_WAIT_L(n) asm volatile("s_waitcnt lgkmcnt(" #n ")" ::: "memory")
; #define PG8_BAR __builtin_amdgcn_s_barrier()
; #define PG8_SCHED __builtin_amdgcn_sched_barrier(0)
; template <class Epi, class Sched, bool ALIGN_EPI = false, bool SP2 = false>
; __device__ __forceinline__ void gemm_phase(PG8_LAS unsigned char* lds, const Gemm g, const Sched& S, const Epi& E) {
;     ...
;             const char* a1 = cA + (size_t)(t + 1) * kstep;
;             const char* a2 = last ? nA : cA + (size_t)(t + 2) * kstep; const char* b2 = last ? nB : cB + (size_t)(t + 2) * kstep;
;             const char* a3 = a2 + kstep; const char* b3 = b2 + kstep;
;             if (last && has_next) S.a_ready(nxt);
;             if constexpr (SP2) {
;             PG8_LDB(B0, 0, 0); PG8_LDB(B1, 0, 1); PG8_SCHED; PG8_LDA(At, 0, 0); PG8_STAGE(PG8_SA(1, 1), a1 + hstepA, voffA);
;             PG8_WAIT_V(8); PG8_WAIT_L(0); PG8_BAR; PG8_MMA(0, 0, At, B0); PG8_MMA(0, 1, At, B1); PG8_BAR; PG8_SCHED;
;             PG8_LDA(At, 0, 1); PG8_STAGE(PG8_SB(0, 0), b2, voffB); PG8_STAGE(PG8_SB(0, 1), b2 + hstepB, voffB); PG8_STAGE(PG8_SA(0, 0), a2, voffA);
.LBB0_899:
	ds_read_b128 v[154:157], v150
	ds_read_b128 v[158:161], v150 offset:1024
	ds_read_b128 v[162:165], v150 offset:2048
	ds_read_b128 v[166:169], v150 offset:3072
	ds_read_b128 v[170:173], v151
	ds_read_b128 v[174:177], v151 offset:1024
	ds_read_b128 v[178:181], v151 offset:2048
	ds_read_b128 v[182:185], v151 offset:3072
	s_add_u32 s12, s0, 0xfffc0080
	s_addc_u32 s13, s1, -1
	s_cmp_eq_u32 s82, 12
	s_cselect_b32 s47, s15, s13
	s_cselect_b32 s46, s37, s12
	s_cselect_b32 s45, s39, s81
	s_cselect_b32 s44, s38, s80
	v_lshl_add_u64 v[146:147], s[0:1], 0, v[138:139]
	s_add_i32 m0, s43, 0xc000
	ds_read_b128 v[186:189], v152
	ds_read_b128 v[190:193], v152 offset:1024
	ds_read_b128 v[194:197], v152 offset:2048
	ds_read_b128 v[200:203], v152 offset:3072
	ds_read_b128 v[204:207], v152 offset:4096
	ds_read_b128 v[208:211], v152 offset:5120
	ds_read_b128 v[212:215], v152 offset:6144
	ds_read_b128 v[216:219], v152 offset:7168
	global_load_lds_dwordx4 v[146:147], off
	v_lshl_add_u64 v[146:147], s[0:1], 0, v[140:141]
	s_add_i32 m0, s43, 0xe000
	s_nop 0
	global_load_lds_dwordx4 v[146:147], off
	s_waitcnt vmcnt(8)
	s_waitcnt lgkmcnt(0)
	s_barrier
	s_setprio 1
	s_waitcnt lgkmcnt(0)
	v_mfma_f32_16x16x32_bf16 v[126:129], v[154:157], v[186:189], v[126:129]
	v_mfma_f32_16x16x32_bf16 v[122:125], v[162:165], v[186:189], v[122:125]
	v_mfma_f32_16x16x32_bf16 v[118:121], v[154:157], v[194:197], v[118:121]
	v_mfma_f32_16x16x32_bf16 v[110:113], v[162:165], v[194:197], v[110:113]
	v_mfma_f32_16x16x32_bf16 v[102:105], v[154:157], v[204:207], v[102:105]
	v_mfma_f32_16x16x32_bf16 v[94:97], v[162:165], v[204:207], v[94:97]
	v_mfma_f32_16x16x32_bf16 v[86:89], v[154:157], v[212:215], v[86:89]
	v_mfma_f32_16x16x32_bf16 v[78:81], v[162:165], v[212:215], v[78:81]
	v_mfma_f32_16x16x32_bf16 v[126:129], v[158:161], v[190:193], v[126:129]
	v_mfma_f32_16x16x32_bf16 v[122:125], v[166:169], v[190:193], v[122:125]
	v_mfma_f32_16x16x32_bf16 v[118:121], v[158:161], v[200:203], v[118:121]
	v_mfma_f32_16x16x32_bf16 v[110:113], v[166:169], v[200:203], v[110:113]
	v_mfma_f32_16x16x32_bf16 v[102:105], v[158:161], v[208:211], v[102:105]
	v_mfma_f32_16x16x32_bf16 v[94:97], v[166:169], v[208:211], v[94:97]
	v_mfma_f32_16x16x32_bf16 v[86:89], v[158:161], v[216:219], v[86:89]
	v_mfma_f32_16x16x32_bf16 v[78:81], v[166:169], v[216:219], v[78:81]
	s_setprio 0
	s_setprio 1
	v_mfma_f32_16x16x32_bf16 v[114:117], v[170:173], v[186:189], v[114:117]
	v_mfma_f32_16x16x32_bf16 v[106:109], v[178:181], v[186:189], v[106:109]
	v_mfma_f32_16x16x32_bf16 v[98:101], v[170:173], v[194:197], v[98:101]
	v_mfma_f32_16x16x32_bf16 v[90:93], v[178:181], v[194:197], v[90:93]
	v_mfma_f32_16x16x32_bf16 v[82:85], v[170:173], v[204:207], v[82:85]
	v_mfma_f32_16x16x32_bf16 v[74:77], v[178:181], v[204:207], v[74:77]
	v_mfma_f32_16x16x32_bf16 v[70:73], v[170:173], v[212:215], v[70:73]
	v_mfma_f32_16x16x32_bf16 v[66:69], v[178:181], v[212:215], v[66:69]
	v_mfma_f32_16x16x32_bf16 v[114:117], v[174:177], v[190:193], v[114:117]
	v_mfma_f32_16x16x32_bf16 v[106:109], v[182:185], v[190:193], v[106:109]
	v_mfma_f32_16x16x32_bf16 v[98:101], v[174:177], v[200:203], v[98:101]
	v_mfma_f32_16x16x32_bf16 v[90:93], v[182:185], v[200:203], v[90:93]
	v_mfma_f32_16x16x32_bf16 v[82:85], v[174:177], v[208:211], v[82:85]
	v_mfma_f32_16x16x32_bf16 v[74:77], v[182:185], v[208:211], v[74:77]
	v_mfma_f32_16x16x32_bf16 v[70:73], v[174:177], v[216:219], v[70:73]
	v_mfma_f32_16x16x32_bf16 v[66:69], v[182:185], v[216:219], v[66:69]
	s_setprio 0
	s_barrier
	s_add_i32 s12, s72, s55
	v_lshl_add_u64 v[146:147], s[44:45], 0, v[132:133]
	s_mov_b32 m0, s12
	ds_read_b128 v[186:189], v152 offset:16384
	ds_read_b128 v[190:193], v152 offset:17408
	ds_read_b128 v[194:197], v152 offset:18432
	ds_read_b128 v[200:203], v152 offset:19456
	ds_read_b128 v[204:207], v152 offset:20480
	ds_read_b128 v[208:211], v152 offset:21504
	ds_read_b128 v[212:215], v152 offset:22528
	ds_read_b128 v[216:219], v152 offset:23552
	global_load_lds_dwordx4 v[146:147], off
	s_add_i32 m0, s12, 0x2000
	s_add_u32 s12, s44, 0x40000
	v_lshl_add_u64 v[220:221], s[44:45], 0, v[136:137]
	s_addc_u32 s13, s45, 0
	s_add_i32 s33, s73, s55
	global_load_lds_dwordx4 v[220:221], off
	v_lshl_add_u64 v[222:223], s[12:13], 0, v[132:133]
	s_mov_b32 m0, s33
	v_lshl_add_u64 v[224:225], s[46:47], 0, v[134:135]
	global_load_lds_dwordx4 v[222:223], off
	v_lshl_add_u64 v[222:223], s[12:13], 0, v[136:137]
	s_add_i32 m0, s33, 0x2000
	s_nop 0
	global_load_lds_dwordx4 v[222:223], off
	s_waitcnt vmcnt(6)
	s_waitcnt lgkmcnt(0)
	s_barrier
; #define PG8_STAGE(bufoff, gbase, voff) do { _Pragma("unroll") for (int _i = 0; _i < 2; ++_i) \
;         __builtin_amdgcn_global_load_lds((const unsigned*)((const char*)(gbase) + (voff)[_i]), (PG8_LAS unsigned*)(lds + (bufoff) + ldsw + _i * 8192), 16, 0, 0); } while (0)
; #define PG8_LDA(dst, b, h) do { _Pragma("unroll") for (int m = 0; m < 4; ++m) _Pragma("unroll") for (int k = 0; k < 2; ++k) dst[m][k] = *(const PG8_LAS bf16x8*)(lds + PG8_SA(b, h) + aoff + m * 2048 + k * 1024); } while (0)
; #define PG8_LDB(dst, b, h) do { _Pragma("unroll") for (int n = 0; n < 2; ++n) _Pragma("unroll") for (int k = 0; k < 2; ++k) dst[n][k] = *(const PG8_LAS bf16x8*)(lds + PG8_SB(b, h) + boff + n * 2048 + k * 1024); } while (0)
; #define PG8_MMA(ai, bj, At, Bt) do { __builtin_amdgcn_s_setprio(1); _Pragma("unroll") for (int m = 0; m < 4; ++m) _Pragma("unroll") for (int n = 0; n < 2; ++n) _Pragma("unroll") for (int k = 0; k < 2; ++k) \
;         acc[ai][bj][m][n] = __builtin_amdgcn_mfma_f32_16x16x32_bf16(Bt[n][k], At[m][k], acc[ai][bj][m][n], 0, 0, 0); __builtin_amdgcn_s_setprio(0); } while (0)
; #define PG8_WAIT_V(n) asm volatile("s_waitcnt vmcnt(" #n ")" ::: "memory")
; #define PG8_WAIT_L(n) asm volatile("s_waitcnt lgkmcnt(" #n ")" ::: "memory")
; #define PG8_BAR __builtin_amdgcn_s_barrier()
; #define PG8_SCHED __builtin_amdgcn_sched_barrier(0)
; template <class Epi, class Sched, bool ALIGN_EPI = false, bool SP2 = false>
; __device__ __forceinline__ void gemm_phase(PG8_LAS unsigned char* lds, const Gemm g, const Sched& S, const Epi& E) {
;     ...
;             PG8_WAIT_V(8); PG8_WAIT_L(0); PG8_BAR; PG8_MMA(1, 0, At, B0); PG8_MMA(1, 1, At, B1); PG8_BAR; PG8_SCHED;
;             PG8_LDB(B0, 1, 0); PG8_LDB(B1, 1, 1); PG8_SCHED; PG8_LDA(At, 1, 0); PG8_STAGE(PG8_SA(0, 1), a2 + hstepA, voffA);
;             PG8_WAIT_V(8); PG8_WAIT_L(0); PG8_BAR; PG8_MMA(0, 0, At, B0); PG8_MMA(0, 1, At, B1); PG8_BAR; PG8_SCHED;
;             PG8_LDA(At, 1, 1); PG8_STAGE(PG8_SB(1, 0), b3, voffB); PG8_STAGE(PG8_SB(1, 1), b3 + hstepB, voffB); PG8_STAGE(PG8_SA(1, 0), a3, voffA);
	s_setprio 1
	s_waitcnt lgkmcnt(0)
	v_mfma_f32_16x16x32_bf16 v[62:65], v[154:157], v[186:189], v[62:65]
	v_mfma_f32_16x16x32_bf16 v[58:61], v[162:165], v[186:189], v[58:61]
	v_mfma_f32_16x16x32_bf16 v[54:57], v[154:157], v[194:197], v[54:57]
	v_mfma_f32_16x16x32_bf16 v[46:49], v[162:165], v[194:197], v[46:49]
	v_mfma_f32_16x16x32_bf16 v[38:41], v[154:157], v[204:207], v[38:41]
	v_mfma_f32_16x16x32_bf16 v[30:33], v[162:165], v[204:207], v[30:33]
	v_mfma_f32_16x16x32_bf16 v[22:25], v[154:157], v[212:215], v[22:25]
	v_mfma_f32_16x16x32_bf16 v[14:17], v[162:165], v[212:215], v[14:17]
	v_mfma_f32_16x16x32_bf16 v[62:65], v[158:161], v[190:193], v[62:65]
	v_mfma_f32_16x16x32_bf16 v[58:61], v[166:169], v[190:193], v[58:61]
	v_lshl_add_u64 v[222:223], s[46:47], 0, v[130:131]
	s_mov_b32 m0, s43
	s_nop 0
	global_load_lds_dwordx4 v[222:223], off
	v_mfma_f32_16x16x32_bf16 v[54:57], v[158:161], v[200:203], v[54:57]
	v_mfma_f32_16x16x32_bf16 v[46:49], v[166:169], v[200:203], v[46:49]
	v_mfma_f32_16x16x32_bf16 v[38:41], v[158:161], v[208:211], v[38:41]
	v_mfma_f32_16x16x32_bf16 v[30:33], v[166:169], v[208:211], v[30:33]
	v_mfma_f32_16x16x32_bf16 v[22:25], v[158:161], v[216:219], v[22:25]
	v_mfma_f32_16x16x32_bf16 v[14:17], v[166:169], v[216:219], v[14:17]
	s_setprio 0
	s_setprio 1
	v_mfma_f32_16x16x32_bf16 v[50:53], v[170:173], v[186:189], v[50:53]
	v_mfma_f32_16x16x32_bf16 v[42:45], v[178:181], v[186:189], v[42:45]
	v_mfma_f32_16x16x32_bf16 v[34:37], v[170:173], v[194:197], v[34:37]
	v_mfma_f32_16x16x32_bf16 v[26:29], v[178:181], v[194:197], v[26:29]
	v_mfma_f32_16x16x32_bf16 v[18:21], v[170:173], v[204:207], v[18:21]
	v_mfma_f32_16x16x32_bf16 v[10:13], v[178:181], v[204:207], v[10:13]
	s_mov_b32 m0, s64
	s_nop 0
	global_load_lds_dwordx4 v[224:225], off
	v_mfma_f32_16x16x32_bf16 v[6:9], v[170:173], v[212:215], v[6:9]
	v_mfma_f32_16x16x32_bf16 v[2:5], v[178:181], v[212:215], v[2:5]
	v_mfma_f32_16x16x32_bf16 v[50:53], v[174:177], v[190:193], v[50:53]
	v_mfma_f32_16x16x32_bf16 v[42:45], v[182:185], v[190:193], v[42:45]
	v_mfma_f32_16x16x32_bf16 v[34:37], v[174:177], v[200:203], v[34:37]
	v_mfma_f32_16x16x32_bf16 v[26:29], v[182:185], v[200:203], v[26:29]
	v_mfma_f32_16x16x32_bf16 v[18:21], v[174:177], v[208:211], v[18:21]
	v_mfma_f32_16x16x32_bf16 v[10:13], v[182:185], v[208:211], v[10:13]
	v_mfma_f32_16x16x32_bf16 v[6:9], v[174:177], v[216:219], v[6:9]
	v_mfma_f32_16x16x32_bf16 v[2:5], v[182:185], v[216:219], v[2:5]
	s_setprio 0
	s_barrier
	s_add_i32 s33, 0, 0x18000
	v_add_u32_e32 v153, s33, v148
	s_add_i32 s34, 0, 0x1c000
	ds_read_b128 v[154:157], v153
	ds_read_b128 v[158:161], v153 offset:1024
	ds_read_b128 v[162:165], v153 offset:2048
	ds_read_b128 v[166:169], v153 offset:3072
	v_add_u32_e32 v153, s34, v148
	ds_read_b128 v[170:173], v153
	ds_read_b128 v[174:177], v153 offset:1024
	ds_read_b128 v[178:181], v153 offset:2048
	ds_read_b128 v[182:185], v153 offset:3072
	s_add_u32 s12, s46, 0x40000
	s_addc_u32 s13, s47, 0
	s_mov_b32 m0, s65
	v_lshl_add_u64 v[226:227], s[12:13], 0, v[130:131]
	ds_read_b128 v[186:189], v152 offset:32768
	ds_read_b128 v[190:193], v152 offset:33792
	ds_read_b128 v[194:197], v152 offset:34816
	ds_read_b128 v[200:203], v152 offset:35840
	ds_read_b128 v[204:207], v152 offset:36864
	ds_read_b128 v[208:211], v152 offset:37888
	ds_read_b128 v[212:215], v152 offset:38912
	ds_read_b128 v[216:219], v152 offset:39936
	global_load_lds_dwordx4 v[226:227], off
	v_lshl_add_u64 v[226:227], s[12:13], 0, v[134:135]
	s_mov_b32 m0, s66
	s_nop 0
	global_load_lds_dwordx4 v[226:227], off
	s_waitcnt vmcnt(8)
	s_waitcnt lgkmcnt(0)
	s_barrier
	s_setprio 1
	s_waitcnt lgkmcnt(0)
	v_mfma_f32_16x16x32_bf16 v[126:129], v[154:157], v[186:189], v[126:129]
	v_mfma_f32_16x16x32_bf16 v[122:125], v[162:165], v[186:189], v[122:125]
	v_mfma_f32_16x16x32_bf16 v[118:121], v[154:157], v[194:197], v[118:121]
	v_mfma_f32_16x16x32_bf16 v[110:113], v[162:165], v[194:197], v[110:113]
	v_mfma_f32_16x16x32_bf16 v[102:105], v[154:157], v[204:207], v[102:105]
	v_mfma_f32_16x16x32_bf16 v[94:97], v[162:165], v[204:207], v[94:97]
	v_mfma_f32_16x16x32_bf16 v[86:89], v[154:157], v[212:215], v[86:89]
	v_mfma_f32_16x16x32_bf16 v[78:81], v[162:165], v[212:215], v[78:81]
	v_mfma_f32_16x16x32_bf16 v[126:129], v[158:161], v[190:193], v[126:129]
	v_mfma_f32_16x16x32_bf16 v[122:125], v[166:169], v[190:193], v[122:125]
	v_mfma_f32_16x16x32_bf16 v[118:121], v[158:161], v[200:203], v[118:121]
	v_mfma_f32_16x16x32_bf16 v[110:113], v[166:169], v[200:203], v[110:113]
	v_mfma_f32_16x16x32_bf16 v[102:105], v[158:161], v[208:211], v[102:105]
	v_mfma_f32_16x16x32_bf16 v[94:97], v[166:169], v[208:211], v[94:97]
	v_mfma_f32_16x16x32_bf16 v[86:89], v[158:161], v[216:219], v[86:89]
	v_mfma_f32_16x16x32_bf16 v[78:81], v[166:169], v[216:219], v[78:81]
	s_setprio 0
	s_setprio 1
	v_mfma_f32_16x16x32_bf16 v[114:117], v[170:173], v[186:189], v[114:117]
	v_mfma_f32_16x16x32_bf16 v[106:109], v[178:181], v[186:189], v[106:109]
	v_mfma_f32_16x16x32_bf16 v[98:101], v[170:173], v[194:197], v[98:101]
	v_mfma_f32_16x16x32_bf16 v[90:93], v[178:181], v[194:197], v[90:93]
	v_mfma_f32_16x16x32_bf16 v[82:85], v[170:173], v[204:207], v[82:85]
	v_mfma_f32_16x16x32_bf16 v[74:77], v[178:181], v[204:207], v[74:77]
	v_mfma_f32_16x16x32_bf16 v[70:73], v[170:173], v[212:215], v[70:73]
	v_mfma_f32_16x16x32_bf16 v[66:69], v[178:181], v[212:215], v[66:69]
	v_mfma_f32_16x16x32_bf16 v[114:117], v[174:177], v[190:193], v[114:117]
	v_mfma_f32_16x16x32_bf16 v[106:109], v[182:185], v[190:193], v[106:109]
	v_mfma_f32_16x16x32_bf16 v[98:101], v[174:177], v[200:203], v[98:101]
	v_mfma_f32_16x16x32_bf16 v[90:93], v[182:185], v[200:203], v[90:93]
	v_mfma_f32_16x16x32_bf16 v[82:85], v[174:177], v[208:211], v[82:85]
	v_mfma_f32_16x16x32_bf16 v[74:77], v[182:185], v[208:211], v[74:77]
	v_mfma_f32_16x16x32_bf16 v[70:73], v[174:177], v[216:219], v[70:73]
	v_mfma_f32_16x16x32_bf16 v[66:69], v[182:185], v[216:219], v[66:69]
	s_setprio 0
	s_barrier
; #define PG8_STAGE(bufoff, gbase, voff) do { _Pragma("unroll") for (int _i = 0; _i < 2; ++_i) \
;         __builtin_amdgcn_global_load_lds((const unsigned*)((const char*)(gbase) + (voff)[_i]), (PG8_LAS unsigned*)(lds + (bufoff) + ldsw + _i * 8192), 16, 0, 0); } while (0)
; #define PG8_LDA(dst, b, h) do { _Pragma("unroll") for (int m = 0; m < 4; ++m) _Pragma("unroll") for (int k = 0; k < 2; ++k) dst[m][k] = *(const PG8_LAS bf16x8*)(lds + PG8_SA(b, h) + aoff + m * 2048 + k * 1024); } while (0)
; #define PG8_MMA(ai, bj, At, Bt) do { __builtin_amdgcn_s_setprio(1); _Pragma("unroll") for (int m = 0; m < 4; ++m) _Pragma("unroll") for (int n = 0; n < 2; ++n) _Pragma("unroll") for (int k = 0; k < 2; ++k) \
;         acc[ai][bj][m][n] = __builtin_amdgcn_mfma_f32_16x16x32_bf16(Bt[n][k], At[m][k], acc[ai][bj][m][n], 0, 0, 0); __builtin_amdgcn_s_setprio(0); } while (0)
; #define PG8_WAIT_V(n) asm volatile("s_waitcnt vmcnt(" #n ")" ::: "memory")
; #define PG8_WAIT_L(n) asm volatile("s_waitcnt lgkmcnt(" #n ")" ::: "memory")
; #define PG8_BAR __builtin_amdgcn_s_barrier()
; #define PG8_SCHED __builtin_amdgcn_sched_barrier(0)
; template <class Epi, class Sched, bool ALIGN_EPI = false, bool SP2 = false>
; __device__ __forceinline__ void gemm_phase(PG8_LAS unsigned char* lds, const Gemm g, const Sched& S, const Epi& E) {
;     ...
;         for (int t = 0; t < nt; t += 2) {
;             const bool last = (t == nt - 2);
;             const char* a1 = cA + (size_t)(t + 1) * kstep;
;             const char* a2 = last ? nA : cA + (size_t)(t + 2) * kstep; const char* b2 = last ? nB : cB + (size_t)(t + 2) * kstep;
;     ...
;             PG8_LDA(At, 1, 1); PG8_STAGE(PG8_SB(1, 0), b3, voffB); PG8_STAGE(PG8_SB(1, 1), b3 + hstepB, voffB); PG8_STAGE(PG8_SA(1, 0), a3, voffA);
;             PG8_WAIT_V(8); PG8_WAIT_L(0); PG8_BAR; PG8_MMA(1, 0, At, B0); PG8_MMA(1, 1, At, B1); PG8_BAR; PG8_SCHED;
	s_add_i32 s12, s33, s55
	v_lshl_add_u64 v[146:147], v[146:147], 0, s[10:11]
	s_mov_b32 m0, s12
	ds_read_b128 v[186:189], v152 offset:49152
	ds_read_b128 v[190:193], v152 offset:50176
	ds_read_b128 v[194:197], v152 offset:51200
	ds_read_b128 v[200:203], v152 offset:52224
	ds_read_b128 v[204:207], v152 offset:53248
	ds_read_b128 v[208:211], v152 offset:54272
	ds_read_b128 v[212:215], v152 offset:55296
	ds_read_b128 v[216:219], v152 offset:56320
	global_load_lds_dwordx4 v[146:147], off
	s_add_i32 m0, s12, 0x2000
	s_add_u32 s12, s44, 0x40080
	v_lshl_add_u64 v[146:147], v[220:221], 0, s[10:11]
	s_addc_u32 s13, s45, 0
	s_add_i32 s33, s34, s55
	global_load_lds_dwordx4 v[146:147], off
	v_lshl_add_u64 v[146:147], s[12:13], 0, v[132:133]
	s_mov_b32 m0, s33
	s_nop 0
	global_load_lds_dwordx4 v[146:147], off
	v_lshl_add_u64 v[146:147], s[12:13], 0, v[136:137]
	s_add_i32 m0, s33, 0x2000
	s_nop 0
	global_load_lds_dwordx4 v[146:147], off
	s_waitcnt vmcnt(6)
	s_waitcnt lgkmcnt(0)
	s_barrier
	s_setprio 1
	s_waitcnt lgkmcnt(0)
	v_mfma_f32_16x16x32_bf16 v[62:65], v[154:157], v[186:189], v[62:65]
	v_mfma_f32_16x16x32_bf16 v[58:61], v[162:165], v[186:189], v[58:61]
	v_mfma_f32_16x16x32_bf16 v[54:57], v[154:157], v[194:197], v[54:57]
	v_mfma_f32_16x16x32_bf16 v[46:49], v[162:165], v[194:197], v[46:49]
	v_mfma_f32_16x16x32_bf16 v[38:41], v[154:157], v[204:207], v[38:41]
	v_mfma_f32_16x16x32_bf16 v[30:33], v[162:165], v[204:207], v[30:33]
	v_mfma_f32_16x16x32_bf16 v[22:25], v[154:157], v[212:215], v[22:25]
	v_mfma_f32_16x16x32_bf16 v[14:17], v[162:165], v[212:215], v[14:17]
	v_mfma_f32_16x16x32_bf16 v[62:65], v[158:161], v[190:193], v[62:65]
	v_mfma_f32_16x16x32_bf16 v[58:61], v[166:169], v[190:193], v[58:61]
	v_lshl_add_u64 v[146:147], v[222:223], 0, s[10:11]
	s_mov_b32 m0, s68
	s_nop 0
	global_load_lds_dwordx4 v[146:147], off
	v_mfma_f32_16x16x32_bf16 v[54:57], v[158:161], v[200:203], v[54:57]
	v_mfma_f32_16x16x32_bf16 v[46:49], v[166:169], v[200:203], v[46:49]
	v_mfma_f32_16x16x32_bf16 v[38:41], v[158:161], v[208:211], v[38:41]
	v_mfma_f32_16x16x32_bf16 v[30:33], v[166:169], v[208:211], v[30:33]
	v_mfma_f32_16x16x32_bf16 v[22:25], v[158:161], v[216:219], v[22:25]
	v_mfma_f32_16x16x32_bf16 v[14:17], v[166:169], v[216:219], v[14:17]
	s_setprio 0
	s_setprio 1
	v_mfma_f32_16x16x32_bf16 v[50:53], v[170:173], v[186:189], v[50:53]
	v_mfma_f32_16x16x32_bf16 v[42:45], v[178:181], v[186:189], v[42:45]
	v_mfma_f32_16x16x32_bf16 v[34:37], v[170:173], v[194:197], v[34:37]
	v_mfma_f32_16x16x32_bf16 v[26:29], v[178:181], v[194:197], v[26:29]
	v_mfma_f32_16x16x32_bf16 v[18:21], v[170:173], v[204:207], v[18:21]
	v_mfma_f32_16x16x32_bf16 v[10:13], v[178:181], v[204:207], v[10:13]
	v_lshl_add_u64 v[146:147], v[224:225], 0, s[10:11]
	s_mov_b32 m0, s69
	s_nop 0
	global_load_lds_dwordx4 v[146:147], off
	v_mfma_f32_16x16x32_bf16 v[6:9], v[170:173], v[212:215], v[6:9]
	v_mfma_f32_16x16x32_bf16 v[2:5], v[178:181], v[212:215], v[2:5]
	v_mfma_f32_16x16x32_bf16 v[50:53], v[174:177], v[190:193], v[50:53]
	v_mfma_f32_16x16x32_bf16 v[42:45], v[182:185], v[190:193], v[42:45]
	v_mfma_f32_16x16x32_bf16 v[34:37], v[174:177], v[200:203], v[34:37]
	v_mfma_f32_16x16x32_bf16 v[26:29], v[182:185], v[200:203], v[26:29]
	v_mfma_f32_16x16x32_bf16 v[18:21], v[174:177], v[208:211], v[18:21]
	v_mfma_f32_16x16x32_bf16 v[10:13], v[182:185], v[208:211], v[10:13]
	v_mfma_f32_16x16x32_bf16 v[6:9], v[174:177], v[216:219], v[6:9]
	v_mfma_f32_16x16x32_bf16 v[2:5], v[182:185], v[216:219], v[2:5]
	s_setprio 0
	s_barrier
	s_add_i32 s82, s82, 2
	s_add_u32 s0, s0, 0x100
	s_addc_u32 s1, s1, 0
	s_add_u32 s80, s80, 0x100
	s_addc_u32 s81, s81, 0
	s_cmp_gt_u32 s82, 13
	s_cbranch_scc0 .LBB0_899
	s_and_b64 vcc, exec, s[24:25]
	s_cbranch_vccz .LBB0_902
	s_barrier

; #define PG8_STAGE(bufoff, gbase, voff) do { _Pragma("unroll") for (int _i = 0; _i < 2; ++_i) \
;         __builtin_amdgcn_global_load_lds((const unsigned*)((const char*)(gbase) + (voff)[_i]), (PG8_LAS unsigned*)(lds + (bufoff) + ldsw + _i * 8192), 16, 0, 0); } while (0)
; #define PG8_LDA(dst, b, h) do { _Pragma("unroll") for (int m = 0; m < 4; ++m) _Pragma("unroll") for (int k = 0; k < 2; ++k) dst[m][k] = *(const PG8_LAS bf16x8*)(lds + PG8_SA(b, h) + aoff + m * 2048 + k * 1024); } while (0)
; #define PG8_LDB(dst, b, h) do { _Pragma("unroll") for (int n = 0; n < 2; ++n) _Pragma("unroll") for (int k = 0; k < 2; ++k) dst[n][k] = *(const PG8_LAS bf16x8*)(lds + PG8_SB(b, h) + boff + n * 2048 + k * 1024); } while (0)
; #define PG8_MMA(ai, bj, At, Bt) do { __builtin_amdgcn_s_setprio(1); _Pragma("unroll") for (int m = 0; m < 4; ++m) _Pragma("unroll") for (int n = 0; n < 2; ++n) _Pragma("unroll") for (int k = 0; k < 2; ++k) \
;         acc[ai][bj][m][n] = __builtin_amdgcn_mfma_f32_16x16x32_bf16(Bt[n][k], At[m][k], acc[ai][bj][m][n], 0, 0, 0); __builtin_amdgcn_s_setprio(0); } while (0)
; #define PG8_WAIT_V(n) asm volatile("s_waitcnt vmcnt(" #n ")" ::: "memory")
; #define PG8_WAIT_L(n) asm volatile("s_waitcnt lgkmcnt(" #n ")" ::: "memory")
; #define PG8_BAR __builtin_amdgcn_s_barrier()
; #define PG8_SCHED __builtin_amdgcn_sched_barrier(0)
; template <class Epi, class Sched, bool ALIGN_EPI = false, bool SP2 = false>
; __device__ __forceinline__ void gemm_phase(PG8_LAS unsigned char* lds, const Gemm g, const Sched& S, const Epi& E) {
;     ...
;             const char* a1 = cA + (size_t)(t + 1) * kstep;
;             const char* a2 = last ? nA : cA + (size_t)(t + 2) * kstep; const char* b2 = last ? nB : cB + (size_t)(t + 2) * kstep;
;             const char* a3 = a2 + kstep; const char* b3 = b2 + kstep;
;             if (last && has_next) S.a_ready(nxt);
;             if constexpr (SP2) {
;             PG8_LDB(B0, 0, 0); PG8_LDB(B1, 0, 1); PG8_SCHED; PG8_LDA(At, 0, 0); PG8_STAGE(PG8_SA(1, 1), a1 + hstepA, voffA);
;             PG8_WAIT_V(8); PG8_WAIT_L(0); PG8_BAR; PG8_MMA(0, 0, At, B0); PG8_MMA(0, 1, At, B1); PG8_BAR; PG8_SCHED;
;             PG8_LDA(At, 0, 1); PG8_STAGE(PG8_SB(0, 0), b2, voffB); PG8_STAGE(PG8_SB(0, 1), b2 + hstepB, voffB); PG8_STAGE(PG8_SA(0, 0), a2, voffA);
.LBB0_1040:
	ds_read_b128 v[146:149], v154
	ds_read_b128 v[158:161], v154 offset:1024
	ds_read_b128 v[162:165], v154 offset:2048
	ds_read_b128 v[166:169], v154 offset:3072
	ds_read_b128 v[170:173], v155
	ds_read_b128 v[174:177], v155 offset:1024
	ds_read_b128 v[178:181], v155 offset:2048
	ds_read_b128 v[182:185], v155 offset:3072
	s_add_u32 s12, s0, 0xfffc0080
	s_addc_u32 s13, s1, -1
	s_cmp_eq_u32 s76, 12
	s_cselect_b32 s45, s15, s13
	s_cselect_b32 s44, s31, s12
	s_cselect_b32 s43, s37, s75
	s_cselect_b32 s42, s36, s74
	v_lshl_add_u64 v[150:151], s[0:1], 0, v[138:139]
	s_add_i32 m0, s41, 0xc000
	ds_read_b128 v[186:189], v156
	ds_read_b128 v[190:193], v156 offset:1024
	ds_read_b128 v[194:197], v156 offset:2048
	ds_read_b128 v[200:203], v156 offset:3072
	ds_read_b128 v[204:207], v156 offset:4096
	ds_read_b128 v[208:211], v156 offset:5120
	ds_read_b128 v[212:215], v156 offset:6144
	ds_read_b128 v[216:219], v156 offset:7168
	global_load_lds_dwordx4 v[150:151], off
	v_lshl_add_u64 v[150:151], s[0:1], 0, v[140:141]
	s_add_i32 m0, s41, 0xe000
	s_nop 0
	global_load_lds_dwordx4 v[150:151], off
	s_waitcnt vmcnt(8)
	s_waitcnt lgkmcnt(0)
	s_barrier
	s_setprio 1
	s_waitcnt lgkmcnt(0)
	v_mfma_f32_16x16x32_bf16 v[126:129], v[146:149], v[186:189], v[126:129]
	v_mfma_f32_16x16x32_bf16 v[122:125], v[162:165], v[186:189], v[122:125]
	v_mfma_f32_16x16x32_bf16 v[110:113], v[146:149], v[194:197], v[110:113]
	v_mfma_f32_16x16x32_bf16 v[106:109], v[162:165], v[194:197], v[106:109]
	v_mfma_f32_16x16x32_bf16 v[94:97], v[146:149], v[204:207], v[94:97]
	v_mfma_f32_16x16x32_bf16 v[90:93], v[162:165], v[204:207], v[90:93]
	v_mfma_f32_16x16x32_bf16 v[78:81], v[146:149], v[212:215], v[78:81]
	v_mfma_f32_16x16x32_bf16 v[74:77], v[162:165], v[212:215], v[74:77]
	v_mfma_f32_16x16x32_bf16 v[126:129], v[158:161], v[190:193], v[126:129]
	v_mfma_f32_16x16x32_bf16 v[122:125], v[166:169], v[190:193], v[122:125]
	v_mfma_f32_16x16x32_bf16 v[110:113], v[158:161], v[200:203], v[110:113]
	v_mfma_f32_16x16x32_bf16 v[106:109], v[166:169], v[200:203], v[106:109]
	v_mfma_f32_16x16x32_bf16 v[94:97], v[158:161], v[208:211], v[94:97]
	v_mfma_f32_16x16x32_bf16 v[90:93], v[166:169], v[208:211], v[90:93]
	v_mfma_f32_16x16x32_bf16 v[78:81], v[158:161], v[216:219], v[78:81]
	v_mfma_f32_16x16x32_bf16 v[74:77], v[166:169], v[216:219], v[74:77]
	s_setprio 0
	s_setprio 1
	v_mfma_f32_16x16x32_bf16 v[118:121], v[170:173], v[186:189], v[118:121]
	v_mfma_f32_16x16x32_bf16 v[114:117], v[178:181], v[186:189], v[114:117]
	v_mfma_f32_16x16x32_bf16 v[102:105], v[170:173], v[194:197], v[102:105]
	v_mfma_f32_16x16x32_bf16 v[98:101], v[178:181], v[194:197], v[98:101]
	v_mfma_f32_16x16x32_bf16 v[86:89], v[170:173], v[204:207], v[86:89]
	v_mfma_f32_16x16x32_bf16 v[82:85], v[178:181], v[204:207], v[82:85]
	v_mfma_f32_16x16x32_bf16 v[70:73], v[170:173], v[212:215], v[70:73]
	v_mfma_f32_16x16x32_bf16 v[66:69], v[178:181], v[212:215], v[66:69]
	v_mfma_f32_16x16x32_bf16 v[118:121], v[174:177], v[190:193], v[118:121]
	v_mfma_f32_16x16x32_bf16 v[114:117], v[182:185], v[190:193], v[114:117]
	v_mfma_f32_16x16x32_bf16 v[102:105], v[174:177], v[200:203], v[102:105]
	v_mfma_f32_16x16x32_bf16 v[98:101], v[182:185], v[200:203], v[98:101]
	v_mfma_f32_16x16x32_bf16 v[86:89], v[174:177], v[208:211], v[86:89]
	v_mfma_f32_16x16x32_bf16 v[82:85], v[182:185], v[208:211], v[82:85]
	v_mfma_f32_16x16x32_bf16 v[70:73], v[174:177], v[216:219], v[70:73]
	v_mfma_f32_16x16x32_bf16 v[66:69], v[182:185], v[216:219], v[66:69]
	s_setprio 0
	s_barrier
	s_add_i32 s12, s66, s49
	v_lshl_add_u64 v[150:151], s[42:43], 0, v[132:133]
	s_mov_b32 m0, s12
	ds_read_b128 v[186:189], v156 offset:16384
	ds_read_b128 v[190:193], v156 offset:17408
	ds_read_b128 v[194:197], v156 offset:18432
	ds_read_b128 v[200:203], v156 offset:19456
	ds_read_b128 v[204:207], v156 offset:20480
	ds_read_b128 v[208:211], v156 offset:21504
	ds_read_b128 v[212:215], v156 offset:22528
	ds_read_b128 v[216:219], v156 offset:23552
	global_load_lds_dwordx4 v[150:151], off
	s_add_i32 m0, s12, 0x2000
	s_add_u32 s12, s42, 0x40000
	v_lshl_add_u64 v[220:221], s[42:43], 0, v[136:137]
	s_addc_u32 s13, s43, 0
	s_add_i32 s33, s67, s49
	global_load_lds_dwordx4 v[220:221], off
	v_lshl_add_u64 v[222:223], s[12:13], 0, v[132:133]
	s_mov_b32 m0, s33
	v_lshl_add_u64 v[224:225], s[44:45], 0, v[134:135]
	global_load_lds_dwordx4 v[222:223], off
	v_lshl_add_u64 v[222:223], s[12:13], 0, v[136:137]
	s_add_i32 m0, s33, 0x2000
	s_nop 0
	global_load_lds_dwordx4 v[222:223], off
	s_waitcnt vmcnt(6)
	s_waitcnt lgkmcnt(0)
	s_barrier
; #define PG8_STAGE(bufoff, gbase, voff) do { _Pragma("unroll") for (int _i = 0; _i < 2; ++_i) \
;         __builtin_amdgcn_global_load_lds((const unsigned*)((const char*)(gbase) + (voff)[_i]), (PG8_LAS unsigned*)(lds + (bufoff) + ldsw + _i * 8192), 16, 0, 0); } while (0)
; #define PG8_LDA(dst, b, h) do { _Pragma("unroll") for (int m = 0; m < 4; ++m) _Pragma("unroll") for (int k = 0; k < 2; ++k) dst[m][k] = *(const PG8_LAS bf16x8*)(lds + PG8_SA(b, h) + aoff + m * 2048 + k * 1024); } while (0)
; #define PG8_LDB(dst, b, h) do { _Pragma("unroll") for (int n = 0; n < 2; ++n) _Pragma("unroll") for (int k = 0; k < 2; ++k) dst[n][k] = *(const PG8_LAS bf16x8*)(lds + PG8_SB(b, h) + boff + n * 2048 + k * 1024); } while (0)
; #define PG8_MMA(ai, bj, At, Bt) do { __builtin_amdgcn_s_setprio(1); _Pragma("unroll") for (int m = 0; m < 4; ++m) _Pragma("unroll") for (int n = 0; n < 2; ++n) _Pragma("unroll") for (int k = 0; k < 2; ++k) \
;         acc[ai][bj][m][n] = __builtin_amdgcn_mfma_f32_16x16x32_bf16(Bt[n][k], At[m][k], acc[ai][bj][m][n], 0, 0, 0); __builtin_amdgcn_s_setprio(0); } while (0)
; #define PG8_WAIT_V(n) asm volatile("s_waitcnt vmcnt(" #n ")" ::: "memory")
; #define PG8_WAIT_L(n) asm volatile("s_waitcnt lgkmcnt(" #n ")" ::: "memory")
; #define PG8_BAR __builtin_amdgcn_s_barrier()
; #define PG8_SCHED __builtin_amdgcn_sched_barrier(0)
; template <class Epi, class Sched, bool ALIGN_EPI = false, bool SP2 = false>
; __device__ __forceinline__ void gemm_phase(PG8_LAS unsigned char* lds, const Gemm g, const Sched& S, const Epi& E) {
;     ...
;             PG8_WAIT_V(8); PG8_WAIT_L(0); PG8_BAR; PG8_MMA(1, 0, At, B0); PG8_MMA(1, 1, At, B1); PG8_BAR; PG8_SCHED;
;             PG8_LDB(B0, 1, 0); PG8_LDB(B1, 1, 1); PG8_SCHED; PG8_LDA(At, 1, 0); PG8_STAGE(PG8_SA(0, 1), a2 + hstepA, voffA);
;             PG8_WAIT_V(8); PG8_WAIT_L(0); PG8_BAR; PG8_MMA(0, 0, At, B0); PG8_MMA(0, 1, At, B1); PG8_BAR; PG8_SCHED;
;             PG8_LDA(At, 1, 1); PG8_STAGE(PG8_SB(1, 0), b3, voffB); PG8_STAGE(PG8_SB(1, 1), b3 + hstepB, voffB); PG8_STAGE(PG8_SA(1, 0), a3, voffA);
	s_setprio 1
	s_waitcnt lgkmcnt(0)
	v_mfma_f32_16x16x32_bf16 v[62:65], v[146:149], v[186:189], v[62:65]
	v_mfma_f32_16x16x32_bf16 v[58:61], v[162:165], v[186:189], v[58:61]
	v_mfma_f32_16x16x32_bf16 v[46:49], v[146:149], v[194:197], v[46:49]
	v_mfma_f32_16x16x32_bf16 v[42:45], v[162:165], v[194:197], v[42:45]
	v_mfma_f32_16x16x32_bf16 v[30:33], v[146:149], v[204:207], v[30:33]
	v_mfma_f32_16x16x32_bf16 v[26:29], v[162:165], v[204:207], v[26:29]
	v_mfma_f32_16x16x32_bf16 v[14:17], v[146:149], v[212:215], v[14:17]
	v_mfma_f32_16x16x32_bf16 v[10:13], v[162:165], v[212:215], v[10:13]
	v_mfma_f32_16x16x32_bf16 v[62:65], v[158:161], v[190:193], v[62:65]
	v_mfma_f32_16x16x32_bf16 v[58:61], v[166:169], v[190:193], v[58:61]
	v_lshl_add_u64 v[222:223], s[44:45], 0, v[130:131]
	s_mov_b32 m0, s41
	s_nop 0
	global_load_lds_dwordx4 v[222:223], off
	v_mfma_f32_16x16x32_bf16 v[46:49], v[158:161], v[200:203], v[46:49]
	v_mfma_f32_16x16x32_bf16 v[42:45], v[166:169], v[200:203], v[42:45]
	v_mfma_f32_16x16x32_bf16 v[30:33], v[158:161], v[208:211], v[30:33]
	v_mfma_f32_16x16x32_bf16 v[26:29], v[166:169], v[208:211], v[26:29]
	v_mfma_f32_16x16x32_bf16 v[14:17], v[158:161], v[216:219], v[14:17]
	v_mfma_f32_16x16x32_bf16 v[10:13], v[166:169], v[216:219], v[10:13]
	s_setprio 0
	s_setprio 1
	v_mfma_f32_16x16x32_bf16 v[54:57], v[170:173], v[186:189], v[54:57]
	v_mfma_f32_16x16x32_bf16 v[50:53], v[178:181], v[186:189], v[50:53]
	v_mfma_f32_16x16x32_bf16 v[38:41], v[170:173], v[194:197], v[38:41]
	v_mfma_f32_16x16x32_bf16 v[34:37], v[178:181], v[194:197], v[34:37]
	v_mfma_f32_16x16x32_bf16 v[22:25], v[170:173], v[204:207], v[22:25]
	v_mfma_f32_16x16x32_bf16 v[18:21], v[178:181], v[204:207], v[18:21]
	s_mov_b32 m0, s50
	s_nop 0
	global_load_lds_dwordx4 v[224:225], off
	v_mfma_f32_16x16x32_bf16 v[6:9], v[170:173], v[212:215], v[6:9]
	v_mfma_f32_16x16x32_bf16 v[2:5], v[178:181], v[212:215], v[2:5]
	v_mfma_f32_16x16x32_bf16 v[54:57], v[174:177], v[190:193], v[54:57]
	v_mfma_f32_16x16x32_bf16 v[50:53], v[182:185], v[190:193], v[50:53]
	v_mfma_f32_16x16x32_bf16 v[38:41], v[174:177], v[200:203], v[38:41]
	v_mfma_f32_16x16x32_bf16 v[34:37], v[182:185], v[200:203], v[34:37]
	v_mfma_f32_16x16x32_bf16 v[22:25], v[174:177], v[208:211], v[22:25]
	v_mfma_f32_16x16x32_bf16 v[18:21], v[182:185], v[208:211], v[18:21]
	v_mfma_f32_16x16x32_bf16 v[6:9], v[174:177], v[216:219], v[6:9]
	v_mfma_f32_16x16x32_bf16 v[2:5], v[182:185], v[216:219], v[2:5]
	s_setprio 0
	s_barrier
	s_add_i32 s33, 0, 0x18000
	v_add_u32_e32 v157, s33, v152
	s_add_i32 s34, 0, 0x1c000
	ds_read_b128 v[146:149], v157
	ds_read_b128 v[158:161], v157 offset:1024
	ds_read_b128 v[162:165], v157 offset:2048
	ds_read_b128 v[166:169], v157 offset:3072
	v_add_u32_e32 v157, s34, v152
	ds_read_b128 v[170:173], v157
	ds_read_b128 v[174:177], v157 offset:1024
	ds_read_b128 v[178:181], v157 offset:2048
	ds_read_b128 v[182:185], v157 offset:3072
	s_add_u32 s12, s44, 0x40000
	s_addc_u32 s13, s45, 0
	s_mov_b32 m0, s51
	v_lshl_add_u64 v[226:227], s[12:13], 0, v[130:131]
	ds_read_b128 v[186:189], v156 offset:32768
	ds_read_b128 v[190:193], v156 offset:33792
	ds_read_b128 v[194:197], v156 offset:34816
	ds_read_b128 v[200:203], v156 offset:35840
	ds_read_b128 v[204:207], v156 offset:36864
	ds_read_b128 v[208:211], v156 offset:37888
	ds_read_b128 v[212:215], v156 offset:38912
	ds_read_b128 v[216:219], v156 offset:39936
	global_load_lds_dwordx4 v[226:227], off
	v_lshl_add_u64 v[226:227], s[12:13], 0, v[134:135]
	s_mov_b32 m0, s52
	s_nop 0
	global_load_lds_dwordx4 v[226:227], off
	s_waitcnt vmcnt(8)
	s_waitcnt lgkmcnt(0)
	s_barrier
	s_setprio 1
	s_waitcnt lgkmcnt(0)
	v_mfma_f32_16x16x32_bf16 v[126:129], v[146:149], v[186:189], v[126:129]
	v_mfma_f32_16x16x32_bf16 v[122:125], v[162:165], v[186:189], v[122:125]
	v_mfma_f32_16x16x32_bf16 v[110:113], v[146:149], v[194:197], v[110:113]
	v_mfma_f32_16x16x32_bf16 v[106:109], v[162:165], v[194:197], v[106:109]
	v_mfma_f32_16x16x32_bf16 v[94:97], v[146:149], v[204:207], v[94:97]
	v_mfma_f32_16x16x32_bf16 v[90:93], v[162:165], v[204:207], v[90:93]
	v_mfma_f32_16x16x32_bf16 v[78:81], v[146:149], v[212:215], v[78:81]
	v_mfma_f32_16x16x32_bf16 v[74:77], v[162:165], v[212:215], v[74:77]
	v_mfma_f32_16x16x32_bf16 v[126:129], v[158:161], v[190:193], v[126:129]
	v_mfma_f32_16x16x32_bf16 v[122:125], v[166:169], v[190:193], v[122:125]
	v_mfma_f32_16x16x32_bf16 v[110:113], v[158:161], v[200:203], v[110:113]
	v_mfma_f32_16x16x32_bf16 v[106:109], v[166:169], v[200:203], v[106:109]
	v_mfma_f32_16x16x32_bf16 v[94:97], v[158:161], v[208:211], v[94:97]
	v_mfma_f32_16x16x32_bf16 v[90:93], v[166:169], v[208:211], v[90:93]
	v_mfma_f32_16x16x32_bf16 v[78:81], v[158:161], v[216:219], v[78:81]
	v_mfma_f32_16x16x32_bf16 v[74:77], v[166:169], v[216:219], v[74:77]
	s_setprio 0
	s_setprio 1
	v_mfma_f32_16x16x32_bf16 v[118:121], v[170:173], v[186:189], v[118:121]
	v_mfma_f32_16x16x32_bf16 v[114:117], v[178:181], v[186:189], v[114:117]
	v_mfma_f32_16x16x32_bf16 v[102:105], v[170:173], v[194:197], v[102:105]
	v_mfma_f32_16x16x32_bf16 v[98:101], v[178:181], v[194:197], v[98:101]
	v_mfma_f32_16x16x32_bf16 v[86:89], v[170:173], v[204:207], v[86:89]
	v_mfma_f32_16x16x32_bf16 v[82:85], v[178:181], v[204:207], v[82:85]
	v_mfma_f32_16x16x32_bf16 v[70:73], v[170:173], v[212:215], v[70:73]
	v_mfma_f32_16x16x32_bf16 v[66:69], v[178:181], v[212:215], v[66:69]
	v_mfma_f32_16x16x32_bf16 v[118:121], v[174:177], v[190:193], v[118:121]
	v_mfma_f32_16x16x32_bf16 v[114:117], v[182:185], v[190:193], v[114:117]
	v_mfma_f32_16x16x32_bf16 v[102:105], v[174:177], v[200:203], v[102:105]
	v_mfma_f32_16x16x32_bf16 v[98:101], v[182:185], v[200:203], v[98:101]
	v_mfma_f32_16x16x32_bf16 v[86:89], v[174:177], v[208:211], v[86:89]
	v_mfma_f32_16x16x32_bf16 v[82:85], v[182:185], v[208:211], v[82:85]
	v_mfma_f32_16x16x32_bf16 v[70:73], v[174:177], v[216:219], v[70:73]
	v_mfma_f32_16x16x32_bf16 v[66:69], v[182:185], v[216:219], v[66:69]
	s_setprio 0
	s_barrier
; #define PG8_STAGE(bufoff, gbase, voff) do { _Pragma("unroll") for (int _i = 0; _i < 2; ++_i) \
;         __builtin_amdgcn_global_load_lds((const unsigned*)((const char*)(gbase) + (voff)[_i]), (PG8_LAS unsigned*)(lds + (bufoff) + ldsw + _i * 8192), 16, 0, 0); } while (0)
; #define PG8_LDA(dst, b, h) do { _Pragma("unroll") for (int m = 0; m < 4; ++m) _Pragma("unroll") for (int k = 0; k < 2; ++k) dst[m][k] = *(const PG8_LAS bf16x8*)(lds + PG8_SA(b, h) + aoff + m * 2048 + k * 1024); } while (0)
; #define PG8_MMA(ai, bj, At, Bt) do { __builtin_amdgcn_s_setprio(1); _Pragma("unroll") for (int m = 0; m < 4; ++m) _Pragma("unroll") for (int n = 0; n < 2; ++n) _Pragma("unroll") for (int k = 0; k < 2; ++k) \
;         acc[ai][bj][m][n] = __builtin_amdgcn_mfma_f32_16x16x32_bf16(Bt[n][k], At[m][k], acc[ai][bj][m][n], 0, 0, 0); __builtin_amdgcn_s_setprio(0); } while (0)
; #define PG8_WAIT_V(n) asm volatile("s_waitcnt vmcnt(" #n ")" ::: "memory")
; #define PG8_WAIT_L(n) asm volatile("s_waitcnt lgkmcnt(" #n ")" ::: "memory")
; #define PG8_BAR __builtin_amdgcn_s_barrier()
; #define PG8_SCHED __builtin_amdgcn_sched_barrier(0)
; template <class Epi, class Sched, bool ALIGN_EPI = false, bool SP2 = false>
; __device__ __forceinline__ void gemm_phase(PG8_LAS unsigned char* lds, const Gemm g, const Sched& S, const Epi& E) {
;     ...
;         for (int t = 0; t < nt; t += 2) {
;             const bool last = (t == nt - 2);
;             const char* a1 = cA + (size_t)(t + 1) * kstep;
;             const char* a2 = last ? nA : cA + (size_t)(t + 2) * kstep; const char* b2 = last ? nB : cB + (size_t)(t + 2) * kstep;
;     ...
;             PG8_LDA(At, 1, 1); PG8_STAGE(PG8_SB(1, 0), b3, voffB); PG8_STAGE(PG8_SB(1, 1), b3 + hstepB, voffB); PG8_STAGE(PG8_SA(1, 0), a3, voffA);
;             PG8_WAIT_V(8); PG8_WAIT_L(0); PG8_BAR; PG8_MMA(1, 0, At, B0); PG8_MMA(1, 1, At, B1); PG8_BAR; PG8_SCHED;
	s_add_i32 s12, s33, s49
	v_lshl_add_u64 v[150:151], v[150:151], 0, s[8:9]
	s_mov_b32 m0, s12
	ds_read_b128 v[186:189], v156 offset:49152
	ds_read_b128 v[190:193], v156 offset:50176
	ds_read_b128 v[194:197], v156 offset:51200
	ds_read_b128 v[200:203], v156 offset:52224
	ds_read_b128 v[204:207], v156 offset:53248
	ds_read_b128 v[208:211], v156 offset:54272
	ds_read_b128 v[212:215], v156 offset:55296
	ds_read_b128 v[216:219], v156 offset:56320
	global_load_lds_dwordx4 v[150:151], off
	s_add_i32 m0, s12, 0x2000
	s_add_u32 s12, s42, 0x40080
	v_lshl_add_u64 v[150:151], v[220:221], 0, s[8:9]
	s_addc_u32 s13, s43, 0
	s_add_i32 s33, s34, s49
	global_load_lds_dwordx4 v[150:151], off
	v_lshl_add_u64 v[150:151], s[12:13], 0, v[132:133]
	s_mov_b32 m0, s33
	s_nop 0
	global_load_lds_dwordx4 v[150:151], off
	v_lshl_add_u64 v[150:151], s[12:13], 0, v[136:137]
	s_add_i32 m0, s33, 0x2000
	s_nop 0
	global_load_lds_dwordx4 v[150:151], off
	s_waitcnt vmcnt(6)
	s_waitcnt lgkmcnt(0)
	s_barrier
	s_setprio 1
	s_waitcnt lgkmcnt(0)
	v_mfma_f32_16x16x32_bf16 v[62:65], v[146:149], v[186:189], v[62:65]
	v_mfma_f32_16x16x32_bf16 v[58:61], v[162:165], v[186:189], v[58:61]
	v_mfma_f32_16x16x32_bf16 v[46:49], v[146:149], v[194:197], v[46:49]
	v_mfma_f32_16x16x32_bf16 v[42:45], v[162:165], v[194:197], v[42:45]
	v_mfma_f32_16x16x32_bf16 v[30:33], v[146:149], v[204:207], v[30:33]
	v_mfma_f32_16x16x32_bf16 v[26:29], v[162:165], v[204:207], v[26:29]
	v_mfma_f32_16x16x32_bf16 v[14:17], v[146:149], v[212:215], v[14:17]
	v_mfma_f32_16x16x32_bf16 v[10:13], v[162:165], v[212:215], v[10:13]
	v_mfma_f32_16x16x32_bf16 v[62:65], v[158:161], v[190:193], v[62:65]
	v_mfma_f32_16x16x32_bf16 v[58:61], v[166:169], v[190:193], v[58:61]
	v_lshl_add_u64 v[150:151], v[222:223], 0, s[8:9]
	s_mov_b32 m0, s54
	s_nop 0
	global_load_lds_dwordx4 v[150:151], off
	v_mfma_f32_16x16x32_bf16 v[46:49], v[158:161], v[200:203], v[46:49]
	v_mfma_f32_16x16x32_bf16 v[42:45], v[166:169], v[200:203], v[42:45]
	v_mfma_f32_16x16x32_bf16 v[30:33], v[158:161], v[208:211], v[30:33]
	v_mfma_f32_16x16x32_bf16 v[26:29], v[166:169], v[208:211], v[26:29]
	v_mfma_f32_16x16x32_bf16 v[14:17], v[158:161], v[216:219], v[14:17]
	v_mfma_f32_16x16x32_bf16 v[10:13], v[166:169], v[216:219], v[10:13]
	s_setprio 0
	s_setprio 1
	v_mfma_f32_16x16x32_bf16 v[54:57], v[170:173], v[186:189], v[54:57]
	v_mfma_f32_16x16x32_bf16 v[50:53], v[178:181], v[186:189], v[50:53]
	v_mfma_f32_16x16x32_bf16 v[38:41], v[170:173], v[194:197], v[38:41]
	v_mfma_f32_16x16x32_bf16 v[34:37], v[178:181], v[194:197], v[34:37]
	v_mfma_f32_16x16x32_bf16 v[22:25], v[170:173], v[204:207], v[22:25]
	v_mfma_f32_16x16x32_bf16 v[18:21], v[178:181], v[204:207], v[18:21]
	v_lshl_add_u64 v[150:151], v[224:225], 0, s[8:9]
	s_mov_b32 m0, s55
	s_nop 0
	global_load_lds_dwordx4 v[150:151], off
	v_mfma_f32_16x16x32_bf16 v[6:9], v[170:173], v[212:215], v[6:9]
	v_mfma_f32_16x16x32_bf16 v[2:5], v[178:181], v[212:215], v[2:5]
	v_mfma_f32_16x16x32_bf16 v[54:57], v[174:177], v[190:193], v[54:57]
	v_mfma_f32_16x16x32_bf16 v[50:53], v[182:185], v[190:193], v[50:53]
	v_mfma_f32_16x16x32_bf16 v[38:41], v[174:177], v[200:203], v[38:41]
	v_mfma_f32_16x16x32_bf16 v[34:37], v[182:185], v[200:203], v[34:37]
	v_mfma_f32_16x16x32_bf16 v[22:25], v[174:177], v[208:211], v[22:25]
	v_mfma_f32_16x16x32_bf16 v[18:21], v[182:185], v[208:211], v[18:21]
	v_mfma_f32_16x16x32_bf16 v[6:9], v[174:177], v[216:219], v[6:9]
	v_mfma_f32_16x16x32_bf16 v[2:5], v[182:185], v[216:219], v[2:5]
	s_setprio 0
	s_barrier
	s_add_i32 s76, s76, 2
	s_add_u32 s0, s0, 0x100
	s_addc_u32 s1, s1, 0
	s_add_u32 s74, s74, 0x100
	s_addc_u32 s75, s75, 0
	s_cmp_gt_u32 s76, 13
	s_cbranch_scc0 .LBB0_1040
	s_and_b64 vcc, exec, s[10:11]
	s_cbranch_vccz .LBB0_1043
	s_barrier

; #define PG8_STAGE(bufoff, gbase, voff) do { _Pragma("unroll") for (int _i = 0; _i < 2; ++_i) \
;         __builtin_amdgcn_global_load_lds((const unsigned*)((const char*)(gbase) + (voff)[_i]), (PG8_LAS unsigned*)(lds + (bufoff) + ldsw + _i * 8192), 16, 0, 0); } while (0)
; #define PG8_LDA(dst, b, h) do { _Pragma("unroll") for (int m = 0; m < 4; ++m) _Pragma("unroll") for (int k = 0; k < 2; ++k) dst[m][k] = *(const PG8_LAS bf16x8*)(lds + PG8_SA(b, h) + aoff + m * 2048 + k * 1024); } while (0)
; #define PG8_LDB(dst, b, h) do { _Pragma("unroll") for (int n = 0; n < 2; ++n) _Pragma("unroll") for (int k = 0; k < 2; ++k) dst[n][k] = *(const PG8_LAS bf16x8*)(lds + PG8_SB(b, h) + boff + n * 2048 + k * 1024); } while (0)
; #define PG8_MMA(ai, bj, At, Bt) do { __builtin_amdgcn_s_setprio(1); _Pragma("unroll") for (int m = 0; m < 4; ++m) _Pragma("unroll") for (int n = 0; n < 2; ++n) _Pragma("unroll") for (int k = 0; k < 2; ++k) \
;         acc[ai][bj][m][n] = __builtin_amdgcn_mfma_f32_16x16x32_bf16(Bt[n][k], At[m][k], acc[ai][bj][m][n], 0, 0, 0); __builtin_amdgcn_s_setprio(0); } while (0)
; #define PG8_WAIT_V(n) asm volatile("s_waitcnt vmcnt(" #n ")" ::: "memory")
; #define PG8_WAIT_L(n) asm volatile("s_waitcnt lgkmcnt(" #n ")" ::: "memory")
; #define PG8_BAR __builtin_amdgcn_s_barrier()
; #define PG8_SCHED __builtin_amdgcn_sched_barrier(0)
; template <class Epi, class Sched, bool ALIGN_EPI = false, bool SP2 = false>
; __device__ __forceinline__ void gemm_phase(PG8_LAS unsigned char* lds, const Gemm g, const Sched& S, const Epi& E) {
;     ...
;             const char* a1 = cA + (size_t)(t + 1) * kstep;
;             const char* a2 = last ? nA : cA + (size_t)(t + 2) * kstep; const char* b2 = last ? nB : cB + (size_t)(t + 2) * kstep;
;             const char* a3 = a2 + kstep; const char* b3 = b2 + kstep;
;             if (last && has_next) S.a_ready(nxt);
;             if constexpr (SP2) {
;             PG8_LDB(B0, 0, 0); PG8_LDB(B1, 0, 1); PG8_SCHED; PG8_LDA(At, 0, 0); PG8_STAGE(PG8_SA(1, 1), a1 + hstepA, voffA);
;             PG8_WAIT_V(8); PG8_WAIT_L(0); PG8_BAR; PG8_MMA(0, 0, At, B0); PG8_MMA(0, 1, At, B1); PG8_BAR; PG8_SCHED;
;             PG8_LDA(At, 0, 1); PG8_STAGE(PG8_SB(0, 0), b2, voffB); PG8_STAGE(PG8_SB(0, 1), b2 + hstepB, voffB); PG8_STAGE(PG8_SA(0, 0), a2, voffA);
.LBB0_1121:
	ds_read_b128 v[152:155], v149
	ds_read_b128 v[156:159], v149 offset:1024
	ds_read_b128 v[160:163], v149 offset:2048
	ds_read_b128 v[164:167], v149 offset:3072
	ds_read_b128 v[168:171], v150
	ds_read_b128 v[172:175], v150 offset:1024
	ds_read_b128 v[176:179], v150 offset:2048
	ds_read_b128 v[180:183], v150 offset:3072
	s_add_u32 s12, s0, 0xfff00080
	s_addc_u32 s13, s1, -1
	s_cmp_eq_u32 s76, 60
	s_cselect_b32 s45, s15, s13
	s_cselect_b32 s44, s31, s12
	s_cselect_b32 s43, s37, s75
	s_cselect_b32 s42, s36, s74
	v_lshl_add_u64 v[144:145], s[0:1], 0, v[136:137]
	s_add_i32 m0, s41, 0xc000
	ds_read_b128 v[184:187], v151
	ds_read_b128 v[188:191], v151 offset:1024
	ds_read_b128 v[192:195], v151 offset:2048
	ds_read_b128 v[200:203], v151 offset:3072
	ds_read_b128 v[204:207], v151 offset:4096
	ds_read_b128 v[208:211], v151 offset:5120
	ds_read_b128 v[212:215], v151 offset:6144
	ds_read_b128 v[216:219], v151 offset:7168
	global_load_lds_dwordx4 v[144:145], off
	v_lshl_add_u64 v[144:145], s[0:1], 0, v[138:139]
	s_add_i32 m0, s41, 0xe000
	s_nop 0
	global_load_lds_dwordx4 v[144:145], off
	s_waitcnt vmcnt(8)
	s_waitcnt lgkmcnt(0)
	s_barrier
	s_setprio 1
	s_waitcnt lgkmcnt(0)
	v_mfma_f32_16x16x32_bf16 v[124:127], v[152:155], v[184:187], v[124:127]
	v_mfma_f32_16x16x32_bf16 v[120:123], v[160:163], v[184:187], v[120:123]
	v_mfma_f32_16x16x32_bf16 v[116:119], v[152:155], v[192:195], v[116:119]
	v_mfma_f32_16x16x32_bf16 v[108:111], v[160:163], v[192:195], v[108:111]
	v_mfma_f32_16x16x32_bf16 v[100:103], v[152:155], v[204:207], v[100:103]
	v_mfma_f32_16x16x32_bf16 v[92:95], v[160:163], v[204:207], v[92:95]
	v_mfma_f32_16x16x32_bf16 v[84:87], v[152:155], v[212:215], v[84:87]
	v_mfma_f32_16x16x32_bf16 v[76:79], v[160:163], v[212:215], v[76:79]
	v_mfma_f32_16x16x32_bf16 v[124:127], v[156:159], v[188:191], v[124:127]
	v_mfma_f32_16x16x32_bf16 v[120:123], v[164:167], v[188:191], v[120:123]
	v_mfma_f32_16x16x32_bf16 v[116:119], v[156:159], v[200:203], v[116:119]
	v_mfma_f32_16x16x32_bf16 v[108:111], v[164:167], v[200:203], v[108:111]
	v_mfma_f32_16x16x32_bf16 v[100:103], v[156:159], v[208:211], v[100:103]
	v_mfma_f32_16x16x32_bf16 v[92:95], v[164:167], v[208:211], v[92:95]
	v_mfma_f32_16x16x32_bf16 v[84:87], v[156:159], v[216:219], v[84:87]
	v_mfma_f32_16x16x32_bf16 v[76:79], v[164:167], v[216:219], v[76:79]
	s_setprio 0
	s_setprio 1
	v_mfma_f32_16x16x32_bf16 v[112:115], v[168:171], v[184:187], v[112:115]
	v_mfma_f32_16x16x32_bf16 v[104:107], v[176:179], v[184:187], v[104:107]
	v_mfma_f32_16x16x32_bf16 v[96:99], v[168:171], v[192:195], v[96:99]
	v_mfma_f32_16x16x32_bf16 v[88:91], v[176:179], v[192:195], v[88:91]
	v_mfma_f32_16x16x32_bf16 v[80:83], v[168:171], v[204:207], v[80:83]
	v_mfma_f32_16x16x32_bf16 v[72:75], v[176:179], v[204:207], v[72:75]
	v_mfma_f32_16x16x32_bf16 v[68:71], v[168:171], v[212:215], v[68:71]
	v_mfma_f32_16x16x32_bf16 v[64:67], v[176:179], v[212:215], v[64:67]
	v_mfma_f32_16x16x32_bf16 v[112:115], v[172:175], v[188:191], v[112:115]
	v_mfma_f32_16x16x32_bf16 v[104:107], v[180:183], v[188:191], v[104:107]
	v_mfma_f32_16x16x32_bf16 v[96:99], v[172:175], v[200:203], v[96:99]
	v_mfma_f32_16x16x32_bf16 v[88:91], v[180:183], v[200:203], v[88:91]
	v_mfma_f32_16x16x32_bf16 v[80:83], v[172:175], v[208:211], v[80:83]
	v_mfma_f32_16x16x32_bf16 v[72:75], v[180:183], v[208:211], v[72:75]
	v_mfma_f32_16x16x32_bf16 v[68:71], v[172:175], v[216:219], v[68:71]
	v_mfma_f32_16x16x32_bf16 v[64:67], v[180:183], v[216:219], v[64:67]
	s_setprio 0
	s_barrier
	s_add_i32 s12, s66, s49
	v_lshl_add_u64 v[144:145], s[42:43], 0, v[130:131]
	s_mov_b32 m0, s12
	ds_read_b128 v[184:187], v151 offset:16384
	ds_read_b128 v[188:191], v151 offset:17408
	ds_read_b128 v[192:195], v151 offset:18432
	ds_read_b128 v[200:203], v151 offset:19456
	ds_read_b128 v[204:207], v151 offset:20480
	ds_read_b128 v[208:211], v151 offset:21504
	ds_read_b128 v[212:215], v151 offset:22528
	ds_read_b128 v[216:219], v151 offset:23552
	global_load_lds_dwordx4 v[144:145], off
	s_add_i32 m0, s12, 0x2000
	s_add_u32 s12, s42, 0x100000
	v_lshl_add_u64 v[196:197], s[42:43], 0, v[134:135]
	s_addc_u32 s13, s43, 0
	s_add_i32 s33, s67, s49
	global_load_lds_dwordx4 v[196:197], off
	v_lshl_add_u64 v[220:221], s[12:13], 0, v[130:131]
	s_mov_b32 m0, s33
	v_lshl_add_u64 v[222:223], s[44:45], 0, v[132:133]
	global_load_lds_dwordx4 v[220:221], off
	v_lshl_add_u64 v[220:221], s[12:13], 0, v[134:135]
	s_add_i32 m0, s33, 0x2000
	s_nop 0
	global_load_lds_dwordx4 v[220:221], off
	s_waitcnt vmcnt(6)
	s_waitcnt lgkmcnt(0)
	s_barrier
; #define PG8_STAGE(bufoff, gbase, voff) do { _Pragma("unroll") for (int _i = 0; _i < 2; ++_i) \
;         __builtin_amdgcn_global_load_lds((const unsigned*)((const char*)(gbase) + (voff)[_i]), (PG8_LAS unsigned*)(lds + (bufoff) + ldsw + _i * 8192), 16, 0, 0); } while (0)
; #define PG8_LDA(dst, b, h) do { _Pragma("unroll") for (int m = 0; m < 4; ++m) _Pragma("unroll") for (int k = 0; k < 2; ++k) dst[m][k] = *(const PG8_LAS bf16x8*)(lds + PG8_SA(b, h) + aoff + m * 2048 + k * 1024); } while (0)
; #define PG8_LDB(dst, b, h) do { _Pragma("unroll") for (int n = 0; n < 2; ++n) _Pragma("unroll") for (int k = 0; k < 2; ++k) dst[n][k] = *(const PG8_LAS bf16x8*)(lds + PG8_SB(b, h) + boff + n * 2048 + k * 1024); } while (0)
; #define PG8_MMA(ai, bj, At, Bt) do { __builtin_amdgcn_s_setprio(1); _Pragma("unroll") for (int m = 0; m < 4; ++m) _Pragma("unroll") for (int n = 0; n < 2; ++n) _Pragma("unroll") for (int k = 0; k < 2; ++k) \
;         acc[ai][bj][m][n] = __builtin_amdgcn_mfma_f32_16x16x32_bf16(Bt[n][k], At[m][k], acc[ai][bj][m][n], 0, 0, 0); __builtin_amdgcn_s_setprio(0); } while (0)
; #define PG8_WAIT_V(n) asm volatile("s_waitcnt vmcnt(" #n ")" ::: "memory")
; #define PG8_WAIT_L(n) asm volatile("s_waitcnt lgkmcnt(" #n ")" ::: "memory")
; #define PG8_BAR __builtin_amdgcn_s_barrier()
; #define PG8_SCHED __builtin_amdgcn_sched_barrier(0)
; template <class Epi, class Sched, bool ALIGN_EPI = false, bool SP2 = false>
; __device__ __forceinline__ void gemm_phase(PG8_LAS unsigned char* lds, const Gemm g, const Sched& S, const Epi& E) {
;     ...
;             PG8_WAIT_V(8); PG8_WAIT_L(0); PG8_BAR; PG8_MMA(1, 0, At, B0); PG8_MMA(1, 1, At, B1); PG8_BAR; PG8_SCHED;
;             PG8_LDB(B0, 1, 0); PG8_LDB(B1, 1, 1); PG8_SCHED; PG8_LDA(At, 1, 0); PG8_STAGE(PG8_SA(0, 1), a2 + hstepA, voffA);
;             PG8_WAIT_V(8); PG8_WAIT_L(0); PG8_BAR; PG8_MMA(0, 0, At, B0); PG8_MMA(0, 1, At, B1); PG8_BAR; PG8_SCHED;
;             PG8_LDA(At, 1, 1); PG8_STAGE(PG8_SB(1, 0), b3, voffB); PG8_STAGE(PG8_SB(1, 1), b3 + hstepB, voffB); PG8_STAGE(PG8_SA(1, 0), a3, voffA);
	s_setprio 1
	s_waitcnt lgkmcnt(0)
	v_mfma_f32_16x16x32_bf16 v[60:63], v[152:155], v[184:187], v[60:63]
	v_mfma_f32_16x16x32_bf16 v[56:59], v[160:163], v[184:187], v[56:59]
	v_mfma_f32_16x16x32_bf16 v[52:55], v[152:155], v[192:195], v[52:55]
	v_mfma_f32_16x16x32_bf16 v[44:47], v[160:163], v[192:195], v[44:47]
	v_mfma_f32_16x16x32_bf16 v[36:39], v[152:155], v[204:207], v[36:39]
	v_mfma_f32_16x16x32_bf16 v[28:31], v[160:163], v[204:207], v[28:31]
	v_mfma_f32_16x16x32_bf16 v[20:23], v[152:155], v[212:215], v[20:23]
	v_mfma_f32_16x16x32_bf16 v[12:15], v[160:163], v[212:215], v[12:15]
	v_mfma_f32_16x16x32_bf16 v[60:63], v[156:159], v[188:191], v[60:63]
	v_mfma_f32_16x16x32_bf16 v[56:59], v[164:167], v[188:191], v[56:59]
	v_lshl_add_u64 v[220:221], s[44:45], 0, v[128:129]
	s_mov_b32 m0, s41
	s_nop 0
	global_load_lds_dwordx4 v[220:221], off
	v_mfma_f32_16x16x32_bf16 v[52:55], v[156:159], v[200:203], v[52:55]
	v_mfma_f32_16x16x32_bf16 v[44:47], v[164:167], v[200:203], v[44:47]
	v_mfma_f32_16x16x32_bf16 v[36:39], v[156:159], v[208:211], v[36:39]
	v_mfma_f32_16x16x32_bf16 v[28:31], v[164:167], v[208:211], v[28:31]
	v_mfma_f32_16x16x32_bf16 v[20:23], v[156:159], v[216:219], v[20:23]
	v_mfma_f32_16x16x32_bf16 v[12:15], v[164:167], v[216:219], v[12:15]
	s_setprio 0
	s_setprio 1
	v_mfma_f32_16x16x32_bf16 v[48:51], v[168:171], v[184:187], v[48:51]
	v_mfma_f32_16x16x32_bf16 v[40:43], v[176:179], v[184:187], v[40:43]
	v_mfma_f32_16x16x32_bf16 v[32:35], v[168:171], v[192:195], v[32:35]
	v_mfma_f32_16x16x32_bf16 v[24:27], v[176:179], v[192:195], v[24:27]
	v_mfma_f32_16x16x32_bf16 v[16:19], v[168:171], v[204:207], v[16:19]
	v_mfma_f32_16x16x32_bf16 v[8:11], v[176:179], v[204:207], v[8:11]
	s_mov_b32 m0, s50
	s_nop 0
	global_load_lds_dwordx4 v[222:223], off
	v_mfma_f32_16x16x32_bf16 v[4:7], v[168:171], v[212:215], v[4:7]
	v_mfma_f32_16x16x32_bf16 v[0:3], v[176:179], v[212:215], v[0:3]
	v_mfma_f32_16x16x32_bf16 v[48:51], v[172:175], v[188:191], v[48:51]
	v_mfma_f32_16x16x32_bf16 v[40:43], v[180:183], v[188:191], v[40:43]
	v_mfma_f32_16x16x32_bf16 v[32:35], v[172:175], v[200:203], v[32:35]
	v_mfma_f32_16x16x32_bf16 v[24:27], v[180:183], v[200:203], v[24:27]
	v_mfma_f32_16x16x32_bf16 v[16:19], v[172:175], v[208:211], v[16:19]
	v_mfma_f32_16x16x32_bf16 v[8:11], v[180:183], v[208:211], v[8:11]
	v_mfma_f32_16x16x32_bf16 v[4:7], v[172:175], v[216:219], v[4:7]
	v_mfma_f32_16x16x32_bf16 v[0:3], v[180:183], v[216:219], v[0:3]
	s_setprio 0
	s_barrier
	s_add_i32 s33, 0, 0x18000
	s_add_i32 s34, 0, 0x1c000
	v_add_u32_e32 v164, s33, v147
	v_add_u32_e32 v180, s34, v147
	ds_read_b128 v[152:155], v164
	ds_read_b128 v[156:159], v164 offset:1024
	ds_read_b128 v[160:163], v164 offset:2048
	ds_read_b128 v[164:167], v164 offset:3072
	ds_read_b128 v[168:171], v180
	ds_read_b128 v[172:175], v180 offset:1024
	ds_read_b128 v[176:179], v180 offset:2048
	ds_read_b128 v[180:183], v180 offset:3072
	s_add_u32 s12, s44, 0x100000
	s_addc_u32 s13, s45, 0
	s_mov_b32 m0, s51
	v_lshl_add_u64 v[224:225], s[12:13], 0, v[128:129]
	ds_read_b128 v[184:187], v151 offset:32768
	ds_read_b128 v[188:191], v151 offset:33792
	ds_read_b128 v[192:195], v151 offset:34816
	ds_read_b128 v[200:203], v151 offset:35840
	ds_read_b128 v[204:207], v151 offset:36864
	ds_read_b128 v[208:211], v151 offset:37888
	ds_read_b128 v[212:215], v151 offset:38912
	ds_read_b128 v[216:219], v151 offset:39936
	global_load_lds_dwordx4 v[224:225], off
	v_lshl_add_u64 v[224:225], s[12:13], 0, v[132:133]
	s_mov_b32 m0, s52
	s_nop 0
	global_load_lds_dwordx4 v[224:225], off
	s_waitcnt vmcnt(8)
	s_waitcnt lgkmcnt(0)
	s_barrier
	s_setprio 1
	s_waitcnt lgkmcnt(0)
	v_mfma_f32_16x16x32_bf16 v[124:127], v[152:155], v[184:187], v[124:127]
	v_mfma_f32_16x16x32_bf16 v[120:123], v[160:163], v[184:187], v[120:123]
	v_mfma_f32_16x16x32_bf16 v[116:119], v[152:155], v[192:195], v[116:119]
	v_mfma_f32_16x16x32_bf16 v[108:111], v[160:163], v[192:195], v[108:111]
	v_mfma_f32_16x16x32_bf16 v[100:103], v[152:155], v[204:207], v[100:103]
	v_mfma_f32_16x16x32_bf16 v[92:95], v[160:163], v[204:207], v[92:95]
	v_mfma_f32_16x16x32_bf16 v[84:87], v[152:155], v[212:215], v[84:87]
	v_mfma_f32_16x16x32_bf16 v[76:79], v[160:163], v[212:215], v[76:79]
	v_mfma_f32_16x16x32_bf16 v[124:127], v[156:159], v[188:191], v[124:127]
	v_mfma_f32_16x16x32_bf16 v[120:123], v[164:167], v[188:191], v[120:123]
	v_mfma_f32_16x16x32_bf16 v[116:119], v[156:159], v[200:203], v[116:119]
	v_mfma_f32_16x16x32_bf16 v[108:111], v[164:167], v[200:203], v[108:111]
	v_mfma_f32_16x16x32_bf16 v[100:103], v[156:159], v[208:211], v[100:103]
	v_mfma_f32_16x16x32_bf16 v[92:95], v[164:167], v[208:211], v[92:95]
	v_mfma_f32_16x16x32_bf16 v[84:87], v[156:159], v[216:219], v[84:87]
	v_mfma_f32_16x16x32_bf16 v[76:79], v[164:167], v[216:219], v[76:79]
	s_setprio 0
	s_setprio 1
	v_mfma_f32_16x16x32_bf16 v[112:115], v[168:171], v[184:187], v[112:115]
	v_mfma_f32_16x16x32_bf16 v[104:107], v[176:179], v[184:187], v[104:107]
	v_mfma_f32_16x16x32_bf16 v[96:99], v[168:171], v[192:195], v[96:99]
	v_mfma_f32_16x16x32_bf16 v[88:91], v[176:179], v[192:195], v[88:91]
	v_mfma_f32_16x16x32_bf16 v[80:83], v[168:171], v[204:207], v[80:83]
	v_mfma_f32_16x16x32_bf16 v[72:75], v[176:179], v[204:207], v[72:75]
	v_mfma_f32_16x16x32_bf16 v[68:71], v[168:171], v[212:215], v[68:71]
	v_mfma_f32_16x16x32_bf16 v[64:67], v[176:179], v[212:215], v[64:67]
	v_mfma_f32_16x16x32_bf16 v[112:115], v[172:175], v[188:191], v[112:115]
	v_mfma_f32_16x16x32_bf16 v[104:107], v[180:183], v[188:191], v[104:107]
	v_mfma_f32_16x16x32_bf16 v[96:99], v[172:175], v[200:203], v[96:99]
	v_mfma_f32_16x16x32_bf16 v[88:91], v[180:183], v[200:203], v[88:91]
	v_mfma_f32_16x16x32_bf16 v[80:83], v[172:175], v[208:211], v[80:83]
	v_mfma_f32_16x16x32_bf16 v[72:75], v[180:183], v[208:211], v[72:75]
	v_mfma_f32_16x16x32_bf16 v[68:71], v[172:175], v[216:219], v[68:71]
	v_mfma_f32_16x16x32_bf16 v[64:67], v[180:183], v[216:219], v[64:67]
	s_setprio 0
	s_barrier
; #define PG8_STAGE(bufoff, gbase, voff) do { _Pragma("unroll") for (int _i = 0; _i < 2; ++_i) \
;         __builtin_amdgcn_global_load_lds((const unsigned*)((const char*)(gbase) + (voff)[_i]), (PG8_LAS unsigned*)(lds + (bufoff) + ldsw + _i * 8192), 16, 0, 0); } while (0)
; #define PG8_LDA(dst, b, h) do { _Pragma("unroll") for (int m = 0; m < 4; ++m) _Pragma("unroll") for (int k = 0; k < 2; ++k) dst[m][k] = *(const PG8_LAS bf16x8*)(lds + PG8_SA(b, h) + aoff + m * 2048 + k * 1024); } while (0)
; #define PG8_MMA(ai, bj, At, Bt) do { __builtin_amdgcn_s_setprio(1); _Pragma("unroll") for (int m = 0; m < 4; ++m) _Pragma("unroll") for (int n = 0; n < 2; ++n) _Pragma("unroll") for (int k = 0; k < 2; ++k) \
;         acc[ai][bj][m][n] = __builtin_amdgcn_mfma_f32_16x16x32_bf16(Bt[n][k], At[m][k], acc[ai][bj][m][n], 0, 0, 0); __builtin_amdgcn_s_setprio(0); } while (0)
; #define PG8_WAIT_V(n) asm volatile("s_waitcnt vmcnt(" #n ")" ::: "memory")
; #define PG8_WAIT_L(n) asm volatile("s_waitcnt lgkmcnt(" #n ")" ::: "memory")
; #define PG8_BAR __builtin_amdgcn_s_barrier()
; #define PG8_SCHED __builtin_amdgcn_sched_barrier(0)
; template <class Epi, class Sched, bool ALIGN_EPI = false, bool SP2 = false>
; __device__ __forceinline__ void gemm_phase(PG8_LAS unsigned char* lds, const Gemm g, const Sched& S, const Epi& E) {
;     ...
;         for (int t = 0; t < nt; t += 2) {
;             const bool last = (t == nt - 2);
;             const char* a1 = cA + (size_t)(t + 1) * kstep;
;             const char* a2 = last ? nA : cA + (size_t)(t + 2) * kstep; const char* b2 = last ? nB : cB + (size_t)(t + 2) * kstep;
;             const char* a3 = a2 + kstep; const char* b3 = b2 + kstep;
;     ...
;             PG8_LDA(At, 1, 1); PG8_STAGE(PG8_SB(1, 0), b3, voffB); PG8_STAGE(PG8_SB(1, 1), b3 + hstepB, voffB); PG8_STAGE(PG8_SA(1, 0), a3, voffA);
;             PG8_WAIT_V(8); PG8_WAIT_L(0); PG8_BAR; PG8_MMA(1, 0, At, B0); PG8_MMA(1, 1, At, B1); PG8_BAR; PG8_SCHED;
	s_add_i32 s12, s33, s49
	v_lshl_add_u64 v[144:145], v[144:145], 0, s[8:9]
	s_mov_b32 m0, s12
	ds_read_b128 v[184:187], v151 offset:49152
	ds_read_b128 v[188:191], v151 offset:50176
	ds_read_b128 v[192:195], v151 offset:51200
	ds_read_b128 v[200:203], v151 offset:52224
	ds_read_b128 v[204:207], v151 offset:53248
	ds_read_b128 v[208:211], v151 offset:54272
	ds_read_b128 v[212:215], v151 offset:55296
	ds_read_b128 v[216:219], v151 offset:56320
	global_load_lds_dwordx4 v[144:145], off
	s_add_i32 m0, s12, 0x2000
	s_add_u32 s12, s42, 0x100080
	v_lshl_add_u64 v[144:145], v[196:197], 0, s[8:9]
	s_addc_u32 s13, s43, 0
	s_add_i32 s33, s34, s49
	global_load_lds_dwordx4 v[144:145], off
	v_lshl_add_u64 v[144:145], s[12:13], 0, v[130:131]
	s_mov_b32 m0, s33
	s_nop 0
	global_load_lds_dwordx4 v[144:145], off
	v_lshl_add_u64 v[144:145], s[12:13], 0, v[134:135]
	s_add_i32 m0, s33, 0x2000
	s_nop 0
	global_load_lds_dwordx4 v[144:145], off
	s_waitcnt vmcnt(6)
	s_waitcnt lgkmcnt(0)
	s_barrier
	s_setprio 1
	s_waitcnt lgkmcnt(0)
	v_mfma_f32_16x16x32_bf16 v[60:63], v[152:155], v[184:187], v[60:63]
	v_mfma_f32_16x16x32_bf16 v[56:59], v[160:163], v[184:187], v[56:59]
	v_mfma_f32_16x16x32_bf16 v[52:55], v[152:155], v[192:195], v[52:55]
	v_mfma_f32_16x16x32_bf16 v[44:47], v[160:163], v[192:195], v[44:47]
	v_mfma_f32_16x16x32_bf16 v[36:39], v[152:155], v[204:207], v[36:39]
	v_mfma_f32_16x16x32_bf16 v[28:31], v[160:163], v[204:207], v[28:31]
	v_mfma_f32_16x16x32_bf16 v[20:23], v[152:155], v[212:215], v[20:23]
	v_mfma_f32_16x16x32_bf16 v[12:15], v[160:163], v[212:215], v[12:15]
	v_mfma_f32_16x16x32_bf16 v[60:63], v[156:159], v[188:191], v[60:63]
	v_mfma_f32_16x16x32_bf16 v[56:59], v[164:167], v[188:191], v[56:59]
	v_lshl_add_u64 v[144:145], v[220:221], 0, s[8:9]
	s_mov_b32 m0, s54
	s_nop 0
	global_load_lds_dwordx4 v[144:145], off
	v_mfma_f32_16x16x32_bf16 v[52:55], v[156:159], v[200:203], v[52:55]
	v_mfma_f32_16x16x32_bf16 v[44:47], v[164:167], v[200:203], v[44:47]
	v_mfma_f32_16x16x32_bf16 v[36:39], v[156:159], v[208:211], v[36:39]
	v_mfma_f32_16x16x32_bf16 v[28:31], v[164:167], v[208:211], v[28:31]
	v_mfma_f32_16x16x32_bf16 v[20:23], v[156:159], v[216:219], v[20:23]
	v_mfma_f32_16x16x32_bf16 v[12:15], v[164:167], v[216:219], v[12:15]
	s_setprio 0
	s_setprio 1
	v_mfma_f32_16x16x32_bf16 v[48:51], v[168:171], v[184:187], v[48:51]
	v_mfma_f32_16x16x32_bf16 v[40:43], v[176:179], v[184:187], v[40:43]
	v_mfma_f32_16x16x32_bf16 v[32:35], v[168:171], v[192:195], v[32:35]
	v_mfma_f32_16x16x32_bf16 v[24:27], v[176:179], v[192:195], v[24:27]
	v_mfma_f32_16x16x32_bf16 v[16:19], v[168:171], v[204:207], v[16:19]
	v_mfma_f32_16x16x32_bf16 v[8:11], v[176:179], v[204:207], v[8:11]
	v_lshl_add_u64 v[144:145], v[222:223], 0, s[8:9]
	s_mov_b32 m0, s55
	s_nop 0
	global_load_lds_dwordx4 v[144:145], off
	v_mfma_f32_16x16x32_bf16 v[4:7], v[168:171], v[212:215], v[4:7]
	v_mfma_f32_16x16x32_bf16 v[0:3], v[176:179], v[212:215], v[0:3]
	v_mfma_f32_16x16x32_bf16 v[48:51], v[172:175], v[188:191], v[48:51]
	v_mfma_f32_16x16x32_bf16 v[40:43], v[180:183], v[188:191], v[40:43]
	v_mfma_f32_16x16x32_bf16 v[32:35], v[172:175], v[200:203], v[32:35]
	v_mfma_f32_16x16x32_bf16 v[24:27], v[180:183], v[200:203], v[24:27]
	v_mfma_f32_16x16x32_bf16 v[16:19], v[172:175], v[208:211], v[16:19]
	v_mfma_f32_16x16x32_bf16 v[8:11], v[180:183], v[208:211], v[8:11]
	v_mfma_f32_16x16x32_bf16 v[4:7], v[172:175], v[216:219], v[4:7]
	v_mfma_f32_16x16x32_bf16 v[0:3], v[180:183], v[216:219], v[0:3]
	s_setprio 0
	s_barrier
	s_add_i32 s76, s76, 2
	s_add_u32 s0, s0, 0x100
	s_addc_u32 s1, s1, 0
	s_add_u32 s74, s74, 0x100
	s_addc_u32 s75, s75, 0
	s_cmp_gt_u32 s76, 61
	s_cbranch_scc0 .LBB0_1121
	s_and_b64 vcc, exec, s[10:11]
	s_cbranch_vccz .LBB0_1124
	s_barrier
